# v11 + K-loop back-edge rotation (counter/pointer advance before the barrier), attention C-init as plain v_fma instead of v_pk_fma, softmax row-sum chains start from the first term
# speedup vs baseline: 1.0047x; 1.0047x over previous
; #define PG8_STAGE(bufoff, gbase, voff) do { _Pragma("unroll") for (int _i = 0; _i < 2; ++_i) \
;         __builtin_amdgcn_global_load_lds((const unsigned*)((const char*)(gbase) + (voff)[_i]), (PG8_LAS unsigned*)(lds + (bufoff) + ldsw + _i * 8192), 16, 0, 0); } while (0)
; #define PG8_LDA(dst, b, h) do { _Pragma("unroll") for (int m = 0; m < 4; ++m) _Pragma("unroll") for (int k = 0; k < 2; ++k) dst[m][k] = *(const PG8_LAS bf16x8*)(lds + PG8_SA(b, h) + aoff + m * 2048 + k * 1024); } while (0)
; #define PG8_LDB(dst, b, h) do { _Pragma("unroll") for (int n = 0; n < 2; ++n) _Pragma("unroll") for (int k = 0; k < 2; ++k) dst[n][k] = *(const PG8_LAS bf16x8*)(lds + PG8_SB(b, h) + boff + n * 2048 + k * 1024); } while (0)
; #define PG8_MMA(ai, bj, At, Bt) do { __builtin_amdgcn_s_setprio(1); _Pragma("unroll") for (int m = 0; m < 4; ++m) _Pragma("unroll") for (int n = 0; n < 2; ++n) _Pragma("unroll") for (int k = 0; k < 2; ++k) \
;         acc[ai][bj][m][n] = __builtin_amdgcn_mfma_f32_16x16x32_bf16(Bt[n][k], At[m][k], acc[ai][bj][m][n], 0, 0, 0); __builtin_amdgcn_s_setprio(0); } while (0)
; #define PG8_WAIT_V(n) asm volatile("s_waitcnt vmcnt(" #n ")" ::: "memory")
; #define PG8_WAIT_L(n) asm volatile("s_waitcnt lgkmcnt(" #n ")" ::: "memory")
; #define PG8_BAR __builtin_amdgcn_s_barrier()
; #define PG8_SCHED __builtin_amdgcn_sched_barrier(0)
; template <class Epi, class Sched, bool ALIGN_EPI = false, bool SP2 = false>
; __device__ __forceinline__ void gemm_phase(PG8_LAS unsigned char* lds, const Gemm g, const Sched& S, const Epi& E, int tid_in) {
;     ...
;             PG8_LDB(B0, 0, 0); PG8_LDB(B1, 0, 1); PG8_SCHED; PG8_LDA(At, 0, 0); PG8_STAGE(PG8_SA(1, 1), a1 + hstep, voffA);
;             PG8_WAIT_V(8); PG8_WAIT_L(0); PG8_BAR; PG8_MMA(0, 0, At, B0); PG8_MMA(0, 1, At, B1); PG8_BAR; PG8_SCHED;
;             PG8_LDA(At, 0, 1); PG8_STAGE(PG8_SB(0, 0), b2, voffB); PG8_STAGE(PG8_SB(0, 1), b2 + hstep, voffB); PG8_STAGE(PG8_SA(0, 0), a2, voffA);
.LBB0_116:
	ds_read_b128 v[148:151], v175
	ds_read_b128 v[152:155], v175 offset:1024
	ds_read_b128 v[156:159], v175 offset:2048
	ds_read_b128 v[160:163], v175 offset:3072
	ds_read_b128 v[164:167], v176
	ds_read_b128 v[180:183], v176 offset:1024
	ds_read_b128 v[184:187], v176 offset:2048
	ds_read_b128 v[188:191], v176 offset:3072
	s_add_u32 s66, s6, 0xfffc0080
	s_addc_u32 s67, s7, -1
	s_cmp_eq_u32 s91, 12
	s_cselect_b32 s71, s53, s67
	s_cselect_b32 s70, s87, s66
	s_cselect_b32 s67, s43, s90
	s_cselect_b32 s66, s88, s89
	v_lshl_add_u64 v[212:213], s[6:7], 0, v[140:141]
	s_add_i32 m0, s63, 0xc000
	ds_read_b128 v[192:195], v177
	ds_read_b128 v[196:199], v177 offset:1024
	ds_read_b128 v[200:203], v177 offset:2048
	ds_read_b128 v[204:207], v177 offset:3072
	ds_read_b128 v[208:211], v177 offset:4096
	ds_read_b128 v[220:223], v177 offset:5120
	ds_read_b128 v[224:227], v177 offset:6144
	ds_read_b128 v[230:233], v177 offset:7168
	global_load_lds_dwordx4 v[212:213], off
	v_lshl_add_u64 v[212:213], s[6:7], 0, v[142:143]
	s_add_i32 m0, s63, 0xe000
	s_nop 0
	global_load_lds_dwordx4 v[212:213], off
	s_waitcnt vmcnt(8)
	s_waitcnt lgkmcnt(0)
	s_barrier
	s_setprio 1
	s_waitcnt lgkmcnt(0)
	v_mfma_f32_16x16x32_bf16 v[124:127], v[148:151], v[192:195], v[124:127]
	v_mfma_f32_16x16x32_bf16 v[120:123], v[156:159], v[192:195], v[120:123]
	v_mfma_f32_16x16x32_bf16 v[108:111], v[148:151], v[200:203], v[108:111]
	v_mfma_f32_16x16x32_bf16 v[104:107], v[156:159], v[200:203], v[104:107]
	v_mfma_f32_16x16x32_bf16 v[92:95], v[148:151], v[208:211], v[92:95]
	v_mfma_f32_16x16x32_bf16 v[88:91], v[156:159], v[208:211], v[88:91]
	v_mfma_f32_16x16x32_bf16 v[76:79], v[148:151], v[224:227], v[76:79]
	v_mfma_f32_16x16x32_bf16 v[72:75], v[156:159], v[224:227], v[72:75]
	v_mfma_f32_16x16x32_bf16 v[124:127], v[152:155], v[196:199], v[124:127]
	v_mfma_f32_16x16x32_bf16 v[120:123], v[160:163], v[196:199], v[120:123]
	v_mfma_f32_16x16x32_bf16 v[108:111], v[152:155], v[204:207], v[108:111]
	v_mfma_f32_16x16x32_bf16 v[104:107], v[160:163], v[204:207], v[104:107]
	v_mfma_f32_16x16x32_bf16 v[92:95], v[152:155], v[220:223], v[92:95]
	v_mfma_f32_16x16x32_bf16 v[88:91], v[160:163], v[220:223], v[88:91]
	v_mfma_f32_16x16x32_bf16 v[76:79], v[152:155], v[230:233], v[76:79]
	v_mfma_f32_16x16x32_bf16 v[72:75], v[160:163], v[230:233], v[72:75]
	v_mfma_f32_16x16x32_bf16 v[116:119], v[164:167], v[192:195], v[116:119]
	v_mfma_f32_16x16x32_bf16 v[112:115], v[184:187], v[192:195], v[112:115]
	v_mfma_f32_16x16x32_bf16 v[100:103], v[164:167], v[200:203], v[100:103]
	v_mfma_f32_16x16x32_bf16 v[96:99], v[184:187], v[200:203], v[96:99]
	v_mfma_f32_16x16x32_bf16 v[84:87], v[164:167], v[208:211], v[84:87]
	v_mfma_f32_16x16x32_bf16 v[80:83], v[184:187], v[208:211], v[80:83]
	v_mfma_f32_16x16x32_bf16 v[68:71], v[164:167], v[224:227], v[68:71]
	v_mfma_f32_16x16x32_bf16 v[64:67], v[184:187], v[224:227], v[64:67]
	v_mfma_f32_16x16x32_bf16 v[116:119], v[180:183], v[196:199], v[116:119]
	v_mfma_f32_16x16x32_bf16 v[112:115], v[188:191], v[196:199], v[112:115]
	v_mfma_f32_16x16x32_bf16 v[100:103], v[180:183], v[204:207], v[100:103]
	v_mfma_f32_16x16x32_bf16 v[96:99], v[188:191], v[204:207], v[96:99]
	v_mfma_f32_16x16x32_bf16 v[84:87], v[180:183], v[220:223], v[84:87]
	v_mfma_f32_16x16x32_bf16 v[80:83], v[188:191], v[220:223], v[80:83]
	v_mfma_f32_16x16x32_bf16 v[68:71], v[180:183], v[230:233], v[68:71]
	v_mfma_f32_16x16x32_bf16 v[64:67], v[188:191], v[230:233], v[64:67]
	s_setprio 0
	s_barrier
	s_add_i32 s92, s79, s69
	v_lshl_add_u64 v[212:213], s[66:67], 0, v[130:131]
	s_mov_b32 m0, s92
	ds_read_b128 v[192:195], v177 offset:16384
	ds_read_b128 v[196:199], v177 offset:17408
	ds_read_b128 v[200:203], v177 offset:18432
	ds_read_b128 v[204:207], v177 offset:19456
	ds_read_b128 v[208:211], v177 offset:20480
	ds_read_b128 v[220:223], v177 offset:21504
	ds_read_b128 v[224:227], v177 offset:22528
	ds_read_b128 v[230:233], v177 offset:23552
	global_load_lds_dwordx4 v[212:213], off
	s_add_i32 m0, s92, 0x2000
	s_add_u32 s92, s66, 0x40000
	v_lshl_add_u64 v[216:217], s[66:67], 0, v[134:135]
	s_addc_u32 s93, s67, 0
	s_add_i32 s94, s80, s69
	global_load_lds_dwordx4 v[216:217], off
	v_lshl_add_u64 v[234:235], s[92:93], 0, v[130:131]
	s_mov_b32 m0, s94
	v_lshl_add_u64 v[236:237], s[70:71], 0, v[132:133]
	global_load_lds_dwordx4 v[234:235], off
	v_lshl_add_u64 v[234:235], s[92:93], 0, v[134:135]
	s_add_i32 m0, s94, 0x2000
	s_nop 0
	global_load_lds_dwordx4 v[234:235], off
	v_lshl_add_u64 v[234:235], s[70:71], 0, v[128:129]
	s_mov_b32 m0, s63
	s_nop 0
	global_load_lds_dwordx4 v[234:235], off
	s_mov_b32 m0, s65
	s_nop 0
	global_load_lds_dwordx4 v[236:237], off
	s_waitcnt vmcnt(8)
	s_waitcnt lgkmcnt(0)
	s_barrier
; #define PG8_STAGE(bufoff, gbase, voff) do { _Pragma("unroll") for (int _i = 0; _i < 2; ++_i) \
;         __builtin_amdgcn_global_load_lds((const unsigned*)((const char*)(gbase) + (voff)[_i]), (PG8_LAS unsigned*)(lds + (bufoff) + ldsw + _i * 8192), 16, 0, 0); } while (0)
; #define PG8_LDA(dst, b, h) do { _Pragma("unroll") for (int m = 0; m < 4; ++m) _Pragma("unroll") for (int k = 0; k < 2; ++k) dst[m][k] = *(const PG8_LAS bf16x8*)(lds + PG8_SA(b, h) + aoff + m * 2048 + k * 1024); } while (0)
; #define PG8_LDB(dst, b, h) do { _Pragma("unroll") for (int n = 0; n < 2; ++n) _Pragma("unroll") for (int k = 0; k < 2; ++k) dst[n][k] = *(const PG8_LAS bf16x8*)(lds + PG8_SB(b, h) + boff + n * 2048 + k * 1024); } while (0)
; #define PG8_MMA(ai, bj, At, Bt) do { __builtin_amdgcn_s_setprio(1); _Pragma("unroll") for (int m = 0; m < 4; ++m) _Pragma("unroll") for (int n = 0; n < 2; ++n) _Pragma("unroll") for (int k = 0; k < 2; ++k) \
;         acc[ai][bj][m][n] = __builtin_amdgcn_mfma_f32_16x16x32_bf16(Bt[n][k], At[m][k], acc[ai][bj][m][n], 0, 0, 0); __builtin_amdgcn_s_setprio(0); } while (0)
; #define PG8_WAIT_V(n) asm volatile("s_waitcnt vmcnt(" #n ")" ::: "memory")
; #define PG8_WAIT_L(n) asm volatile("s_waitcnt lgkmcnt(" #n ")" ::: "memory")
; #define PG8_BAR __builtin_amdgcn_s_barrier()
; #define PG8_SCHED __builtin_amdgcn_sched_barrier(0)
; template <class Epi, class Sched, bool ALIGN_EPI = false, bool SP2 = false>
; __device__ __forceinline__ void gemm_phase(PG8_LAS unsigned char* lds, const Gemm g, const Sched& S, const Epi& E, int tid_in) {
;     ...
;             PG8_WAIT_V(8); PG8_WAIT_L(0); PG8_BAR; PG8_MMA(1, 0, At, B0); PG8_MMA(1, 1, At, B1); PG8_BAR; PG8_SCHED;
;             PG8_LDB(B0, 1, 0); PG8_LDB(B1, 1, 1); PG8_SCHED; PG8_LDA(At, 1, 0); PG8_STAGE(PG8_SA(0, 1), a2 + hstep, voffA);
;             PG8_WAIT_V(8); PG8_WAIT_L(0); PG8_BAR; PG8_MMA(0, 0, At, B0); PG8_MMA(0, 1, At, B1); PG8_BAR; PG8_SCHED;
	s_setprio 1
	s_waitcnt lgkmcnt(0)
	v_mfma_f32_16x16x32_bf16 v[60:63], v[148:151], v[192:195], v[60:63]
	v_mfma_f32_16x16x32_bf16 v[56:59], v[156:159], v[192:195], v[56:59]
	v_mfma_f32_16x16x32_bf16 v[44:47], v[148:151], v[200:203], v[44:47]
	v_mfma_f32_16x16x32_bf16 v[40:43], v[156:159], v[200:203], v[40:43]
	v_mfma_f32_16x16x32_bf16 v[28:31], v[148:151], v[208:211], v[28:31]
	v_mfma_f32_16x16x32_bf16 v[24:27], v[156:159], v[208:211], v[24:27]
	v_mfma_f32_16x16x32_bf16 v[12:15], v[148:151], v[224:227], v[12:15]
	v_mfma_f32_16x16x32_bf16 v[8:11], v[156:159], v[224:227], v[8:11]
	v_mfma_f32_16x16x32_bf16 v[60:63], v[152:155], v[196:199], v[60:63]
	v_mfma_f32_16x16x32_bf16 v[56:59], v[160:163], v[196:199], v[56:59]
	v_mfma_f32_16x16x32_bf16 v[44:47], v[152:155], v[204:207], v[44:47]
	v_mfma_f32_16x16x32_bf16 v[40:43], v[160:163], v[204:207], v[40:43]
	v_mfma_f32_16x16x32_bf16 v[28:31], v[152:155], v[220:223], v[28:31]
	v_mfma_f32_16x16x32_bf16 v[24:27], v[160:163], v[220:223], v[24:27]
	v_mfma_f32_16x16x32_bf16 v[12:15], v[152:155], v[230:233], v[12:15]
	v_mfma_f32_16x16x32_bf16 v[8:11], v[160:163], v[230:233], v[8:11]
	v_mfma_f32_16x16x32_bf16 v[52:55], v[164:167], v[192:195], v[52:55]
	v_mfma_f32_16x16x32_bf16 v[48:51], v[184:187], v[192:195], v[48:51]
	v_mfma_f32_16x16x32_bf16 v[36:39], v[164:167], v[200:203], v[36:39]
	v_mfma_f32_16x16x32_bf16 v[32:35], v[184:187], v[200:203], v[32:35]
	v_mfma_f32_16x16x32_bf16 v[20:23], v[164:167], v[208:211], v[20:23]
	v_mfma_f32_16x16x32_bf16 v[16:19], v[184:187], v[208:211], v[16:19]
	v_mfma_f32_16x16x32_bf16 v[4:7], v[164:167], v[224:227], v[4:7]
	v_mfma_f32_16x16x32_bf16 v[0:3], v[184:187], v[224:227], v[0:3]
	v_mfma_f32_16x16x32_bf16 v[52:55], v[180:183], v[196:199], v[52:55]
	v_mfma_f32_16x16x32_bf16 v[48:51], v[188:191], v[196:199], v[48:51]
	v_mfma_f32_16x16x32_bf16 v[36:39], v[180:183], v[204:207], v[36:39]
	v_mfma_f32_16x16x32_bf16 v[32:35], v[188:191], v[204:207], v[32:35]
	v_mfma_f32_16x16x32_bf16 v[20:23], v[180:183], v[220:223], v[20:23]
	v_mfma_f32_16x16x32_bf16 v[16:19], v[188:191], v[220:223], v[16:19]
	v_mfma_f32_16x16x32_bf16 v[4:7], v[180:183], v[230:233], v[4:7]
	v_mfma_f32_16x16x32_bf16 v[0:3], v[188:191], v[230:233], v[0:3]
	s_setprio 0
	s_barrier
	s_add_i32 s92, 0, 0x18000
	s_add_i32 s93, 0, 0x1c000
	v_add_u32_e32 v160, s92, v172
	v_add_u32_e32 v168, s93, v172
	ds_read_b128 v[148:151], v160
	ds_read_b128 v[152:155], v160 offset:1024
	ds_read_b128 v[156:159], v160 offset:2048
	ds_read_b128 v[160:163], v160 offset:3072
	ds_read_b128 v[164:167], v168
	ds_read_b128 v[180:183], v168 offset:1024
	ds_read_b128 v[184:187], v168 offset:2048
	ds_read_b128 v[188:191], v168 offset:3072
	s_add_u32 s70, s70, 0x40000
	s_addc_u32 s71, s71, 0
	s_mov_b32 m0, s72
	v_lshl_add_u64 v[238:239], s[70:71], 0, v[128:129]
	ds_read_b128 v[192:195], v177 offset:32768
	ds_read_b128 v[196:199], v177 offset:33792
	ds_read_b128 v[200:203], v177 offset:34816
	ds_read_b128 v[204:207], v177 offset:35840
	ds_read_b128 v[208:211], v177 offset:36864
	ds_read_b128 v[220:223], v177 offset:37888
	ds_read_b128 v[224:227], v177 offset:38912
	ds_read_b128 v[230:233], v177 offset:39936
	global_load_lds_dwordx4 v[238:239], off
	v_lshl_add_u64 v[238:239], s[70:71], 0, v[132:133]
	s_mov_b32 m0, s73
	s_nop 0
	global_load_lds_dwordx4 v[238:239], off
	s_waitcnt vmcnt(8)
	s_waitcnt lgkmcnt(0)
	s_barrier
	s_setprio 1
	s_waitcnt lgkmcnt(0)
	v_mfma_f32_16x16x32_bf16 v[124:127], v[148:151], v[192:195], v[124:127]
	v_mfma_f32_16x16x32_bf16 v[120:123], v[156:159], v[192:195], v[120:123]
	v_mfma_f32_16x16x32_bf16 v[108:111], v[148:151], v[200:203], v[108:111]
	v_mfma_f32_16x16x32_bf16 v[104:107], v[156:159], v[200:203], v[104:107]
	v_mfma_f32_16x16x32_bf16 v[92:95], v[148:151], v[208:211], v[92:95]
	v_mfma_f32_16x16x32_bf16 v[88:91], v[156:159], v[208:211], v[88:91]
	v_mfma_f32_16x16x32_bf16 v[76:79], v[148:151], v[224:227], v[76:79]
	v_mfma_f32_16x16x32_bf16 v[72:75], v[156:159], v[224:227], v[72:75]
	v_mfma_f32_16x16x32_bf16 v[124:127], v[152:155], v[196:199], v[124:127]
	v_mfma_f32_16x16x32_bf16 v[120:123], v[160:163], v[196:199], v[120:123]
	v_mfma_f32_16x16x32_bf16 v[108:111], v[152:155], v[204:207], v[108:111]
	v_mfma_f32_16x16x32_bf16 v[104:107], v[160:163], v[204:207], v[104:107]
	v_mfma_f32_16x16x32_bf16 v[92:95], v[152:155], v[220:223], v[92:95]
	v_mfma_f32_16x16x32_bf16 v[88:91], v[160:163], v[220:223], v[88:91]
	v_mfma_f32_16x16x32_bf16 v[76:79], v[152:155], v[230:233], v[76:79]
	v_mfma_f32_16x16x32_bf16 v[72:75], v[160:163], v[230:233], v[72:75]
	v_mfma_f32_16x16x32_bf16 v[116:119], v[164:167], v[192:195], v[116:119]
	v_mfma_f32_16x16x32_bf16 v[112:115], v[184:187], v[192:195], v[112:115]
	v_mfma_f32_16x16x32_bf16 v[100:103], v[164:167], v[200:203], v[100:103]
	v_mfma_f32_16x16x32_bf16 v[96:99], v[184:187], v[200:203], v[96:99]
	v_mfma_f32_16x16x32_bf16 v[84:87], v[164:167], v[208:211], v[84:87]
	v_mfma_f32_16x16x32_bf16 v[80:83], v[184:187], v[208:211], v[80:83]
	v_mfma_f32_16x16x32_bf16 v[68:71], v[164:167], v[224:227], v[68:71]
	v_mfma_f32_16x16x32_bf16 v[64:67], v[184:187], v[224:227], v[64:67]
	v_mfma_f32_16x16x32_bf16 v[116:119], v[180:183], v[196:199], v[116:119]
	v_mfma_f32_16x16x32_bf16 v[112:115], v[188:191], v[196:199], v[112:115]
	v_mfma_f32_16x16x32_bf16 v[100:103], v[180:183], v[204:207], v[100:103]
	v_mfma_f32_16x16x32_bf16 v[96:99], v[188:191], v[204:207], v[96:99]
	v_mfma_f32_16x16x32_bf16 v[84:87], v[180:183], v[220:223], v[84:87]
	v_mfma_f32_16x16x32_bf16 v[80:83], v[188:191], v[220:223], v[80:83]
	v_mfma_f32_16x16x32_bf16 v[68:71], v[180:183], v[230:233], v[68:71]
	v_mfma_f32_16x16x32_bf16 v[64:67], v[188:191], v[230:233], v[64:67]
	s_setprio 0
	s_barrier
; #define PG8_STAGE(bufoff, gbase, voff) do { _Pragma("unroll") for (int _i = 0; _i < 2; ++_i) \
;         __builtin_amdgcn_global_load_lds((const unsigned*)((const char*)(gbase) + (voff)[_i]), (PG8_LAS unsigned*)(lds + (bufoff) + ldsw + _i * 8192), 16, 0, 0); } while (0)
; #define PG8_LDA(dst, b, h) do { _Pragma("unroll") for (int m = 0; m < 4; ++m) _Pragma("unroll") for (int k = 0; k < 2; ++k) dst[m][k] = *(const PG8_LAS bf16x8*)(lds + PG8_SA(b, h) + aoff + m * 2048 + k * 1024); } while (0)
; #define PG8_MMA(ai, bj, At, Bt) do { __builtin_amdgcn_s_setprio(1); _Pragma("unroll") for (int m = 0; m < 4; ++m) _Pragma("unroll") for (int n = 0; n < 2; ++n) _Pragma("unroll") for (int k = 0; k < 2; ++k) \
;         acc[ai][bj][m][n] = __builtin_amdgcn_mfma_f32_16x16x32_bf16(Bt[n][k], At[m][k], acc[ai][bj][m][n], 0, 0, 0); __builtin_amdgcn_s_setprio(0); } while (0)
; #define PG8_WAIT_V(n) asm volatile("s_waitcnt vmcnt(" #n ")" ::: "memory")
; #define PG8_WAIT_L(n) asm volatile("s_waitcnt lgkmcnt(" #n ")" ::: "memory")
; #define PG8_BAR __builtin_amdgcn_s_barrier()
; #define PG8_SCHED __builtin_amdgcn_sched_barrier(0)
; template <class Epi, class Sched, bool ALIGN_EPI = false, bool SP2 = false>
; __device__ __forceinline__ void gemm_phase(PG8_LAS unsigned char* lds, const Gemm g, const Sched& S, const Epi& E, int tid_in) {
;     ...
;         for (int t = 0; t < nt; t += 2) {
;     ...
;             PG8_LDA(At, 1, 1); PG8_STAGE(PG8_SB(1, 0), b3, voffB); PG8_STAGE(PG8_SB(1, 1), b3 + hstep, voffB); PG8_STAGE(PG8_SA(1, 0), a3, voffA);
;             PG8_WAIT_V(8); PG8_WAIT_L(0); PG8_BAR; PG8_MMA(1, 0, At, B0); PG8_MMA(1, 1, At, B1); PG8_BAR; PG8_SCHED;
	s_add_i32 s70, s92, s69
	v_lshl_add_u64 v[212:213], v[212:213], 0, s[10:11]
	s_mov_b32 m0, s70
	ds_read_b128 v[192:195], v177 offset:49152
	ds_read_b128 v[196:199], v177 offset:50176
	ds_read_b128 v[200:203], v177 offset:51200
	ds_read_b128 v[204:207], v177 offset:52224
	ds_read_b128 v[208:211], v177 offset:53248
	ds_read_b128 v[220:223], v177 offset:54272
	ds_read_b128 v[224:227], v177 offset:55296
	ds_read_b128 v[230:233], v177 offset:56320
	global_load_lds_dwordx4 v[212:213], off
	s_add_i32 m0, s70, 0x2000
	s_add_u32 s66, s66, 0x40080
	v_lshl_add_u64 v[212:213], v[216:217], 0, s[10:11]
	s_addc_u32 s67, s67, 0
	s_add_i32 s70, s93, s69
	global_load_lds_dwordx4 v[212:213], off
	v_lshl_add_u64 v[212:213], s[66:67], 0, v[130:131]
	s_mov_b32 m0, s70
	s_nop 0
	global_load_lds_dwordx4 v[212:213], off
	v_lshl_add_u64 v[212:213], s[66:67], 0, v[134:135]
	s_add_i32 m0, s70, 0x2000
	s_nop 0
	global_load_lds_dwordx4 v[212:213], off
	v_lshl_add_u64 v[212:213], v[234:235], 0, s[10:11]
	s_mov_b32 m0, s75
	s_nop 0
	global_load_lds_dwordx4 v[212:213], off
	v_lshl_add_u64 v[212:213], v[236:237], 0, s[10:11]
	s_mov_b32 m0, s76
	s_nop 0
	global_load_lds_dwordx4 v[212:213], off
	s_waitcnt vmcnt(8)
	s_waitcnt lgkmcnt(0)
	s_barrier
	s_setprio 1
	s_waitcnt lgkmcnt(0)
	v_mfma_f32_16x16x32_bf16 v[60:63], v[148:151], v[192:195], v[60:63]
	v_mfma_f32_16x16x32_bf16 v[56:59], v[156:159], v[192:195], v[56:59]
	v_mfma_f32_16x16x32_bf16 v[44:47], v[148:151], v[200:203], v[44:47]
	v_mfma_f32_16x16x32_bf16 v[40:43], v[156:159], v[200:203], v[40:43]
	v_mfma_f32_16x16x32_bf16 v[28:31], v[148:151], v[208:211], v[28:31]
	v_mfma_f32_16x16x32_bf16 v[24:27], v[156:159], v[208:211], v[24:27]
	v_mfma_f32_16x16x32_bf16 v[12:15], v[148:151], v[224:227], v[12:15]
	v_mfma_f32_16x16x32_bf16 v[8:11], v[156:159], v[224:227], v[8:11]
	v_mfma_f32_16x16x32_bf16 v[60:63], v[152:155], v[196:199], v[60:63]
	v_mfma_f32_16x16x32_bf16 v[56:59], v[160:163], v[196:199], v[56:59]
	v_mfma_f32_16x16x32_bf16 v[44:47], v[152:155], v[204:207], v[44:47]
	v_mfma_f32_16x16x32_bf16 v[40:43], v[160:163], v[204:207], v[40:43]
	v_mfma_f32_16x16x32_bf16 v[28:31], v[152:155], v[220:223], v[28:31]
	v_mfma_f32_16x16x32_bf16 v[24:27], v[160:163], v[220:223], v[24:27]
	v_mfma_f32_16x16x32_bf16 v[12:15], v[152:155], v[230:233], v[12:15]
	v_mfma_f32_16x16x32_bf16 v[8:11], v[160:163], v[230:233], v[8:11]
	v_mfma_f32_16x16x32_bf16 v[52:55], v[164:167], v[192:195], v[52:55]
	v_mfma_f32_16x16x32_bf16 v[48:51], v[184:187], v[192:195], v[48:51]
	v_mfma_f32_16x16x32_bf16 v[36:39], v[164:167], v[200:203], v[36:39]
	v_mfma_f32_16x16x32_bf16 v[32:35], v[184:187], v[200:203], v[32:35]
	v_mfma_f32_16x16x32_bf16 v[20:23], v[164:167], v[208:211], v[20:23]
	v_mfma_f32_16x16x32_bf16 v[16:19], v[184:187], v[208:211], v[16:19]
	v_mfma_f32_16x16x32_bf16 v[4:7], v[164:167], v[224:227], v[4:7]
	v_mfma_f32_16x16x32_bf16 v[0:3], v[184:187], v[224:227], v[0:3]
	v_mfma_f32_16x16x32_bf16 v[52:55], v[180:183], v[196:199], v[52:55]
	v_mfma_f32_16x16x32_bf16 v[48:51], v[188:191], v[196:199], v[48:51]
	v_mfma_f32_16x16x32_bf16 v[36:39], v[180:183], v[204:207], v[36:39]
	v_mfma_f32_16x16x32_bf16 v[32:35], v[188:191], v[204:207], v[32:35]
	v_mfma_f32_16x16x32_bf16 v[20:23], v[180:183], v[220:223], v[20:23]
	v_mfma_f32_16x16x32_bf16 v[16:19], v[188:191], v[220:223], v[16:19]
	v_mfma_f32_16x16x32_bf16 v[4:7], v[180:183], v[230:233], v[4:7]
	v_mfma_f32_16x16x32_bf16 v[0:3], v[188:191], v[230:233], v[0:3]
	s_add_i32 s91, s91, 2
	s_add_u32 s6, s6, 0x100
	s_addc_u32 s7, s7, 0
	s_add_u32 s89, s89, 0x100
	s_addc_u32 s90, s90, 0
	s_cmp_gt_u32 s91, 13
	s_setprio 0
	s_barrier
	s_cbranch_scc0 .LBB0_116
	s_and_b64 vcc, exec, s[22:23]
	s_cbranch_vccz .LBB0_119
	s_barrier

; #define PG8_STAGE(bufoff, gbase, voff) do { _Pragma("unroll") for (int _i = 0; _i < 2; ++_i) \
;         __builtin_amdgcn_global_load_lds((const unsigned*)((const char*)(gbase) + (voff)[_i]), (PG8_LAS unsigned*)(lds + (bufoff) + ldsw + _i * 8192), 16, 0, 0); } while (0)
; #define PG8_LDA(dst, b, h) do { _Pragma("unroll") for (int m = 0; m < 4; ++m) _Pragma("unroll") for (int k = 0; k < 2; ++k) dst[m][k] = *(const PG8_LAS bf16x8*)(lds + PG8_SA(b, h) + aoff + m * 2048 + k * 1024); } while (0)
; #define PG8_LDB(dst, b, h) do { _Pragma("unroll") for (int n = 0; n < 2; ++n) _Pragma("unroll") for (int k = 0; k < 2; ++k) dst[n][k] = *(const PG8_LAS bf16x8*)(lds + PG8_SB(b, h) + boff + n * 2048 + k * 1024); } while (0)
; #define PG8_MMA(ai, bj, At, Bt) do { __builtin_amdgcn_s_setprio(1); _Pragma("unroll") for (int m = 0; m < 4; ++m) _Pragma("unroll") for (int n = 0; n < 2; ++n) _Pragma("unroll") for (int k = 0; k < 2; ++k) \
;         acc[ai][bj][m][n] = __builtin_amdgcn_mfma_f32_16x16x32_bf16(Bt[n][k], At[m][k], acc[ai][bj][m][n], 0, 0, 0); __builtin_amdgcn_s_setprio(0); } while (0)
; #define PG8_WAIT_V(n) asm volatile("s_waitcnt vmcnt(" #n ")" ::: "memory")
; #define PG8_WAIT_L(n) asm volatile("s_waitcnt lgkmcnt(" #n ")" ::: "memory")
; #define PG8_BAR __builtin_amdgcn_s_barrier()
; #define PG8_SCHED __builtin_amdgcn_sched_barrier(0)
; template <class Epi, class Sched, bool ALIGN_EPI = false, bool SP2 = false>
; __device__ __forceinline__ void gemm_phase(PG8_LAS unsigned char* lds, const Gemm g, const Sched& S, const Epi& E, int tid_in) {
;     ...
;             PG8_LDB(B0, 0, 0); PG8_LDB(B1, 0, 1); PG8_SCHED; PG8_LDA(At, 0, 0); PG8_STAGE(PG8_SA(1, 1), a1 + hstep, voffA);
;             PG8_WAIT_V(8); PG8_WAIT_L(0); PG8_BAR; PG8_MMA(0, 0, At, B0); PG8_MMA(0, 1, At, B1); PG8_BAR; PG8_SCHED;
;             PG8_LDA(At, 0, 1); PG8_STAGE(PG8_SB(0, 0), b2, voffB); PG8_STAGE(PG8_SB(0, 1), b2 + hstep, voffB); PG8_STAGE(PG8_SA(0, 0), a2, voffA);
.LBB0_166:
	ds_read_b128 v[148:151], v175
	ds_read_b128 v[152:155], v175 offset:1024
	ds_read_b128 v[156:159], v175 offset:2048
	ds_read_b128 v[160:163], v175 offset:3072
	ds_read_b128 v[164:167], v176
	ds_read_b128 v[180:183], v176 offset:1024
	ds_read_b128 v[184:187], v176 offset:2048
	ds_read_b128 v[188:191], v176 offset:3072
	s_add_u32 s70, s6, 0xfffc0080
	s_addc_u32 s71, s7, -1
	s_cmp_eq_u32 s95, 12
	s_cselect_b32 s73, s59, s71
	s_cselect_b32 s72, s91, s70
	s_cselect_b32 s71, s53, s94
	s_cselect_b32 s70, s92, s93
	v_lshl_add_u64 v[212:213], s[6:7], 0, v[140:141]
	s_add_i32 m0, s65, 0xc000
	ds_read_b128 v[192:195], v177
	ds_read_b128 v[196:199], v177 offset:1024
	ds_read_b128 v[200:203], v177 offset:2048
	ds_read_b128 v[204:207], v177 offset:3072
	ds_read_b128 v[208:211], v177 offset:4096
	ds_read_b128 v[220:223], v177 offset:5120
	ds_read_b128 v[224:227], v177 offset:6144
	ds_read_b128 v[230:233], v177 offset:7168
	global_load_lds_dwordx4 v[212:213], off
	v_lshl_add_u64 v[212:213], s[6:7], 0, v[142:143]
	s_add_i32 m0, s65, 0xe000
	s_nop 0
	global_load_lds_dwordx4 v[212:213], off
	s_waitcnt vmcnt(8)
	s_waitcnt lgkmcnt(0)
	s_barrier
	s_setprio 1
	s_waitcnt lgkmcnt(0)
	v_mfma_f32_16x16x32_bf16 v[124:127], v[148:151], v[192:195], v[124:127]
	v_mfma_f32_16x16x32_bf16 v[120:123], v[156:159], v[192:195], v[120:123]
	v_mfma_f32_16x16x32_bf16 v[108:111], v[148:151], v[200:203], v[108:111]
	v_mfma_f32_16x16x32_bf16 v[104:107], v[156:159], v[200:203], v[104:107]
	v_mfma_f32_16x16x32_bf16 v[92:95], v[148:151], v[208:211], v[92:95]
	v_mfma_f32_16x16x32_bf16 v[88:91], v[156:159], v[208:211], v[88:91]
	v_mfma_f32_16x16x32_bf16 v[76:79], v[148:151], v[224:227], v[76:79]
	v_mfma_f32_16x16x32_bf16 v[72:75], v[156:159], v[224:227], v[72:75]
	v_mfma_f32_16x16x32_bf16 v[124:127], v[152:155], v[196:199], v[124:127]
	v_mfma_f32_16x16x32_bf16 v[120:123], v[160:163], v[196:199], v[120:123]
	v_mfma_f32_16x16x32_bf16 v[108:111], v[152:155], v[204:207], v[108:111]
	v_mfma_f32_16x16x32_bf16 v[104:107], v[160:163], v[204:207], v[104:107]
	v_mfma_f32_16x16x32_bf16 v[92:95], v[152:155], v[220:223], v[92:95]
	v_mfma_f32_16x16x32_bf16 v[88:91], v[160:163], v[220:223], v[88:91]
	v_mfma_f32_16x16x32_bf16 v[76:79], v[152:155], v[230:233], v[76:79]
	v_mfma_f32_16x16x32_bf16 v[72:75], v[160:163], v[230:233], v[72:75]
	v_mfma_f32_16x16x32_bf16 v[116:119], v[164:167], v[192:195], v[116:119]
	v_mfma_f32_16x16x32_bf16 v[112:115], v[184:187], v[192:195], v[112:115]
	v_mfma_f32_16x16x32_bf16 v[100:103], v[164:167], v[200:203], v[100:103]
	v_mfma_f32_16x16x32_bf16 v[96:99], v[184:187], v[200:203], v[96:99]
	v_mfma_f32_16x16x32_bf16 v[84:87], v[164:167], v[208:211], v[84:87]
	v_mfma_f32_16x16x32_bf16 v[80:83], v[184:187], v[208:211], v[80:83]
	v_mfma_f32_16x16x32_bf16 v[68:71], v[164:167], v[224:227], v[68:71]
	v_mfma_f32_16x16x32_bf16 v[64:67], v[184:187], v[224:227], v[64:67]
	v_mfma_f32_16x16x32_bf16 v[116:119], v[180:183], v[196:199], v[116:119]
	v_mfma_f32_16x16x32_bf16 v[112:115], v[188:191], v[196:199], v[112:115]
	v_mfma_f32_16x16x32_bf16 v[100:103], v[180:183], v[204:207], v[100:103]
	v_mfma_f32_16x16x32_bf16 v[96:99], v[188:191], v[204:207], v[96:99]
	v_mfma_f32_16x16x32_bf16 v[84:87], v[180:183], v[220:223], v[84:87]
	v_mfma_f32_16x16x32_bf16 v[80:83], v[188:191], v[220:223], v[80:83]
	v_mfma_f32_16x16x32_bf16 v[68:71], v[180:183], v[230:233], v[68:71]
	v_mfma_f32_16x16x32_bf16 v[64:67], v[188:191], v[230:233], v[64:67]
	s_setprio 0
	s_barrier
	s_add_i32 s96, s83, s75
	v_lshl_add_u64 v[212:213], s[70:71], 0, v[130:131]
	s_mov_b32 m0, s96
	ds_read_b128 v[192:195], v177 offset:16384
	ds_read_b128 v[196:199], v177 offset:17408
	ds_read_b128 v[200:203], v177 offset:18432
	ds_read_b128 v[204:207], v177 offset:19456
	ds_read_b128 v[208:211], v177 offset:20480
	ds_read_b128 v[220:223], v177 offset:21504
	ds_read_b128 v[224:227], v177 offset:22528
	ds_read_b128 v[230:233], v177 offset:23552
	global_load_lds_dwordx4 v[212:213], off
	s_add_i32 m0, s96, 0x2000
	s_add_u32 s96, s70, 0x40000
	v_lshl_add_u64 v[216:217], s[70:71], 0, v[134:135]
	s_addc_u32 s97, s71, 0
	s_add_i32 vcc_lo, s84, s75
	global_load_lds_dwordx4 v[216:217], off
	v_lshl_add_u64 v[234:235], s[96:97], 0, v[130:131]
	s_mov_b32 m0, vcc_lo
	v_lshl_add_u64 v[236:237], s[72:73], 0, v[132:133]
	global_load_lds_dwordx4 v[234:235], off
	v_lshl_add_u64 v[234:235], s[96:97], 0, v[134:135]
	s_add_i32 m0, vcc_lo, 0x2000
	s_nop 0
	global_load_lds_dwordx4 v[234:235], off
	v_lshl_add_u64 v[234:235], s[72:73], 0, v[128:129]
	s_mov_b32 m0, s65
	s_nop 0
	global_load_lds_dwordx4 v[234:235], off
	s_mov_b32 m0, s67
	s_nop 0
	global_load_lds_dwordx4 v[236:237], off
	s_waitcnt vmcnt(8)
	s_waitcnt lgkmcnt(0)
	s_barrier
; #define PG8_STAGE(bufoff, gbase, voff) do { _Pragma("unroll") for (int _i = 0; _i < 2; ++_i) \
;         __builtin_amdgcn_global_load_lds((const unsigned*)((const char*)(gbase) + (voff)[_i]), (PG8_LAS unsigned*)(lds + (bufoff) + ldsw + _i * 8192), 16, 0, 0); } while (0)
; #define PG8_LDA(dst, b, h) do { _Pragma("unroll") for (int m = 0; m < 4; ++m) _Pragma("unroll") for (int k = 0; k < 2; ++k) dst[m][k] = *(const PG8_LAS bf16x8*)(lds + PG8_SA(b, h) + aoff + m * 2048 + k * 1024); } while (0)
; #define PG8_LDB(dst, b, h) do { _Pragma("unroll") for (int n = 0; n < 2; ++n) _Pragma("unroll") for (int k = 0; k < 2; ++k) dst[n][k] = *(const PG8_LAS bf16x8*)(lds + PG8_SB(b, h) + boff + n * 2048 + k * 1024); } while (0)
; #define PG8_MMA(ai, bj, At, Bt) do { __builtin_amdgcn_s_setprio(1); _Pragma("unroll") for (int m = 0; m < 4; ++m) _Pragma("unroll") for (int n = 0; n < 2; ++n) _Pragma("unroll") for (int k = 0; k < 2; ++k) \
;         acc[ai][bj][m][n] = __builtin_amdgcn_mfma_f32_16x16x32_bf16(Bt[n][k], At[m][k], acc[ai][bj][m][n], 0, 0, 0); __builtin_amdgcn_s_setprio(0); } while (0)
; #define PG8_WAIT_V(n) asm volatile("s_waitcnt vmcnt(" #n ")" ::: "memory")
; #define PG8_WAIT_L(n) asm volatile("s_waitcnt lgkmcnt(" #n ")" ::: "memory")
; #define PG8_BAR __builtin_amdgcn_s_barrier()
; #define PG8_SCHED __builtin_amdgcn_sched_barrier(0)
; template <class Epi, class Sched, bool ALIGN_EPI = false, bool SP2 = false>
; __device__ __forceinline__ void gemm_phase(PG8_LAS unsigned char* lds, const Gemm g, const Sched& S, const Epi& E, int tid_in) {
;     ...
;             PG8_WAIT_V(8); PG8_WAIT_L(0); PG8_BAR; PG8_MMA(1, 0, At, B0); PG8_MMA(1, 1, At, B1); PG8_BAR; PG8_SCHED;
;             PG8_LDB(B0, 1, 0); PG8_LDB(B1, 1, 1); PG8_SCHED; PG8_LDA(At, 1, 0); PG8_STAGE(PG8_SA(0, 1), a2 + hstep, voffA);
;             PG8_WAIT_V(8); PG8_WAIT_L(0); PG8_BAR; PG8_MMA(0, 0, At, B0); PG8_MMA(0, 1, At, B1); PG8_BAR; PG8_SCHED;
	s_setprio 1
	s_waitcnt lgkmcnt(0)
	v_mfma_f32_16x16x32_bf16 v[60:63], v[148:151], v[192:195], v[60:63]
	v_mfma_f32_16x16x32_bf16 v[56:59], v[156:159], v[192:195], v[56:59]
	v_mfma_f32_16x16x32_bf16 v[44:47], v[148:151], v[200:203], v[44:47]
	v_mfma_f32_16x16x32_bf16 v[40:43], v[156:159], v[200:203], v[40:43]
	v_mfma_f32_16x16x32_bf16 v[28:31], v[148:151], v[208:211], v[28:31]
	v_mfma_f32_16x16x32_bf16 v[24:27], v[156:159], v[208:211], v[24:27]
	v_mfma_f32_16x16x32_bf16 v[12:15], v[148:151], v[224:227], v[12:15]
	v_mfma_f32_16x16x32_bf16 v[8:11], v[156:159], v[224:227], v[8:11]
	v_mfma_f32_16x16x32_bf16 v[60:63], v[152:155], v[196:199], v[60:63]
	v_mfma_f32_16x16x32_bf16 v[56:59], v[160:163], v[196:199], v[56:59]
	v_mfma_f32_16x16x32_bf16 v[44:47], v[152:155], v[204:207], v[44:47]
	v_mfma_f32_16x16x32_bf16 v[40:43], v[160:163], v[204:207], v[40:43]
	v_mfma_f32_16x16x32_bf16 v[28:31], v[152:155], v[220:223], v[28:31]
	v_mfma_f32_16x16x32_bf16 v[24:27], v[160:163], v[220:223], v[24:27]
	v_mfma_f32_16x16x32_bf16 v[12:15], v[152:155], v[230:233], v[12:15]
	v_mfma_f32_16x16x32_bf16 v[8:11], v[160:163], v[230:233], v[8:11]
	v_mfma_f32_16x16x32_bf16 v[52:55], v[164:167], v[192:195], v[52:55]
	v_mfma_f32_16x16x32_bf16 v[48:51], v[184:187], v[192:195], v[48:51]
	v_mfma_f32_16x16x32_bf16 v[36:39], v[164:167], v[200:203], v[36:39]
	v_mfma_f32_16x16x32_bf16 v[32:35], v[184:187], v[200:203], v[32:35]
	v_mfma_f32_16x16x32_bf16 v[20:23], v[164:167], v[208:211], v[20:23]
	v_mfma_f32_16x16x32_bf16 v[16:19], v[184:187], v[208:211], v[16:19]
	v_mfma_f32_16x16x32_bf16 v[4:7], v[164:167], v[224:227], v[4:7]
	v_mfma_f32_16x16x32_bf16 v[0:3], v[184:187], v[224:227], v[0:3]
	v_mfma_f32_16x16x32_bf16 v[52:55], v[180:183], v[196:199], v[52:55]
	v_mfma_f32_16x16x32_bf16 v[48:51], v[188:191], v[196:199], v[48:51]
	v_mfma_f32_16x16x32_bf16 v[36:39], v[180:183], v[204:207], v[36:39]
	v_mfma_f32_16x16x32_bf16 v[32:35], v[188:191], v[204:207], v[32:35]
	v_mfma_f32_16x16x32_bf16 v[20:23], v[180:183], v[220:223], v[20:23]
	v_mfma_f32_16x16x32_bf16 v[16:19], v[188:191], v[220:223], v[16:19]
	v_mfma_f32_16x16x32_bf16 v[4:7], v[180:183], v[230:233], v[4:7]
	v_mfma_f32_16x16x32_bf16 v[0:3], v[188:191], v[230:233], v[0:3]
	s_setprio 0
	s_barrier
	s_add_i32 s96, 0, 0x18000
	s_add_i32 s97, 0, 0x1c000
	v_add_u32_e32 v160, s96, v172
	v_add_u32_e32 v168, s97, v172
	ds_read_b128 v[148:151], v160
	ds_read_b128 v[152:155], v160 offset:1024
	ds_read_b128 v[156:159], v160 offset:2048
	ds_read_b128 v[160:163], v160 offset:3072
	ds_read_b128 v[164:167], v168
	ds_read_b128 v[180:183], v168 offset:1024
	ds_read_b128 v[184:187], v168 offset:2048
	ds_read_b128 v[188:191], v168 offset:3072
	s_add_u32 s72, s72, 0x40000
	s_addc_u32 s73, s73, 0
	s_mov_b32 m0, s76
	v_lshl_add_u64 v[238:239], s[72:73], 0, v[128:129]
	ds_read_b128 v[192:195], v177 offset:32768
	ds_read_b128 v[196:199], v177 offset:33792
	ds_read_b128 v[200:203], v177 offset:34816
	ds_read_b128 v[204:207], v177 offset:35840
	ds_read_b128 v[208:211], v177 offset:36864
	ds_read_b128 v[220:223], v177 offset:37888
	ds_read_b128 v[224:227], v177 offset:38912
	ds_read_b128 v[230:233], v177 offset:39936
	global_load_lds_dwordx4 v[238:239], off
	v_lshl_add_u64 v[238:239], s[72:73], 0, v[132:133]
	s_mov_b32 m0, s77
	s_nop 0
	global_load_lds_dwordx4 v[238:239], off
	s_waitcnt vmcnt(8)
	s_waitcnt lgkmcnt(0)
	s_barrier
	s_setprio 1
	s_waitcnt lgkmcnt(0)
	v_mfma_f32_16x16x32_bf16 v[124:127], v[148:151], v[192:195], v[124:127]
	v_mfma_f32_16x16x32_bf16 v[120:123], v[156:159], v[192:195], v[120:123]
	v_mfma_f32_16x16x32_bf16 v[108:111], v[148:151], v[200:203], v[108:111]
	v_mfma_f32_16x16x32_bf16 v[104:107], v[156:159], v[200:203], v[104:107]
	v_mfma_f32_16x16x32_bf16 v[92:95], v[148:151], v[208:211], v[92:95]
	v_mfma_f32_16x16x32_bf16 v[88:91], v[156:159], v[208:211], v[88:91]
	v_mfma_f32_16x16x32_bf16 v[76:79], v[148:151], v[224:227], v[76:79]
	v_mfma_f32_16x16x32_bf16 v[72:75], v[156:159], v[224:227], v[72:75]
	v_mfma_f32_16x16x32_bf16 v[124:127], v[152:155], v[196:199], v[124:127]
	v_mfma_f32_16x16x32_bf16 v[120:123], v[160:163], v[196:199], v[120:123]
	v_mfma_f32_16x16x32_bf16 v[108:111], v[152:155], v[204:207], v[108:111]
	v_mfma_f32_16x16x32_bf16 v[104:107], v[160:163], v[204:207], v[104:107]
	v_mfma_f32_16x16x32_bf16 v[92:95], v[152:155], v[220:223], v[92:95]
	v_mfma_f32_16x16x32_bf16 v[88:91], v[160:163], v[220:223], v[88:91]
	v_mfma_f32_16x16x32_bf16 v[76:79], v[152:155], v[230:233], v[76:79]
	v_mfma_f32_16x16x32_bf16 v[72:75], v[160:163], v[230:233], v[72:75]
	v_mfma_f32_16x16x32_bf16 v[116:119], v[164:167], v[192:195], v[116:119]
	v_mfma_f32_16x16x32_bf16 v[112:115], v[184:187], v[192:195], v[112:115]
	v_mfma_f32_16x16x32_bf16 v[100:103], v[164:167], v[200:203], v[100:103]
	v_mfma_f32_16x16x32_bf16 v[96:99], v[184:187], v[200:203], v[96:99]
	v_mfma_f32_16x16x32_bf16 v[84:87], v[164:167], v[208:211], v[84:87]
	v_mfma_f32_16x16x32_bf16 v[80:83], v[184:187], v[208:211], v[80:83]
	v_mfma_f32_16x16x32_bf16 v[68:71], v[164:167], v[224:227], v[68:71]
	v_mfma_f32_16x16x32_bf16 v[64:67], v[184:187], v[224:227], v[64:67]
	v_mfma_f32_16x16x32_bf16 v[116:119], v[180:183], v[196:199], v[116:119]
	v_mfma_f32_16x16x32_bf16 v[112:115], v[188:191], v[196:199], v[112:115]
	v_mfma_f32_16x16x32_bf16 v[100:103], v[180:183], v[204:207], v[100:103]
	v_mfma_f32_16x16x32_bf16 v[96:99], v[188:191], v[204:207], v[96:99]
	v_mfma_f32_16x16x32_bf16 v[84:87], v[180:183], v[220:223], v[84:87]
	v_mfma_f32_16x16x32_bf16 v[80:83], v[188:191], v[220:223], v[80:83]
	v_mfma_f32_16x16x32_bf16 v[68:71], v[180:183], v[230:233], v[68:71]
	v_mfma_f32_16x16x32_bf16 v[64:67], v[188:191], v[230:233], v[64:67]
	s_setprio 0
	s_barrier
; #define PG8_STAGE(bufoff, gbase, voff) do { _Pragma("unroll") for (int _i = 0; _i < 2; ++_i) \
;         __builtin_amdgcn_global_load_lds((const unsigned*)((const char*)(gbase) + (voff)[_i]), (PG8_LAS unsigned*)(lds + (bufoff) + ldsw + _i * 8192), 16, 0, 0); } while (0)
; #define PG8_LDA(dst, b, h) do { _Pragma("unroll") for (int m = 0; m < 4; ++m) _Pragma("unroll") for (int k = 0; k < 2; ++k) dst[m][k] = *(const PG8_LAS bf16x8*)(lds + PG8_SA(b, h) + aoff + m * 2048 + k * 1024); } while (0)
; #define PG8_MMA(ai, bj, At, Bt) do { __builtin_amdgcn_s_setprio(1); _Pragma("unroll") for (int m = 0; m < 4; ++m) _Pragma("unroll") for (int n = 0; n < 2; ++n) _Pragma("unroll") for (int k = 0; k < 2; ++k) \
;         acc[ai][bj][m][n] = __builtin_amdgcn_mfma_f32_16x16x32_bf16(Bt[n][k], At[m][k], acc[ai][bj][m][n], 0, 0, 0); __builtin_amdgcn_s_setprio(0); } while (0)
; #define PG8_WAIT_V(n) asm volatile("s_waitcnt vmcnt(" #n ")" ::: "memory")
; #define PG8_WAIT_L(n) asm volatile("s_waitcnt lgkmcnt(" #n ")" ::: "memory")
; #define PG8_BAR __builtin_amdgcn_s_barrier()
; #define PG8_SCHED __builtin_amdgcn_sched_barrier(0)
; template <class Epi, class Sched, bool ALIGN_EPI = false, bool SP2 = false>
; __device__ __forceinline__ void gemm_phase(PG8_LAS unsigned char* lds, const Gemm g, const Sched& S, const Epi& E, int tid_in) {
;     ...
;         for (int t = 0; t < nt; t += 2) {
;     ...
;             PG8_LDA(At, 1, 1); PG8_STAGE(PG8_SB(1, 0), b3, voffB); PG8_STAGE(PG8_SB(1, 1), b3 + hstep, voffB); PG8_STAGE(PG8_SA(1, 0), a3, voffA);
;             PG8_WAIT_V(8); PG8_WAIT_L(0); PG8_BAR; PG8_MMA(1, 0, At, B0); PG8_MMA(1, 1, At, B1); PG8_BAR; PG8_SCHED;
	s_add_i32 s72, s96, s75
	v_lshl_add_u64 v[212:213], v[212:213], 0, s[22:23]
	s_mov_b32 m0, s72
	ds_read_b128 v[192:195], v177 offset:49152
	ds_read_b128 v[196:199], v177 offset:50176
	ds_read_b128 v[200:203], v177 offset:51200
	ds_read_b128 v[204:207], v177 offset:52224
	ds_read_b128 v[208:211], v177 offset:53248
	ds_read_b128 v[220:223], v177 offset:54272
	ds_read_b128 v[224:227], v177 offset:55296
	ds_read_b128 v[230:233], v177 offset:56320
	global_load_lds_dwordx4 v[212:213], off
	s_add_i32 m0, s72, 0x2000
	s_add_u32 s70, s70, 0x40080
	v_lshl_add_u64 v[212:213], v[216:217], 0, s[22:23]
	s_addc_u32 s71, s71, 0
	s_add_i32 s72, s97, s75
	global_load_lds_dwordx4 v[212:213], off
	v_lshl_add_u64 v[212:213], s[70:71], 0, v[130:131]
	s_mov_b32 m0, s72
	s_nop 0
	global_load_lds_dwordx4 v[212:213], off
	v_lshl_add_u64 v[212:213], s[70:71], 0, v[134:135]
	s_add_i32 m0, s72, 0x2000
	s_nop 0
	global_load_lds_dwordx4 v[212:213], off
	v_lshl_add_u64 v[212:213], v[234:235], 0, s[22:23]
	s_mov_b32 m0, s79
	s_nop 0
	global_load_lds_dwordx4 v[212:213], off
	v_lshl_add_u64 v[212:213], v[236:237], 0, s[22:23]
	s_mov_b32 m0, s80
	s_nop 0
	global_load_lds_dwordx4 v[212:213], off
	s_waitcnt vmcnt(8)
	s_waitcnt lgkmcnt(0)
	s_barrier
	s_setprio 1
	s_waitcnt lgkmcnt(0)
	v_mfma_f32_16x16x32_bf16 v[60:63], v[148:151], v[192:195], v[60:63]
	v_mfma_f32_16x16x32_bf16 v[56:59], v[156:159], v[192:195], v[56:59]
	v_mfma_f32_16x16x32_bf16 v[44:47], v[148:151], v[200:203], v[44:47]
	v_mfma_f32_16x16x32_bf16 v[40:43], v[156:159], v[200:203], v[40:43]
	v_mfma_f32_16x16x32_bf16 v[28:31], v[148:151], v[208:211], v[28:31]
	v_mfma_f32_16x16x32_bf16 v[24:27], v[156:159], v[208:211], v[24:27]
	v_mfma_f32_16x16x32_bf16 v[12:15], v[148:151], v[224:227], v[12:15]
	v_mfma_f32_16x16x32_bf16 v[8:11], v[156:159], v[224:227], v[8:11]
	v_mfma_f32_16x16x32_bf16 v[60:63], v[152:155], v[196:199], v[60:63]
	v_mfma_f32_16x16x32_bf16 v[56:59], v[160:163], v[196:199], v[56:59]
	v_mfma_f32_16x16x32_bf16 v[44:47], v[152:155], v[204:207], v[44:47]
	v_mfma_f32_16x16x32_bf16 v[40:43], v[160:163], v[204:207], v[40:43]
	v_mfma_f32_16x16x32_bf16 v[28:31], v[152:155], v[220:223], v[28:31]
	v_mfma_f32_16x16x32_bf16 v[24:27], v[160:163], v[220:223], v[24:27]
	v_mfma_f32_16x16x32_bf16 v[12:15], v[152:155], v[230:233], v[12:15]
	v_mfma_f32_16x16x32_bf16 v[8:11], v[160:163], v[230:233], v[8:11]
	v_mfma_f32_16x16x32_bf16 v[52:55], v[164:167], v[192:195], v[52:55]
	v_mfma_f32_16x16x32_bf16 v[48:51], v[184:187], v[192:195], v[48:51]
	v_mfma_f32_16x16x32_bf16 v[36:39], v[164:167], v[200:203], v[36:39]
	v_mfma_f32_16x16x32_bf16 v[32:35], v[184:187], v[200:203], v[32:35]
	v_mfma_f32_16x16x32_bf16 v[20:23], v[164:167], v[208:211], v[20:23]
	v_mfma_f32_16x16x32_bf16 v[16:19], v[184:187], v[208:211], v[16:19]
	v_mfma_f32_16x16x32_bf16 v[4:7], v[164:167], v[224:227], v[4:7]
	v_mfma_f32_16x16x32_bf16 v[0:3], v[184:187], v[224:227], v[0:3]
	v_mfma_f32_16x16x32_bf16 v[52:55], v[180:183], v[196:199], v[52:55]
	v_mfma_f32_16x16x32_bf16 v[48:51], v[188:191], v[196:199], v[48:51]
	v_mfma_f32_16x16x32_bf16 v[36:39], v[180:183], v[204:207], v[36:39]
	v_mfma_f32_16x16x32_bf16 v[32:35], v[188:191], v[204:207], v[32:35]
	v_mfma_f32_16x16x32_bf16 v[20:23], v[180:183], v[220:223], v[20:23]
	v_mfma_f32_16x16x32_bf16 v[16:19], v[188:191], v[220:223], v[16:19]
	v_mfma_f32_16x16x32_bf16 v[4:7], v[180:183], v[230:233], v[4:7]
	v_mfma_f32_16x16x32_bf16 v[0:3], v[188:191], v[230:233], v[0:3]
	s_add_i32 s95, s95, 2
	s_add_u32 s6, s6, 0x100
	s_addc_u32 s7, s7, 0
	s_add_u32 s93, s93, 0x100
	s_addc_u32 s94, s94, 0
	s_cmp_gt_u32 s95, 13
	s_setprio 0
	s_barrier
	s_cbranch_scc0 .LBB0_166
	s_and_b64 vcc, exec, s[24:25]
	s_cbranch_vccz .LBB0_169
	s_barrier

; #define PG8_STAGE(bufoff, gbase, voff) do { _Pragma("unroll") for (int _i = 0; _i < 2; ++_i) \
;         __builtin_amdgcn_global_load_lds((const unsigned*)((const char*)(gbase) + (voff)[_i]), (PG8_LAS unsigned*)(lds + (bufoff) + ldsw + _i * 8192), 16, 0, 0); } while (0)
; #define PG8_LDA(dst, b, h) do { _Pragma("unroll") for (int m = 0; m < 4; ++m) _Pragma("unroll") for (int k = 0; k < 2; ++k) dst[m][k] = *(const PG8_LAS bf16x8*)(lds + PG8_SA(b, h) + aoff + m * 2048 + k * 1024); } while (0)
; #define PG8_LDB(dst, b, h) do { _Pragma("unroll") for (int n = 0; n < 2; ++n) _Pragma("unroll") for (int k = 0; k < 2; ++k) dst[n][k] = *(const PG8_LAS bf16x8*)(lds + PG8_SB(b, h) + boff + n * 2048 + k * 1024); } while (0)
; #define PG8_MMA(ai, bj, At, Bt) do { __builtin_amdgcn_s_setprio(1); _Pragma("unroll") for (int m = 0; m < 4; ++m) _Pragma("unroll") for (int n = 0; n < 2; ++n) _Pragma("unroll") for (int k = 0; k < 2; ++k) \
;         acc[ai][bj][m][n] = __builtin_amdgcn_mfma_f32_16x16x32_bf16(Bt[n][k], At[m][k], acc[ai][bj][m][n], 0, 0, 0); __builtin_amdgcn_s_setprio(0); } while (0)
; #define PG8_WAIT_V(n) asm volatile("s_waitcnt vmcnt(" #n ")" ::: "memory")
; #define PG8_WAIT_L(n) asm volatile("s_waitcnt lgkmcnt(" #n ")" ::: "memory")
; #define PG8_BAR __builtin_amdgcn_s_barrier()
; #define PG8_SCHED __builtin_amdgcn_sched_barrier(0)
; template <class Epi, class Sched, bool ALIGN_EPI = false, bool SP2 = false>
; __device__ __forceinline__ void gemm_phase(PG8_LAS unsigned char* lds, const Gemm g, const Sched& S, const Epi& E, int tid_in) {
;     ...
;             PG8_LDB(B0, 0, 0); PG8_LDB(B1, 0, 1); PG8_SCHED; PG8_LDA(At, 0, 0); PG8_STAGE(PG8_SA(1, 1), a1 + hstep, voffA);
;             PG8_WAIT_V(8); PG8_WAIT_L(0); PG8_BAR; PG8_MMA(0, 0, At, B0); PG8_MMA(0, 1, At, B1); PG8_BAR; PG8_SCHED;
;             PG8_LDA(At, 0, 1); PG8_STAGE(PG8_SB(0, 0), b2, voffB); PG8_STAGE(PG8_SB(0, 1), b2 + hstep, voffB); PG8_STAGE(PG8_SA(0, 0), a2, voffA);
.LBB0_214:
	ds_read_b128 v[154:157], v151
	ds_read_b128 v[158:161], v151 offset:1024
	ds_read_b128 v[162:165], v151 offset:2048
	ds_read_b128 v[172:175], v151 offset:3072
	ds_read_b128 v[176:179], v152
	ds_read_b128 v[180:183], v152 offset:1024
	ds_read_b128 v[184:187], v152 offset:2048
	ds_read_b128 v[188:191], v152 offset:3072
	s_add_u32 s64, s62, 0xfffc0080
	s_addc_u32 s65, s63, -1
	s_cmp_eq_u32 s91, 12
	s_cselect_b32 s67, s43, s65
	s_cselect_b32 s66, s87, s64
	s_cselect_b32 s65, s41, s90
	s_cselect_b32 s64, s88, s89
	v_lshl_add_u64 v[146:147], s[62:63], 0, v[138:139]
	s_add_i32 m0, s61, 0xc000
	ds_read_b128 v[192:195], v153
	ds_read_b128 v[196:199], v153 offset:1024
	ds_read_b128 v[200:203], v153 offset:2048
	ds_read_b128 v[204:207], v153 offset:3072
	ds_read_b128 v[208:211], v153 offset:4096
	ds_read_b128 v[220:223], v153 offset:5120
	ds_read_b128 v[224:227], v153 offset:6144
	ds_read_b128 v[230:233], v153 offset:7168
	global_load_lds_dwordx4 v[146:147], off
	v_lshl_add_u64 v[146:147], s[62:63], 0, v[140:141]
	s_add_i32 m0, s61, 0xe000
	s_nop 0
	global_load_lds_dwordx4 v[146:147], off
	s_waitcnt vmcnt(8)
	s_waitcnt lgkmcnt(0)
	s_barrier
	s_setprio 1
	s_waitcnt lgkmcnt(0)
	v_mfma_f32_16x16x32_bf16 v[124:127], v[154:157], v[192:195], v[124:127]
	v_mfma_f32_16x16x32_bf16 v[120:123], v[162:165], v[192:195], v[120:123]
	v_mfma_f32_16x16x32_bf16 v[116:119], v[154:157], v[200:203], v[116:119]
	v_mfma_f32_16x16x32_bf16 v[108:111], v[162:165], v[200:203], v[108:111]
	v_mfma_f32_16x16x32_bf16 v[100:103], v[154:157], v[208:211], v[100:103]
	v_mfma_f32_16x16x32_bf16 v[92:95], v[162:165], v[208:211], v[92:95]
	v_mfma_f32_16x16x32_bf16 v[84:87], v[154:157], v[224:227], v[84:87]
	v_mfma_f32_16x16x32_bf16 v[76:79], v[162:165], v[224:227], v[76:79]
	v_mfma_f32_16x16x32_bf16 v[124:127], v[158:161], v[196:199], v[124:127]
	v_mfma_f32_16x16x32_bf16 v[120:123], v[172:175], v[196:199], v[120:123]
	v_mfma_f32_16x16x32_bf16 v[116:119], v[158:161], v[204:207], v[116:119]
	v_mfma_f32_16x16x32_bf16 v[108:111], v[172:175], v[204:207], v[108:111]
	v_mfma_f32_16x16x32_bf16 v[100:103], v[158:161], v[220:223], v[100:103]
	v_mfma_f32_16x16x32_bf16 v[92:95], v[172:175], v[220:223], v[92:95]
	v_mfma_f32_16x16x32_bf16 v[84:87], v[158:161], v[230:233], v[84:87]
	v_mfma_f32_16x16x32_bf16 v[76:79], v[172:175], v[230:233], v[76:79]
	v_mfma_f32_16x16x32_bf16 v[112:115], v[176:179], v[192:195], v[112:115]
	v_mfma_f32_16x16x32_bf16 v[104:107], v[184:187], v[192:195], v[104:107]
	v_mfma_f32_16x16x32_bf16 v[96:99], v[176:179], v[200:203], v[96:99]
	v_mfma_f32_16x16x32_bf16 v[88:91], v[184:187], v[200:203], v[88:91]
	v_mfma_f32_16x16x32_bf16 v[80:83], v[176:179], v[208:211], v[80:83]
	v_mfma_f32_16x16x32_bf16 v[72:75], v[184:187], v[208:211], v[72:75]
	v_mfma_f32_16x16x32_bf16 v[68:71], v[176:179], v[224:227], v[68:71]
	v_mfma_f32_16x16x32_bf16 v[64:67], v[184:187], v[224:227], v[64:67]
	v_mfma_f32_16x16x32_bf16 v[112:115], v[180:183], v[196:199], v[112:115]
	v_mfma_f32_16x16x32_bf16 v[104:107], v[188:191], v[196:199], v[104:107]
	v_mfma_f32_16x16x32_bf16 v[96:99], v[180:183], v[204:207], v[96:99]
	v_mfma_f32_16x16x32_bf16 v[88:91], v[188:191], v[204:207], v[88:91]
	v_mfma_f32_16x16x32_bf16 v[80:83], v[180:183], v[220:223], v[80:83]
	v_mfma_f32_16x16x32_bf16 v[72:75], v[188:191], v[220:223], v[72:75]
	v_mfma_f32_16x16x32_bf16 v[68:71], v[180:183], v[230:233], v[68:71]
	v_mfma_f32_16x16x32_bf16 v[64:67], v[188:191], v[230:233], v[64:67]
	s_setprio 0
	s_barrier
	s_add_i32 s92, s80, s72
	v_lshl_add_u64 v[146:147], s[64:65], 0, v[130:131]
	s_mov_b32 m0, s92
	ds_read_b128 v[192:195], v153 offset:16384
	ds_read_b128 v[196:199], v153 offset:17408
	ds_read_b128 v[200:203], v153 offset:18432
	ds_read_b128 v[204:207], v153 offset:19456
	ds_read_b128 v[208:211], v153 offset:20480
	ds_read_b128 v[220:223], v153 offset:21504
	ds_read_b128 v[224:227], v153 offset:22528
	ds_read_b128 v[230:233], v153 offset:23552
	global_load_lds_dwordx4 v[146:147], off
	s_add_i32 m0, s92, 0x2000
	s_add_u32 s92, s64, 0x40000
	v_lshl_add_u64 v[166:167], s[64:65], 0, v[134:135]
	s_addc_u32 s93, s65, 0
	s_add_i32 s94, s81, s72
	global_load_lds_dwordx4 v[166:167], off
	v_lshl_add_u64 v[212:213], s[92:93], 0, v[130:131]
	s_mov_b32 m0, s94
	v_lshl_add_u64 v[216:217], s[66:67], 0, v[132:133]
	global_load_lds_dwordx4 v[212:213], off
	v_lshl_add_u64 v[212:213], s[92:93], 0, v[134:135]
	s_add_i32 m0, s94, 0x2000
	s_nop 0
	global_load_lds_dwordx4 v[212:213], off
	v_lshl_add_u64 v[212:213], s[66:67], 0, v[128:129]
	s_mov_b32 m0, s61
	s_nop 0
	global_load_lds_dwordx4 v[212:213], off
	s_mov_b32 m0, s73
	s_nop 0
	global_load_lds_dwordx4 v[216:217], off
	s_waitcnt vmcnt(8)
	s_waitcnt lgkmcnt(0)
	s_barrier
; #define PG8_STAGE(bufoff, gbase, voff) do { _Pragma("unroll") for (int _i = 0; _i < 2; ++_i) \
;         __builtin_amdgcn_global_load_lds((const unsigned*)((const char*)(gbase) + (voff)[_i]), (PG8_LAS unsigned*)(lds + (bufoff) + ldsw + _i * 8192), 16, 0, 0); } while (0)
; #define PG8_LDA(dst, b, h) do { _Pragma("unroll") for (int m = 0; m < 4; ++m) _Pragma("unroll") for (int k = 0; k < 2; ++k) dst[m][k] = *(const PG8_LAS bf16x8*)(lds + PG8_SA(b, h) + aoff + m * 2048 + k * 1024); } while (0)
; #define PG8_LDB(dst, b, h) do { _Pragma("unroll") for (int n = 0; n < 2; ++n) _Pragma("unroll") for (int k = 0; k < 2; ++k) dst[n][k] = *(const PG8_LAS bf16x8*)(lds + PG8_SB(b, h) + boff + n * 2048 + k * 1024); } while (0)
; #define PG8_MMA(ai, bj, At, Bt) do { __builtin_amdgcn_s_setprio(1); _Pragma("unroll") for (int m = 0; m < 4; ++m) _Pragma("unroll") for (int n = 0; n < 2; ++n) _Pragma("unroll") for (int k = 0; k < 2; ++k) \
;         acc[ai][bj][m][n] = __builtin_amdgcn_mfma_f32_16x16x32_bf16(Bt[n][k], At[m][k], acc[ai][bj][m][n], 0, 0, 0); __builtin_amdgcn_s_setprio(0); } while (0)
; #define PG8_WAIT_V(n) asm volatile("s_waitcnt vmcnt(" #n ")" ::: "memory")
; #define PG8_WAIT_L(n) asm volatile("s_waitcnt lgkmcnt(" #n ")" ::: "memory")
; #define PG8_BAR __builtin_amdgcn_s_barrier()
; #define PG8_SCHED __builtin_amdgcn_sched_barrier(0)
; template <class Epi, class Sched, bool ALIGN_EPI = false, bool SP2 = false>
; __device__ __forceinline__ void gemm_phase(PG8_LAS unsigned char* lds, const Gemm g, const Sched& S, const Epi& E, int tid_in) {
;     ...
;             PG8_WAIT_V(8); PG8_WAIT_L(0); PG8_BAR; PG8_MMA(1, 0, At, B0); PG8_MMA(1, 1, At, B1); PG8_BAR; PG8_SCHED;
;             PG8_LDB(B0, 1, 0); PG8_LDB(B1, 1, 1); PG8_SCHED; PG8_LDA(At, 1, 0); PG8_STAGE(PG8_SA(0, 1), a2 + hstep, voffA);
;             PG8_WAIT_V(8); PG8_WAIT_L(0); PG8_BAR; PG8_MMA(0, 0, At, B0); PG8_MMA(0, 1, At, B1); PG8_BAR; PG8_SCHED;
	s_setprio 1
	s_waitcnt lgkmcnt(0)
	v_mfma_f32_16x16x32_bf16 v[60:63], v[154:157], v[192:195], v[60:63]
	v_mfma_f32_16x16x32_bf16 v[56:59], v[162:165], v[192:195], v[56:59]
	v_mfma_f32_16x16x32_bf16 v[52:55], v[154:157], v[200:203], v[52:55]
	v_mfma_f32_16x16x32_bf16 v[44:47], v[162:165], v[200:203], v[44:47]
	v_mfma_f32_16x16x32_bf16 v[36:39], v[154:157], v[208:211], v[36:39]
	v_mfma_f32_16x16x32_bf16 v[28:31], v[162:165], v[208:211], v[28:31]
	v_mfma_f32_16x16x32_bf16 v[20:23], v[154:157], v[224:227], v[20:23]
	v_mfma_f32_16x16x32_bf16 v[12:15], v[162:165], v[224:227], v[12:15]
	v_mfma_f32_16x16x32_bf16 v[60:63], v[158:161], v[196:199], v[60:63]
	v_mfma_f32_16x16x32_bf16 v[56:59], v[172:175], v[196:199], v[56:59]
	v_mfma_f32_16x16x32_bf16 v[52:55], v[158:161], v[204:207], v[52:55]
	v_mfma_f32_16x16x32_bf16 v[44:47], v[172:175], v[204:207], v[44:47]
	v_mfma_f32_16x16x32_bf16 v[36:39], v[158:161], v[220:223], v[36:39]
	v_mfma_f32_16x16x32_bf16 v[28:31], v[172:175], v[220:223], v[28:31]
	v_mfma_f32_16x16x32_bf16 v[20:23], v[158:161], v[230:233], v[20:23]
	v_mfma_f32_16x16x32_bf16 v[12:15], v[172:175], v[230:233], v[12:15]
	v_mfma_f32_16x16x32_bf16 v[48:51], v[176:179], v[192:195], v[48:51]
	v_mfma_f32_16x16x32_bf16 v[40:43], v[184:187], v[192:195], v[40:43]
	v_mfma_f32_16x16x32_bf16 v[32:35], v[176:179], v[200:203], v[32:35]
	v_mfma_f32_16x16x32_bf16 v[24:27], v[184:187], v[200:203], v[24:27]
	v_mfma_f32_16x16x32_bf16 v[16:19], v[176:179], v[208:211], v[16:19]
	v_mfma_f32_16x16x32_bf16 v[8:11], v[184:187], v[208:211], v[8:11]
	v_mfma_f32_16x16x32_bf16 v[4:7], v[176:179], v[224:227], v[4:7]
	v_mfma_f32_16x16x32_bf16 v[0:3], v[184:187], v[224:227], v[0:3]
	v_mfma_f32_16x16x32_bf16 v[48:51], v[180:183], v[196:199], v[48:51]
	v_mfma_f32_16x16x32_bf16 v[40:43], v[188:191], v[196:199], v[40:43]
	v_mfma_f32_16x16x32_bf16 v[32:35], v[180:183], v[204:207], v[32:35]
	v_mfma_f32_16x16x32_bf16 v[24:27], v[188:191], v[204:207], v[24:27]
	v_mfma_f32_16x16x32_bf16 v[16:19], v[180:183], v[220:223], v[16:19]
	v_mfma_f32_16x16x32_bf16 v[8:11], v[188:191], v[220:223], v[8:11]
	v_mfma_f32_16x16x32_bf16 v[4:7], v[180:183], v[230:233], v[4:7]
	v_mfma_f32_16x16x32_bf16 v[0:3], v[188:191], v[230:233], v[0:3]
	s_setprio 0
	s_barrier
	s_add_i32 s92, 0, 0x18000
	v_add_u32_e32 v136, s92, v149
	s_add_i32 s93, 0, 0x1c000
	ds_read_b128 v[154:157], v136
	ds_read_b128 v[158:161], v136 offset:1024
	ds_read_b128 v[162:165], v136 offset:2048
	ds_read_b128 v[172:175], v136 offset:3072
	v_add_u32_e32 v136, s93, v149
	ds_read_b128 v[176:179], v136
	ds_read_b128 v[180:183], v136 offset:1024
	ds_read_b128 v[184:187], v136 offset:2048
	ds_read_b128 v[188:191], v136 offset:3072
	s_add_u32 s66, s66, 0x40000
	s_addc_u32 s67, s67, 0
	s_mov_b32 m0, s74
	v_lshl_add_u64 v[234:235], s[66:67], 0, v[128:129]
	ds_read_b128 v[192:195], v153 offset:32768
	ds_read_b128 v[196:199], v153 offset:33792
	ds_read_b128 v[200:203], v153 offset:34816
	ds_read_b128 v[204:207], v153 offset:35840
	ds_read_b128 v[208:211], v153 offset:36864
	ds_read_b128 v[220:223], v153 offset:37888
	ds_read_b128 v[224:227], v153 offset:38912
	ds_read_b128 v[230:233], v153 offset:39936
	global_load_lds_dwordx4 v[234:235], off
	v_lshl_add_u64 v[234:235], s[66:67], 0, v[132:133]
	s_mov_b32 m0, s75
	s_nop 0
	global_load_lds_dwordx4 v[234:235], off
	s_waitcnt vmcnt(8)
	s_waitcnt lgkmcnt(0)
	s_barrier
	s_setprio 1
	s_waitcnt lgkmcnt(0)
	v_mfma_f32_16x16x32_bf16 v[124:127], v[154:157], v[192:195], v[124:127]
	v_mfma_f32_16x16x32_bf16 v[120:123], v[162:165], v[192:195], v[120:123]
	v_mfma_f32_16x16x32_bf16 v[116:119], v[154:157], v[200:203], v[116:119]
	v_mfma_f32_16x16x32_bf16 v[108:111], v[162:165], v[200:203], v[108:111]
	v_mfma_f32_16x16x32_bf16 v[100:103], v[154:157], v[208:211], v[100:103]
	v_mfma_f32_16x16x32_bf16 v[92:95], v[162:165], v[208:211], v[92:95]
	v_mfma_f32_16x16x32_bf16 v[84:87], v[154:157], v[224:227], v[84:87]
	v_mfma_f32_16x16x32_bf16 v[76:79], v[162:165], v[224:227], v[76:79]
	v_mfma_f32_16x16x32_bf16 v[124:127], v[158:161], v[196:199], v[124:127]
	v_mfma_f32_16x16x32_bf16 v[120:123], v[172:175], v[196:199], v[120:123]
	v_mfma_f32_16x16x32_bf16 v[116:119], v[158:161], v[204:207], v[116:119]
	v_mfma_f32_16x16x32_bf16 v[108:111], v[172:175], v[204:207], v[108:111]
	v_mfma_f32_16x16x32_bf16 v[100:103], v[158:161], v[220:223], v[100:103]
	v_mfma_f32_16x16x32_bf16 v[92:95], v[172:175], v[220:223], v[92:95]
	v_mfma_f32_16x16x32_bf16 v[84:87], v[158:161], v[230:233], v[84:87]
	v_mfma_f32_16x16x32_bf16 v[76:79], v[172:175], v[230:233], v[76:79]
	v_mfma_f32_16x16x32_bf16 v[112:115], v[176:179], v[192:195], v[112:115]
	v_mfma_f32_16x16x32_bf16 v[104:107], v[184:187], v[192:195], v[104:107]
	v_mfma_f32_16x16x32_bf16 v[96:99], v[176:179], v[200:203], v[96:99]
	v_mfma_f32_16x16x32_bf16 v[88:91], v[184:187], v[200:203], v[88:91]
	v_mfma_f32_16x16x32_bf16 v[80:83], v[176:179], v[208:211], v[80:83]
	v_mfma_f32_16x16x32_bf16 v[72:75], v[184:187], v[208:211], v[72:75]
	v_mfma_f32_16x16x32_bf16 v[68:71], v[176:179], v[224:227], v[68:71]
	v_mfma_f32_16x16x32_bf16 v[64:67], v[184:187], v[224:227], v[64:67]
	v_mfma_f32_16x16x32_bf16 v[112:115], v[180:183], v[196:199], v[112:115]
	v_mfma_f32_16x16x32_bf16 v[104:107], v[188:191], v[196:199], v[104:107]
	v_mfma_f32_16x16x32_bf16 v[96:99], v[180:183], v[204:207], v[96:99]
	v_mfma_f32_16x16x32_bf16 v[88:91], v[188:191], v[204:207], v[88:91]
	v_mfma_f32_16x16x32_bf16 v[80:83], v[180:183], v[220:223], v[80:83]
	v_mfma_f32_16x16x32_bf16 v[72:75], v[188:191], v[220:223], v[72:75]
	v_mfma_f32_16x16x32_bf16 v[68:71], v[180:183], v[230:233], v[68:71]
	v_mfma_f32_16x16x32_bf16 v[64:67], v[188:191], v[230:233], v[64:67]
	s_setprio 0
	s_barrier
; #define PG8_STAGE(bufoff, gbase, voff) do { _Pragma("unroll") for (int _i = 0; _i < 2; ++_i) \
;         __builtin_amdgcn_global_load_lds((const unsigned*)((const char*)(gbase) + (voff)[_i]), (PG8_LAS unsigned*)(lds + (bufoff) + ldsw + _i * 8192), 16, 0, 0); } while (0)
; #define PG8_LDA(dst, b, h) do { _Pragma("unroll") for (int m = 0; m < 4; ++m) _Pragma("unroll") for (int k = 0; k < 2; ++k) dst[m][k] = *(const PG8_LAS bf16x8*)(lds + PG8_SA(b, h) + aoff + m * 2048 + k * 1024); } while (0)
; #define PG8_MMA(ai, bj, At, Bt) do { __builtin_amdgcn_s_setprio(1); _Pragma("unroll") for (int m = 0; m < 4; ++m) _Pragma("unroll") for (int n = 0; n < 2; ++n) _Pragma("unroll") for (int k = 0; k < 2; ++k) \
;         acc[ai][bj][m][n] = __builtin_amdgcn_mfma_f32_16x16x32_bf16(Bt[n][k], At[m][k], acc[ai][bj][m][n], 0, 0, 0); __builtin_amdgcn_s_setprio(0); } while (0)
; #define PG8_WAIT_V(n) asm volatile("s_waitcnt vmcnt(" #n ")" ::: "memory")
; #define PG8_WAIT_L(n) asm volatile("s_waitcnt lgkmcnt(" #n ")" ::: "memory")
; #define PG8_BAR __builtin_amdgcn_s_barrier()
; #define PG8_SCHED __builtin_amdgcn_sched_barrier(0)
; template <class Epi, class Sched, bool ALIGN_EPI = false, bool SP2 = false>
; __device__ __forceinline__ void gemm_phase(PG8_LAS unsigned char* lds, const Gemm g, const Sched& S, const Epi& E, int tid_in) {
;     ...
;         for (int t = 0; t < nt; t += 2) {
;     ...
;             PG8_LDA(At, 1, 1); PG8_STAGE(PG8_SB(1, 0), b3, voffB); PG8_STAGE(PG8_SB(1, 1), b3 + hstep, voffB); PG8_STAGE(PG8_SA(1, 0), a3, voffA);
;             PG8_WAIT_V(8); PG8_WAIT_L(0); PG8_BAR; PG8_MMA(1, 0, At, B0); PG8_MMA(1, 1, At, B1); PG8_BAR; PG8_SCHED;
	s_add_i32 s66, s92, s72
	v_lshl_add_u64 v[146:147], v[146:147], 0, s[10:11]
	s_mov_b32 m0, s66
	ds_read_b128 v[192:195], v153 offset:49152
	ds_read_b128 v[196:199], v153 offset:50176
	ds_read_b128 v[200:203], v153 offset:51200
	ds_read_b128 v[204:207], v153 offset:52224
	ds_read_b128 v[208:211], v153 offset:53248
	ds_read_b128 v[220:223], v153 offset:54272
	ds_read_b128 v[224:227], v153 offset:55296
	ds_read_b128 v[230:233], v153 offset:56320
	global_load_lds_dwordx4 v[146:147], off
	s_add_i32 m0, s66, 0x2000
	s_add_u32 s64, s64, 0x40080
	v_lshl_add_u64 v[146:147], v[166:167], 0, s[10:11]
	s_addc_u32 s65, s65, 0
	s_add_i32 s66, s93, s72
	global_load_lds_dwordx4 v[146:147], off
	v_lshl_add_u64 v[146:147], s[64:65], 0, v[130:131]
	s_mov_b32 m0, s66
	s_nop 0
	global_load_lds_dwordx4 v[146:147], off
	v_lshl_add_u64 v[146:147], s[64:65], 0, v[134:135]
	s_add_i32 m0, s66, 0x2000
	s_nop 0
	global_load_lds_dwordx4 v[146:147], off
	v_lshl_add_u64 v[146:147], v[212:213], 0, s[10:11]
	s_mov_b32 m0, s77
	s_nop 0
	global_load_lds_dwordx4 v[146:147], off
	v_lshl_add_u64 v[146:147], v[216:217], 0, s[10:11]
	s_mov_b32 m0, s78
	s_nop 0
	global_load_lds_dwordx4 v[146:147], off
	s_waitcnt vmcnt(8)
	s_waitcnt lgkmcnt(0)
	s_barrier
	s_setprio 1
	s_waitcnt lgkmcnt(0)
	v_mfma_f32_16x16x32_bf16 v[60:63], v[154:157], v[192:195], v[60:63]
	v_mfma_f32_16x16x32_bf16 v[56:59], v[162:165], v[192:195], v[56:59]
	v_mfma_f32_16x16x32_bf16 v[52:55], v[154:157], v[200:203], v[52:55]
	v_mfma_f32_16x16x32_bf16 v[44:47], v[162:165], v[200:203], v[44:47]
	v_mfma_f32_16x16x32_bf16 v[36:39], v[154:157], v[208:211], v[36:39]
	v_mfma_f32_16x16x32_bf16 v[28:31], v[162:165], v[208:211], v[28:31]
	v_mfma_f32_16x16x32_bf16 v[20:23], v[154:157], v[224:227], v[20:23]
	v_mfma_f32_16x16x32_bf16 v[12:15], v[162:165], v[224:227], v[12:15]
	v_mfma_f32_16x16x32_bf16 v[60:63], v[158:161], v[196:199], v[60:63]
	v_mfma_f32_16x16x32_bf16 v[56:59], v[172:175], v[196:199], v[56:59]
	v_mfma_f32_16x16x32_bf16 v[52:55], v[158:161], v[204:207], v[52:55]
	v_mfma_f32_16x16x32_bf16 v[44:47], v[172:175], v[204:207], v[44:47]
	v_mfma_f32_16x16x32_bf16 v[36:39], v[158:161], v[220:223], v[36:39]
	v_mfma_f32_16x16x32_bf16 v[28:31], v[172:175], v[220:223], v[28:31]
	v_mfma_f32_16x16x32_bf16 v[20:23], v[158:161], v[230:233], v[20:23]
	v_mfma_f32_16x16x32_bf16 v[12:15], v[172:175], v[230:233], v[12:15]
	v_mfma_f32_16x16x32_bf16 v[48:51], v[176:179], v[192:195], v[48:51]
	v_mfma_f32_16x16x32_bf16 v[40:43], v[184:187], v[192:195], v[40:43]
	v_mfma_f32_16x16x32_bf16 v[32:35], v[176:179], v[200:203], v[32:35]
	v_mfma_f32_16x16x32_bf16 v[24:27], v[184:187], v[200:203], v[24:27]
	v_mfma_f32_16x16x32_bf16 v[16:19], v[176:179], v[208:211], v[16:19]
	v_mfma_f32_16x16x32_bf16 v[8:11], v[184:187], v[208:211], v[8:11]
	v_mfma_f32_16x16x32_bf16 v[4:7], v[176:179], v[224:227], v[4:7]
	v_mfma_f32_16x16x32_bf16 v[0:3], v[184:187], v[224:227], v[0:3]
	v_mfma_f32_16x16x32_bf16 v[48:51], v[180:183], v[196:199], v[48:51]
	v_mfma_f32_16x16x32_bf16 v[40:43], v[188:191], v[196:199], v[40:43]
	v_mfma_f32_16x16x32_bf16 v[32:35], v[180:183], v[204:207], v[32:35]
	v_mfma_f32_16x16x32_bf16 v[24:27], v[188:191], v[204:207], v[24:27]
	v_mfma_f32_16x16x32_bf16 v[16:19], v[180:183], v[220:223], v[16:19]
	v_mfma_f32_16x16x32_bf16 v[8:11], v[188:191], v[220:223], v[8:11]
	v_mfma_f32_16x16x32_bf16 v[4:7], v[180:183], v[230:233], v[4:7]
	v_mfma_f32_16x16x32_bf16 v[0:3], v[188:191], v[230:233], v[0:3]
	s_add_i32 s91, s91, 2
	s_add_u32 s62, s62, 0x100
	s_addc_u32 s63, s63, 0
	s_add_u32 s89, s89, 0x100
	s_addc_u32 s90, s90, 0
	s_cmp_gt_u32 s91, 13
	s_setprio 0
	s_barrier
	s_cbranch_scc0 .LBB0_214
	s_and_b64 vcc, exec, s[18:19]
	s_cbranch_vccz .LBB0_217
	s_barrier

; #define LAS __attribute__((address_space(3)))
; template <int HF> ...
;     ...
;     const float tb = slope2 * (float)(kvh0 + 4 * hi - qw0 - r32) - SB;
; #pragma unroll
;     for (int sub = 0; sub < 2; ++sub) {
;         f32x16 p;
; #pragma unroll
;         for (int r = 0; r < 16; ++r) p[r] = __builtin_fmaf(s2v, (float)((r & 3) + 8 * (r >> 2)), tb);
; #pragma unroll
;         for (int d0 = 0; d0 < 4; ++d0) { const bf16x8 kf = *(const LAS bf16x8*)(kb + HF * 32 * KROW + sub * 128 + d0 * 32);
;             p = __builtin_amdgcn_mfma_f32_32x32x16_bf16(kf, qf[sub][d0], p, 0, 0, 0); }
;         if (band) { const int lim = qw0 + r32 - (kvh0 + 4 * hi);
;             asm volatile("s_nop 15" : "+v"(p));
;             const float ninf = -INFINITY;
; #pragma unroll
;             for (int r = 0; r < 16; ++r) asm("v_cmp_gt_i32_e32 vcc, %2, %1\n\tv_cndmask_b32_e32 %0, %0, %3, vcc" : "+v"(p[r]) : "v"(lim), "i"((r & 3) + 8 * (r >> 2)), "v"(ninf) : "vcc"); }
.LBB0_251:
	s_mul_i32 s91, s92, 0x4400
	v_cndmask_b32_e64 v128, 0, 1, s[10:11]
	s_andn2_b64 vcc, exec, s[66:67]
	v_add_u32_e32 v247, s91, v235
	v_cmp_ne_u32_e64 s[10:11], 1, v128
	s_cbranch_vccnz .LBB0_259
	v_mov_b32_e32 v142, s86
	ds_read_b128 v[248:251], v247
	ds_read_b128 v[252:255], v247 offset:32
	v_add_u32_e32 v128, s89, v246
	v_cvt_f32_i32_e32 v128, v128
	v_mov_b32_e32 v129, s72
	v_add_u32_e32 v227, 32, v223
	s_and_b64 vcc, exec, s[10:11]
	v_fma_f32 v144, s86, v128, -v129
	v_fma_f32 v128, 0, v142, v144
	v_add_f32_e32 v129, v144, v142
	v_fma_f32 v131, v142, s21, v144
	v_fma_f32 v130, v142, s20, v144
	v_fma_f32 v133, v142, s23, v144
	v_fma_f32 v132, v142, s22, v144
	v_fma_f32 v135, v142, s41, v144
	v_fma_f32 v134, v142, s40, v144
	v_fma_f32 v137, v142, s43, v144
	v_fma_f32 v136, v142, s42, v144
	v_fma_f32 v139, v142, s53, v144
	v_fma_f32 v138, v142, s52, v144
	v_fma_f32 v141, v142, s59, v144
	v_fma_f32 v140, v142, s58, v144
	v_fma_f32 v143, v142, s61, v144
	v_fma_f32 v142, v142, s60, v144
	s_waitcnt vmcnt(7) lgkmcnt(1)
	s_nop 0
	v_mfma_f32_32x32x16_bf16 v[144:159], v[248:251], v[176:179], v[128:143]
	s_waitcnt vmcnt(6) lgkmcnt(0)
	v_mfma_f32_32x32x16_bf16 v[144:159], v[252:255], v[180:183], v[144:159]
	ds_read_b128 v[248:251], v247 offset:64
	ds_read_b128 v[252:255], v247 offset:96
	s_waitcnt vmcnt(5) lgkmcnt(1)
	v_mfma_f32_32x32x16_bf16 v[144:159], v[248:251], v[184:187], v[144:159]
	s_waitcnt vmcnt(4) lgkmcnt(0)
	v_mfma_f32_32x32x16_bf16 v[144:159], v[252:255], v[188:191], v[144:159]
	s_cbranch_vccnz .LBB0_254
	s_nop 15
	s_nop 0
	v_cmp_gt_i32_e32 vcc, 0, v227
	v_cndmask_b32_e32 v144, v144, v244, vcc
	s_nop 0
	v_cmp_gt_i32_e32 vcc, 1, v227
	v_cndmask_b32_e32 v145, v145, v244, vcc
	s_nop 0
	v_cmp_gt_i32_e32 vcc, 2, v227
	v_cndmask_b32_e32 v146, v146, v244, vcc
	s_nop 0
	v_cmp_gt_i32_e32 vcc, 3, v227
	v_cndmask_b32_e32 v147, v147, v244, vcc
	s_nop 0
	v_cmp_gt_i32_e32 vcc, 8, v227
	v_cndmask_b32_e32 v148, v148, v244, vcc
	s_nop 0
	v_cmp_gt_i32_e32 vcc, 9, v227
	v_cndmask_b32_e32 v149, v149, v244, vcc
	s_nop 0
	v_cmp_gt_i32_e32 vcc, 10, v227
	v_cndmask_b32_e32 v150, v150, v244, vcc
	s_nop 0
	v_cmp_gt_i32_e32 vcc, 11, v227
	v_cndmask_b32_e32 v151, v151, v244, vcc
	s_nop 0
	v_cmp_gt_i32_e32 vcc, 16, v227
	v_cndmask_b32_e32 v152, v152, v244, vcc
	s_nop 0
	v_cmp_gt_i32_e32 vcc, 17, v227
	v_cndmask_b32_e32 v153, v153, v244, vcc
	s_nop 0
	v_cmp_gt_i32_e32 vcc, 18, v227
	v_cndmask_b32_e32 v154, v154, v244, vcc
	s_nop 0
	v_cmp_gt_i32_e32 vcc, 19, v227
	v_cndmask_b32_e32 v155, v155, v244, vcc
	s_nop 0
	v_cmp_gt_i32_e32 vcc, 24, v227
	v_cndmask_b32_e32 v156, v156, v244, vcc
	s_nop 0
	v_cmp_gt_i32_e32 vcc, 25, v227
	v_cndmask_b32_e32 v157, v157, v244, vcc
	s_nop 0
	v_cmp_gt_i32_e32 vcc, 26, v227
	v_cndmask_b32_e32 v158, v158, v244, vcc
	s_nop 0
	v_cmp_gt_i32_e32 vcc, 27, v227
	v_cndmask_b32_e32 v159, v159, v244, vcc

; #define LAS __attribute__((address_space(3)))
; __device__ __forceinline__ unsigned cvtpk_s(float lo, float hi) { f32x2_t v = {lo, hi}; bf16x2_t b = __builtin_convertvector(v, bf16x2_t); return __builtin_bit_cast(unsigned, b); }
; template <int HF> ...
;     ...
;         float ls = 0.f;
; #pragma unroll
;         for (int r = 0; r < 16; ++r) { p[r] = __builtin_amdgcn_exp2f(p[r]); ls += p[r]; }
;         lsum[sub] += ls;
;         pw[sub][0] = (u32x4){cvtpk_s(p[0], p[1]), cvtpk_s(p[2], p[3]), cvtpk_s(p[4], p[5]), cvtpk_s(p[6], p[7])};
;         pw[sub][1] = (u32x4){cvtpk_s(p[8], p[9]), cvtpk_s(p[10], p[11]), cvtpk_s(p[12], p[13]), cvtpk_s(p[14], p[15])};
;         __builtin_amdgcn_sched_barrier(0);
;         if (sub == 0 && stage) {
;             if (HF == 0) { *(LAS u32x4*)sdst = st0; *(LAS u32x4*)(sdst + 32 * KROW) = st1; }
;             else { *(LAS u32x2*)sdst = (u32x2){st0.x, st0.y}; *(LAS u32x2*)(sdst + 8) = (u32x2){st0.z, st0.w}; *(LAS u32x2*)(sdst + 64 * VROW) = (u32x2){st1.x, st1.y}; *(LAS u32x2*)(sdst + 64 * VROW + 8) = (u32x2){st1.z, st1.w}; }
;             __builtin_amdgcn_sched_barrier(0);
;         }
;     }
;     ...
;     bf16x8 vcur = AT_VFRAG(0);
;     __builtin_amdgcn_s_setprio(1);
; #pragma unroll
;     for (int idx = 0; idx < 8; ++idx) {
;         bf16x8 vnext = vcur;
;         if (idx + 1 < 8) vnext = AT_VFRAG(idx + 1);
;         const int kk = idx >> 2, d = idx & 3;
;         o[0][d] = __builtin_amdgcn_mfma_f32_32x32x16_bf16(vcur, __builtin_bit_cast(bf16x8, pw[0][kk]), o[0][d], 0, 0, 0);
;         o[1][d] = __builtin_amdgcn_mfma_f32_32x32x16_bf16(vcur, __builtin_bit_cast(bf16x8, pw[1][kk]), o[1][d], 0, 0, 0);
;         __builtin_amdgcn_sched_barrier(0);
;         vcur = vnext;
;     }
;     __builtin_amdgcn_s_setprio(0);
.LBB0_258:
	v_exp_f32_e32 v227, v144
	v_exp_f32_e32 v248, v145
	v_exp_f32_e32 v249, v146
	v_exp_f32_e32 v250, v147
	v_exp_f32_e32 v148, v148
	v_add_f32_e32 v144, v248, v227
	v_exp_f32_e32 v149, v149
	v_add_f32_e32 v144, v249, v144
	v_exp_f32_e32 v150, v150
	v_add_f32_e32 v144, v250, v144
	v_exp_f32_e32 v151, v151
	v_add_f32_e32 v144, v148, v144
	v_exp_f32_e32 v152, v152
	v_add_f32_e32 v144, v149, v144
	v_exp_f32_e32 v153, v153
	v_add_f32_e32 v144, v150, v144
	v_exp_f32_e32 v145, v154
	v_add_f32_e32 v144, v151, v144
	v_exp_f32_e32 v154, v155
	v_add_f32_e32 v144, v152, v144
	v_exp_f32_e32 v146, v156
	v_add_f32_e32 v144, v153, v144
	v_exp_f32_e32 v155, v157
	v_add_f32_e32 v144, v145, v144
	v_exp_f32_e32 v147, v158
	v_add_f32_e32 v144, v154, v144
	v_exp_f32_e32 v156, v159
	v_add_f32_e32 v144, v146, v144
	v_exp_f32_e32 v128, v128
	v_add_f32_e32 v144, v155, v144
	v_exp_f32_e32 v129, v129
	v_add_f32_e32 v144, v147, v144
	v_exp_f32_e32 v130, v130
	v_add_f32_e32 v144, v156, v144
	v_exp_f32_e32 v131, v131
	v_add_f32_e32 v224, v224, v144
	v_cvt_pk_bf16_f32 v144, v152, v153
	v_exp_f32_e32 v132, v132
	v_add_f32_e32 v152, v129, v128
	v_exp_f32_e32 v133, v133
	v_add_f32_e32 v152, v130, v152
	v_exp_f32_e32 v134, v134
	v_add_f32_e32 v152, v131, v152
	v_exp_f32_e32 v135, v135
	v_add_f32_e32 v152, v132, v152
	v_exp_f32_e32 v136, v136
	v_add_f32_e32 v152, v133, v152
	v_exp_f32_e32 v137, v137
	v_add_f32_e32 v152, v134, v152
	v_exp_f32_e32 v138, v138
	v_add_f32_e32 v152, v135, v152
	v_exp_f32_e32 v139, v139
	v_add_f32_e32 v152, v136, v152
	v_exp_f32_e32 v140, v140
	v_add_f32_e32 v152, v137, v152
	v_exp_f32_e32 v141, v141
	v_add_f32_e32 v152, v138, v152
	v_exp_f32_e32 v142, v142
	v_add_f32_e32 v152, v139, v152
	v_exp_f32_e32 v143, v143
	v_add_f32_e32 v152, v140, v152
	v_add_f32_e32 v152, v141, v152
	v_add_f32_e32 v152, v142, v152
	v_add_f32_e32 v152, v143, v152
	v_add_f32_e32 v225, v225, v152
	v_cvt_pk_bf16_f32 v147, v147, v156
	v_cvt_pk_bf16_f32 v146, v146, v155
	v_cvt_pk_bf16_f32 v145, v145, v154
	v_cvt_pk_bf16_f32 v151, v150, v151
	v_cvt_pk_bf16_f32 v150, v148, v149
	v_cvt_pk_bf16_f32 v149, v249, v250
	v_cvt_pk_bf16_f32 v148, v227, v248
	v_cvt_pk_bf16_f32 v128, v128, v129
	v_cvt_pk_bf16_f32 v129, v130, v131
	v_cvt_pk_bf16_f32 v130, v132, v133
	v_cvt_pk_bf16_f32 v131, v134, v135
	v_cvt_pk_bf16_f32 v132, v136, v137
	v_cvt_pk_bf16_f32 v133, v138, v139
	v_cvt_pk_bf16_f32 v134, v140, v141
	v_cvt_pk_bf16_f32 v135, v142, v143
	v_add_u32_e32 v152, s91, v236
	v_add_u32_e32 v153, 0x8800, v152
	v_add_u32_e32 v154, 0x9800, v152
	v_add_u32_e32 v155, 0xa800, v152
	v_add_u32_e32 v156, 0xb800, v152
	ds_read2_b64 v[136:139], v153 offset0:0 offset1:2
	ds_read2_b64 v[140:143], v154 offset0:32 offset1:34
	ds_read2_b64 v[248:251], v155 offset0:64 offset1:66
	s_setprio 1
	s_waitcnt lgkmcnt(2)
	v_mfma_f32_32x32x16_bf16 v[64:79], v[136:139], v[148:151], v[64:79]
	ds_read2_b64 v[252:255], v156 offset0:96 offset1:98
	v_mfma_f32_32x32x16_bf16 v[112:127], v[136:139], v[128:131], v[112:127]
	s_waitcnt lgkmcnt(2)
	v_mfma_f32_32x32x16_bf16 v[48:63], v[140:143], v[148:151], v[48:63]
	ds_read2_b64 v[136:139], v153 offset0:4 offset1:6
	v_mfma_f32_32x32x16_bf16 v[96:111], v[140:143], v[128:131], v[96:111]
	s_waitcnt lgkmcnt(2)
	v_mfma_f32_32x32x16_bf16 v[16:31], v[248:251], v[148:151], v[16:31]
	ds_read2_b64 v[140:143], v154 offset0:36 offset1:38
	v_mfma_f32_32x32x16_bf16 v[80:95], v[248:251], v[128:131], v[80:95]
	s_waitcnt lgkmcnt(2)
	v_mfma_f32_32x32x16_bf16 v[0:15], v[252:255], v[148:151], v[0:15]
	ds_read2_b64 v[248:251], v155 offset0:68 offset1:70
	v_mfma_f32_32x32x16_bf16 v[32:47], v[252:255], v[128:131], v[32:47]
	s_waitcnt lgkmcnt(2)
	v_mfma_f32_32x32x16_bf16 v[64:79], v[136:139], v[144:147], v[64:79]
	ds_read2_b64 v[252:255], v156 offset0:100 offset1:102
	v_mfma_f32_32x32x16_bf16 v[112:127], v[136:139], v[132:135], v[112:127]
	s_waitcnt lgkmcnt(2)
	v_mfma_f32_32x32x16_bf16 v[48:63], v[140:143], v[144:147], v[48:63]
	v_mfma_f32_32x32x16_bf16 v[96:111], v[140:143], v[132:135], v[96:111]
	s_waitcnt lgkmcnt(1)
	v_mfma_f32_32x32x16_bf16 v[16:31], v[248:251], v[144:147], v[16:31]
	v_mfma_f32_32x32x16_bf16 v[80:95], v[248:251], v[132:135], v[80:95]
	s_waitcnt lgkmcnt(0)
	v_mfma_f32_32x32x16_bf16 v[0:15], v[252:255], v[144:147], v[0:15]
	v_mfma_f32_32x32x16_bf16 v[32:47], v[252:255], v[132:135], v[32:47]
	s_setprio 0

; #define LAS __attribute__((address_space(3)))
; template <int HF> ...
;     ...
;     const float tb = slope2 * (float)(kvh0 + 4 * hi - qw0 - r32) - SB;
; #pragma unroll
;     for (int sub = 0; sub < 2; ++sub) {
;         f32x16 p;
; #pragma unroll
;         for (int r = 0; r < 16; ++r) p[r] = __builtin_fmaf(s2v, (float)((r & 3) + 8 * (r >> 2)), tb);
; #pragma unroll
;         for (int d0 = 0; d0 < 4; ++d0) { const bf16x8 kf = *(const LAS bf16x8*)(kb + HF * 32 * KROW + sub * 128 + d0 * 32);
;             p = __builtin_amdgcn_mfma_f32_32x32x16_bf16(kf, qf[sub][d0], p, 0, 0, 0); }
;         if (band) { const int lim = qw0 + r32 - (kvh0 + 4 * hi);
;             asm volatile("s_nop 15" : "+v"(p));
;             const float ninf = -INFINITY;
; #pragma unroll
;             for (int r = 0; r < 16; ++r) asm("v_cmp_gt_i32_e32 vcc, %2, %1\n\tv_cndmask_b32_e32 %0, %0, %3, vcc" : "+v"(p[r]) : "v"(lim), "i"((r & 3) + 8 * (r >> 2)), "v"(ninf) : "vcc"); }
.LBB0_265:
	s_andn2_b64 vcc, exec, s[64:65]
	s_cbranch_vccnz .LBB0_273
	v_mov_b32_e32 v142, s86
	ds_read_b128 v[248:251], v247 offset:8704
	ds_read_b128 v[252:255], v247 offset:8736
	v_add3_u32 v128, v246, s89, 32
	v_cvt_f32_i32_e32 v128, v128
	v_mov_b32_e32 v129, s72
	s_and_b64 vcc, exec, s[10:11]
	v_fma_f32 v144, s86, v128, -v129
	v_fma_f32 v128, 0, v142, v144
	v_add_f32_e32 v129, v144, v142
	v_fma_f32 v131, v142, s21, v144
	v_fma_f32 v130, v142, s20, v144
	v_fma_f32 v133, v142, s23, v144
	v_fma_f32 v132, v142, s22, v144
	v_fma_f32 v135, v142, s41, v144
	v_fma_f32 v134, v142, s40, v144
	v_fma_f32 v137, v142, s43, v144
	v_fma_f32 v136, v142, s42, v144
	v_fma_f32 v139, v142, s53, v144
	v_fma_f32 v138, v142, s52, v144
	v_fma_f32 v141, v142, s59, v144
	v_fma_f32 v140, v142, s58, v144
	v_fma_f32 v143, v142, s61, v144
	v_fma_f32 v142, v142, s60, v144
	s_waitcnt vmcnt(7) lgkmcnt(1)
	s_nop 0
	v_mfma_f32_32x32x16_bf16 v[144:159], v[248:251], v[176:179], v[128:143]
	s_waitcnt vmcnt(6) lgkmcnt(0)
	v_mfma_f32_32x32x16_bf16 v[144:159], v[252:255], v[180:183], v[144:159]
	ds_read_b128 v[248:251], v247 offset:8768
	ds_read_b128 v[252:255], v247 offset:8800
	s_waitcnt vmcnt(5) lgkmcnt(1)
	v_mfma_f32_32x32x16_bf16 v[144:159], v[248:251], v[184:187], v[144:159]
	s_waitcnt vmcnt(4) lgkmcnt(0)
	v_mfma_f32_32x32x16_bf16 v[144:159], v[252:255], v[188:191], v[144:159]
	s_cbranch_vccnz .LBB0_268
	s_nop 15
	s_nop 0
	v_cmp_gt_i32_e32 vcc, 0, v223
	v_cndmask_b32_e32 v144, v144, v244, vcc
	s_nop 0
	v_cmp_gt_i32_e32 vcc, 1, v223
	v_cndmask_b32_e32 v145, v145, v244, vcc
	s_nop 0
	v_cmp_gt_i32_e32 vcc, 2, v223
	v_cndmask_b32_e32 v146, v146, v244, vcc
	s_nop 0
	v_cmp_gt_i32_e32 vcc, 3, v223
	v_cndmask_b32_e32 v147, v147, v244, vcc
	s_nop 0
	v_cmp_gt_i32_e32 vcc, 8, v223
	v_cndmask_b32_e32 v148, v148, v244, vcc
	s_nop 0
	v_cmp_gt_i32_e32 vcc, 9, v223
	v_cndmask_b32_e32 v149, v149, v244, vcc
	s_nop 0
	v_cmp_gt_i32_e32 vcc, 10, v223
	v_cndmask_b32_e32 v150, v150, v244, vcc
	s_nop 0
	v_cmp_gt_i32_e32 vcc, 11, v223
	v_cndmask_b32_e32 v151, v151, v244, vcc
	s_nop 0
	v_cmp_gt_i32_e32 vcc, 16, v223
	v_cndmask_b32_e32 v152, v152, v244, vcc
	s_nop 0
	v_cmp_gt_i32_e32 vcc, 17, v223
	v_cndmask_b32_e32 v153, v153, v244, vcc
	s_nop 0
	v_cmp_gt_i32_e32 vcc, 18, v223
	v_cndmask_b32_e32 v154, v154, v244, vcc
	s_nop 0
	v_cmp_gt_i32_e32 vcc, 19, v223
	v_cndmask_b32_e32 v155, v155, v244, vcc
	s_nop 0
	v_cmp_gt_i32_e32 vcc, 24, v223
	v_cndmask_b32_e32 v156, v156, v244, vcc
	s_nop 0
	v_cmp_gt_i32_e32 vcc, 25, v223
	v_cndmask_b32_e32 v157, v157, v244, vcc
	s_nop 0
	v_cmp_gt_i32_e32 vcc, 26, v223
	v_cndmask_b32_e32 v158, v158, v244, vcc
	s_nop 0
	v_cmp_gt_i32_e32 vcc, 27, v223
	v_cndmask_b32_e32 v159, v159, v244, vcc

; #define LAS __attribute__((address_space(3)))
; __device__ __forceinline__ unsigned cvtpk_s(float lo, float hi) { f32x2_t v = {lo, hi}; bf16x2_t b = __builtin_convertvector(v, bf16x2_t); return __builtin_bit_cast(unsigned, b); }
; template <int HF> ...
;     ...
;         float ls = 0.f;
; #pragma unroll
;         for (int r = 0; r < 16; ++r) { p[r] = __builtin_amdgcn_exp2f(p[r]); ls += p[r]; }
;         lsum[sub] += ls;
;         pw[sub][0] = (u32x4){cvtpk_s(p[0], p[1]), cvtpk_s(p[2], p[3]), cvtpk_s(p[4], p[5]), cvtpk_s(p[6], p[7])};
;         pw[sub][1] = (u32x4){cvtpk_s(p[8], p[9]), cvtpk_s(p[10], p[11]), cvtpk_s(p[12], p[13]), cvtpk_s(p[14], p[15])};
;         __builtin_amdgcn_sched_barrier(0);
;         if (sub == 0 && stage) {
;             if (HF == 0) { *(LAS u32x4*)sdst = st0; *(LAS u32x4*)(sdst + 32 * KROW) = st1; }
;             else { *(LAS u32x2*)sdst = (u32x2){st0.x, st0.y}; *(LAS u32x2*)(sdst + 8) = (u32x2){st0.z, st0.w}; *(LAS u32x2*)(sdst + 64 * VROW) = (u32x2){st1.x, st1.y}; *(LAS u32x2*)(sdst + 64 * VROW + 8) = (u32x2){st1.z, st1.w}; }
;             __builtin_amdgcn_sched_barrier(0);
;         }
;     }
;     ...
;     bf16x8 vcur = AT_VFRAG(0);
;     __builtin_amdgcn_s_setprio(1);
; #pragma unroll
;     for (int idx = 0; idx < 8; ++idx) {
;         bf16x8 vnext = vcur;
;         if (idx + 1 < 8) vnext = AT_VFRAG(idx + 1);
;         const int kk = idx >> 2, d = idx & 3;
;         o[0][d] = __builtin_amdgcn_mfma_f32_32x32x16_bf16(vcur, __builtin_bit_cast(bf16x8, pw[0][kk]), o[0][d], 0, 0, 0);
;         o[1][d] = __builtin_amdgcn_mfma_f32_32x32x16_bf16(vcur, __builtin_bit_cast(bf16x8, pw[1][kk]), o[1][d], 0, 0, 0);
;         __builtin_amdgcn_sched_barrier(0);
;         vcur = vnext;
;     }
;     __builtin_amdgcn_s_setprio(0);
.LBB0_272:
	v_exp_f32_e32 v227, v144
	v_exp_f32_e32 v247, v145
	v_exp_f32_e32 v248, v146
	v_exp_f32_e32 v249, v147
	v_exp_f32_e32 v148, v148
	v_add_f32_e32 v144, v247, v227
	v_exp_f32_e32 v149, v149
	v_add_f32_e32 v144, v248, v144
	v_exp_f32_e32 v150, v150
	v_add_f32_e32 v144, v249, v144
	v_exp_f32_e32 v151, v151
	v_add_f32_e32 v144, v148, v144
	v_exp_f32_e32 v152, v152
	v_add_f32_e32 v144, v149, v144
	v_exp_f32_e32 v153, v153
	v_add_f32_e32 v144, v150, v144
	v_exp_f32_e32 v145, v154
	v_add_f32_e32 v144, v151, v144
	v_exp_f32_e32 v154, v155
	v_add_f32_e32 v144, v152, v144
	v_exp_f32_e32 v146, v156
	v_add_f32_e32 v144, v153, v144
	v_exp_f32_e32 v155, v157
	v_add_f32_e32 v144, v145, v144
	v_exp_f32_e32 v147, v158
	v_add_f32_e32 v144, v154, v144
	v_exp_f32_e32 v156, v159
	v_add_f32_e32 v144, v146, v144
	v_exp_f32_e32 v128, v128
	v_add_f32_e32 v144, v155, v144
	v_exp_f32_e32 v129, v129
	v_add_f32_e32 v144, v147, v144
	v_exp_f32_e32 v130, v130
	v_add_f32_e32 v144, v156, v144
	v_exp_f32_e32 v131, v131
	v_add_f32_e32 v224, v224, v144
	v_cvt_pk_bf16_f32 v144, v152, v153
	v_exp_f32_e32 v132, v132
	v_add_f32_e32 v152, v129, v128
	v_exp_f32_e32 v133, v133
	v_add_f32_e32 v152, v130, v152
	v_exp_f32_e32 v134, v134
	v_add_f32_e32 v152, v131, v152
	v_exp_f32_e32 v135, v135
	v_add_f32_e32 v152, v132, v152
	v_exp_f32_e32 v136, v136
	v_add_f32_e32 v152, v133, v152
	v_exp_f32_e32 v137, v137
	v_add_f32_e32 v152, v134, v152
	v_exp_f32_e32 v138, v138
	v_add_f32_e32 v152, v135, v152
	v_exp_f32_e32 v139, v139
	v_add_f32_e32 v152, v136, v152
	v_exp_f32_e32 v140, v140
	v_add_f32_e32 v152, v137, v152
	v_exp_f32_e32 v141, v141
	v_add_f32_e32 v152, v138, v152
	v_exp_f32_e32 v142, v142
	v_add_f32_e32 v152, v139, v152
	v_exp_f32_e32 v143, v143
	v_add_f32_e32 v152, v140, v152
	v_add_f32_e32 v152, v141, v152
	v_add_f32_e32 v152, v142, v152
	v_add_f32_e32 v152, v143, v152
	v_add_f32_e32 v225, v225, v152
	v_cvt_pk_bf16_f32 v147, v147, v156
	v_cvt_pk_bf16_f32 v146, v146, v155
	v_cvt_pk_bf16_f32 v145, v145, v154
	v_cvt_pk_bf16_f32 v151, v150, v151
	v_cvt_pk_bf16_f32 v150, v148, v149
	v_cvt_pk_bf16_f32 v149, v248, v249
	v_cvt_pk_bf16_f32 v148, v227, v247
	v_cvt_pk_bf16_f32 v128, v128, v129
	v_cvt_pk_bf16_f32 v129, v130, v131
	v_cvt_pk_bf16_f32 v130, v132, v133
	v_cvt_pk_bf16_f32 v131, v134, v135
	v_cvt_pk_bf16_f32 v132, v136, v137
	v_cvt_pk_bf16_f32 v133, v138, v139
	v_cvt_pk_bf16_f32 v134, v140, v141
	v_cvt_pk_bf16_f32 v135, v142, v143
	v_add_u32_e32 v152, s91, v236
	v_add_u32_e32 v153, 0x8800, v152
	v_add_u32_e32 v154, 0x9800, v152
	v_add_u32_e32 v155, 0xa800, v152
	v_add_u32_e32 v156, 0xb800, v152
	ds_read2_b64 v[136:139], v153 offset0:8 offset1:10
	ds_read2_b64 v[140:143], v154 offset0:40 offset1:42
	ds_read2_b64 v[248:251], v155 offset0:72 offset1:74
	s_setprio 1
	s_waitcnt lgkmcnt(2)
	v_mfma_f32_32x32x16_bf16 v[64:79], v[136:139], v[148:151], v[64:79]
	ds_read2_b64 v[252:255], v156 offset0:104 offset1:106
	v_mfma_f32_32x32x16_bf16 v[112:127], v[136:139], v[128:131], v[112:127]
	s_waitcnt lgkmcnt(2)
	v_mfma_f32_32x32x16_bf16 v[48:63], v[140:143], v[148:151], v[48:63]
	ds_read2_b64 v[136:139], v153 offset0:12 offset1:14
	v_mfma_f32_32x32x16_bf16 v[96:111], v[140:143], v[128:131], v[96:111]
	s_waitcnt lgkmcnt(2)
	v_mfma_f32_32x32x16_bf16 v[16:31], v[248:251], v[148:151], v[16:31]
	ds_read2_b64 v[140:143], v154 offset0:44 offset1:46
	v_mfma_f32_32x32x16_bf16 v[80:95], v[248:251], v[128:131], v[80:95]
	s_waitcnt lgkmcnt(2)
	v_mfma_f32_32x32x16_bf16 v[0:15], v[252:255], v[148:151], v[0:15]
	ds_read2_b64 v[248:251], v155 offset0:76 offset1:78
	v_mfma_f32_32x32x16_bf16 v[32:47], v[252:255], v[128:131], v[32:47]
	s_waitcnt lgkmcnt(2)
	v_mfma_f32_32x32x16_bf16 v[64:79], v[136:139], v[144:147], v[64:79]
	ds_read2_b64 v[252:255], v156 offset0:108 offset1:110
	v_mfma_f32_32x32x16_bf16 v[112:127], v[136:139], v[132:135], v[112:127]
	s_waitcnt lgkmcnt(2)
	v_mfma_f32_32x32x16_bf16 v[48:63], v[140:143], v[144:147], v[48:63]
	v_mfma_f32_32x32x16_bf16 v[96:111], v[140:143], v[132:135], v[96:111]
	s_waitcnt lgkmcnt(1)
	v_mfma_f32_32x32x16_bf16 v[16:31], v[248:251], v[144:147], v[16:31]
	v_mfma_f32_32x32x16_bf16 v[80:95], v[248:251], v[132:135], v[80:95]
	s_waitcnt lgkmcnt(0)
	v_mfma_f32_32x32x16_bf16 v[0:15], v[252:255], v[144:147], v[0:15]
	v_mfma_f32_32x32x16_bf16 v[32:47], v[252:255], v[132:135], v[32:47]
	s_setprio 0

; #define PG8_STAGE(bufoff, gbase, voff) do { _Pragma("unroll") for (int _i = 0; _i < 2; ++_i) \
;         __builtin_amdgcn_global_load_lds((const unsigned*)((const char*)(gbase) + (voff)[_i]), (PG8_LAS unsigned*)(lds + (bufoff) + ldsw + _i * 8192), 16, 0, 0); } while (0)
; #define PG8_LDA(dst, b, h) do { _Pragma("unroll") for (int m = 0; m < 4; ++m) _Pragma("unroll") for (int k = 0; k < 2; ++k) dst[m][k] = *(const PG8_LAS bf16x8*)(lds + PG8_SA(b, h) + aoff + m * 2048 + k * 1024); } while (0)
; #define PG8_LDB(dst, b, h) do { _Pragma("unroll") for (int n = 0; n < 2; ++n) _Pragma("unroll") for (int k = 0; k < 2; ++k) dst[n][k] = *(const PG8_LAS bf16x8*)(lds + PG8_SB(b, h) + boff + n * 2048 + k * 1024); } while (0)
; #define PG8_MMA(ai, bj, At, Bt) do { __builtin_amdgcn_s_setprio(1); _Pragma("unroll") for (int m = 0; m < 4; ++m) _Pragma("unroll") for (int n = 0; n < 2; ++n) _Pragma("unroll") for (int k = 0; k < 2; ++k) \
;         acc[ai][bj][m][n] = __builtin_amdgcn_mfma_f32_16x16x32_bf16(Bt[n][k], At[m][k], acc[ai][bj][m][n], 0, 0, 0); __builtin_amdgcn_s_setprio(0); } while (0)
; #define PG8_WAIT_V(n) asm volatile("s_waitcnt vmcnt(" #n ")" ::: "memory")
; #define PG8_WAIT_L(n) asm volatile("s_waitcnt lgkmcnt(" #n ")" ::: "memory")
; #define PG8_BAR __builtin_amdgcn_s_barrier()
; #define PG8_SCHED __builtin_amdgcn_sched_barrier(0)
; template <class Epi, class Sched, bool ALIGN_EPI = false, bool SP2 = false>
; __device__ __forceinline__ void gemm_phase(PG8_LAS unsigned char* lds, const Gemm g, const Sched& S, const Epi& E, int tid_in) {
;     ...
;             PG8_LDB(B0, 0, 0); PG8_LDB(B1, 0, 1); PG8_SCHED; PG8_LDA(At, 0, 0); PG8_STAGE(PG8_SA(1, 1), a1 + hstep, voffA);
;             PG8_WAIT_V(8); PG8_WAIT_L(0); PG8_BAR; PG8_MMA(0, 0, At, B0); PG8_MMA(0, 1, At, B1); PG8_BAR; PG8_SCHED;
;             PG8_LDA(At, 0, 1); PG8_STAGE(PG8_SB(0, 0), b2, voffB); PG8_STAGE(PG8_SB(0, 1), b2 + hstep, voffB); PG8_STAGE(PG8_SA(0, 0), a2, voffA);
.LBB0_302:
	ds_read_b128 v[146:149], v154
	ds_read_b128 v[158:161], v154 offset:1024
	ds_read_b128 v[162:165], v154 offset:2048
	ds_read_b128 v[166:169], v154 offset:3072
	ds_read_b128 v[170:173], v155
	ds_read_b128 v[174:177], v155 offset:1024
	ds_read_b128 v[178:181], v155 offset:2048
	ds_read_b128 v[182:185], v155 offset:3072
	s_add_u32 s62, s60, 0xfff80080
	s_addc_u32 s63, s61, -1
	s_cmp_eq_u32 s85, 28
	s_cselect_b32 s65, s43, s63
	s_cselect_b32 s64, s57, s62
	s_cselect_b32 s63, s41, s84
	s_cselect_b32 s62, s82, s83
	v_lshl_add_u64 v[222:223], s[60:61], 0, v[138:139]
	s_add_i32 m0, s59, 0xc000
	ds_read_b128 v[186:189], v156
	ds_read_b128 v[190:193], v156 offset:1024
	ds_read_b128 v[194:197], v156 offset:2048
	ds_read_b128 v[198:201], v156 offset:3072
	ds_read_b128 v[202:205], v156 offset:4096
	ds_read_b128 v[206:209], v156 offset:5120
	ds_read_b128 v[210:213], v156 offset:6144
	ds_read_b128 v[218:221], v156 offset:7168
	global_load_lds_dwordx4 v[222:223], off
	v_lshl_add_u64 v[222:223], s[60:61], 0, v[140:141]
	s_add_i32 m0, s59, 0xe000
	s_nop 0
	global_load_lds_dwordx4 v[222:223], off
	s_waitcnt vmcnt(8)
	s_waitcnt lgkmcnt(0)
	s_barrier
	s_setprio 1
	s_waitcnt lgkmcnt(0)
	v_mfma_f32_16x16x32_bf16 v[124:127], v[146:149], v[186:189], v[124:127]
	v_mfma_f32_16x16x32_bf16 v[120:123], v[162:165], v[186:189], v[120:123]
	v_mfma_f32_16x16x32_bf16 v[108:111], v[146:149], v[194:197], v[108:111]
	v_mfma_f32_16x16x32_bf16 v[104:107], v[162:165], v[194:197], v[104:107]
	v_mfma_f32_16x16x32_bf16 v[92:95], v[146:149], v[202:205], v[92:95]
	v_mfma_f32_16x16x32_bf16 v[88:91], v[162:165], v[202:205], v[88:91]
	v_mfma_f32_16x16x32_bf16 v[76:79], v[146:149], v[210:213], v[76:79]
	v_mfma_f32_16x16x32_bf16 v[72:75], v[162:165], v[210:213], v[72:75]
	v_mfma_f32_16x16x32_bf16 v[124:127], v[158:161], v[190:193], v[124:127]
	v_mfma_f32_16x16x32_bf16 v[120:123], v[166:169], v[190:193], v[120:123]
	v_mfma_f32_16x16x32_bf16 v[108:111], v[158:161], v[198:201], v[108:111]
	v_mfma_f32_16x16x32_bf16 v[104:107], v[166:169], v[198:201], v[104:107]
	v_mfma_f32_16x16x32_bf16 v[92:95], v[158:161], v[206:209], v[92:95]
	v_mfma_f32_16x16x32_bf16 v[88:91], v[166:169], v[206:209], v[88:91]
	v_mfma_f32_16x16x32_bf16 v[76:79], v[158:161], v[218:221], v[76:79]
	v_mfma_f32_16x16x32_bf16 v[72:75], v[166:169], v[218:221], v[72:75]
	v_mfma_f32_16x16x32_bf16 v[116:119], v[170:173], v[186:189], v[116:119]
	v_mfma_f32_16x16x32_bf16 v[112:115], v[178:181], v[186:189], v[112:115]
	v_mfma_f32_16x16x32_bf16 v[100:103], v[170:173], v[194:197], v[100:103]
	v_mfma_f32_16x16x32_bf16 v[96:99], v[178:181], v[194:197], v[96:99]
	v_mfma_f32_16x16x32_bf16 v[84:87], v[170:173], v[202:205], v[84:87]
	v_mfma_f32_16x16x32_bf16 v[80:83], v[178:181], v[202:205], v[80:83]
	v_mfma_f32_16x16x32_bf16 v[68:71], v[170:173], v[210:213], v[68:71]
	v_mfma_f32_16x16x32_bf16 v[64:67], v[178:181], v[210:213], v[64:67]
	v_mfma_f32_16x16x32_bf16 v[116:119], v[174:177], v[190:193], v[116:119]
	v_mfma_f32_16x16x32_bf16 v[112:115], v[182:185], v[190:193], v[112:115]
	v_mfma_f32_16x16x32_bf16 v[100:103], v[174:177], v[198:201], v[100:103]
	v_mfma_f32_16x16x32_bf16 v[96:99], v[182:185], v[198:201], v[96:99]
	v_mfma_f32_16x16x32_bf16 v[84:87], v[174:177], v[206:209], v[84:87]
	v_mfma_f32_16x16x32_bf16 v[80:83], v[182:185], v[206:209], v[80:83]
	v_mfma_f32_16x16x32_bf16 v[68:71], v[174:177], v[218:221], v[68:71]
	v_mfma_f32_16x16x32_bf16 v[64:67], v[182:185], v[218:221], v[64:67]
	s_setprio 0
	s_barrier
	s_add_i32 s86, s80, s71
	v_lshl_add_u64 v[222:223], s[62:63], 0, v[130:131]
	s_mov_b32 m0, s86
	ds_read_b128 v[186:189], v156 offset:16384
	ds_read_b128 v[190:193], v156 offset:17408
	ds_read_b128 v[194:197], v156 offset:18432
	ds_read_b128 v[198:201], v156 offset:19456
	ds_read_b128 v[202:205], v156 offset:20480
	ds_read_b128 v[206:209], v156 offset:21504
	ds_read_b128 v[210:213], v156 offset:22528
	ds_read_b128 v[218:221], v156 offset:23552
	global_load_lds_dwordx4 v[222:223], off
	s_add_i32 m0, s86, 0x2000
	s_add_u32 s86, s62, 0x80000
	v_lshl_add_u64 v[224:225], s[62:63], 0, v[134:135]
	s_addc_u32 s87, s63, 0
	s_add_i32 s88, s81, s71
	global_load_lds_dwordx4 v[224:225], off
	v_lshl_add_u64 v[226:227], s[86:87], 0, v[130:131]
	s_mov_b32 m0, s88
	v_lshl_add_u64 v[228:229], s[64:65], 0, v[132:133]
	global_load_lds_dwordx4 v[226:227], off
	v_lshl_add_u64 v[226:227], s[86:87], 0, v[134:135]
	s_add_i32 m0, s88, 0x2000
	s_nop 0
	global_load_lds_dwordx4 v[226:227], off
	v_lshl_add_u64 v[226:227], s[64:65], 0, v[128:129]
	s_mov_b32 m0, s59
	s_nop 0
	global_load_lds_dwordx4 v[226:227], off
	s_mov_b32 m0, s72
	s_nop 0
	global_load_lds_dwordx4 v[228:229], off
	s_waitcnt vmcnt(8)
	s_waitcnt lgkmcnt(0)
	s_barrier
; #define PG8_STAGE(bufoff, gbase, voff) do { _Pragma("unroll") for (int _i = 0; _i < 2; ++_i) \
;         __builtin_amdgcn_global_load_lds((const unsigned*)((const char*)(gbase) + (voff)[_i]), (PG8_LAS unsigned*)(lds + (bufoff) + ldsw + _i * 8192), 16, 0, 0); } while (0)
; #define PG8_LDA(dst, b, h) do { _Pragma("unroll") for (int m = 0; m < 4; ++m) _Pragma("unroll") for (int k = 0; k < 2; ++k) dst[m][k] = *(const PG8_LAS bf16x8*)(lds + PG8_SA(b, h) + aoff + m * 2048 + k * 1024); } while (0)
; #define PG8_LDB(dst, b, h) do { _Pragma("unroll") for (int n = 0; n < 2; ++n) _Pragma("unroll") for (int k = 0; k < 2; ++k) dst[n][k] = *(const PG8_LAS bf16x8*)(lds + PG8_SB(b, h) + boff + n * 2048 + k * 1024); } while (0)
; #define PG8_MMA(ai, bj, At, Bt) do { __builtin_amdgcn_s_setprio(1); _Pragma("unroll") for (int m = 0; m < 4; ++m) _Pragma("unroll") for (int n = 0; n < 2; ++n) _Pragma("unroll") for (int k = 0; k < 2; ++k) \
;         acc[ai][bj][m][n] = __builtin_amdgcn_mfma_f32_16x16x32_bf16(Bt[n][k], At[m][k], acc[ai][bj][m][n], 0, 0, 0); __builtin_amdgcn_s_setprio(0); } while (0)
; #define PG8_WAIT_V(n) asm volatile("s_waitcnt vmcnt(" #n ")" ::: "memory")
; #define PG8_WAIT_L(n) asm volatile("s_waitcnt lgkmcnt(" #n ")" ::: "memory")
; #define PG8_BAR __builtin_amdgcn_s_barrier()
; #define PG8_SCHED __builtin_amdgcn_sched_barrier(0)
; template <class Epi, class Sched, bool ALIGN_EPI = false, bool SP2 = false>
; __device__ __forceinline__ void gemm_phase(PG8_LAS unsigned char* lds, const Gemm g, const Sched& S, const Epi& E, int tid_in) {
;     ...
;             PG8_WAIT_V(8); PG8_WAIT_L(0); PG8_BAR; PG8_MMA(1, 0, At, B0); PG8_MMA(1, 1, At, B1); PG8_BAR; PG8_SCHED;
;             PG8_LDB(B0, 1, 0); PG8_LDB(B1, 1, 1); PG8_SCHED; PG8_LDA(At, 1, 0); PG8_STAGE(PG8_SA(0, 1), a2 + hstep, voffA);
;             PG8_WAIT_V(8); PG8_WAIT_L(0); PG8_BAR; PG8_MMA(0, 0, At, B0); PG8_MMA(0, 1, At, B1); PG8_BAR; PG8_SCHED;
	s_setprio 1
	s_waitcnt lgkmcnt(0)
	v_mfma_f32_16x16x32_bf16 v[60:63], v[146:149], v[186:189], v[60:63]
	v_mfma_f32_16x16x32_bf16 v[56:59], v[162:165], v[186:189], v[56:59]
	v_mfma_f32_16x16x32_bf16 v[44:47], v[146:149], v[194:197], v[44:47]
	v_mfma_f32_16x16x32_bf16 v[40:43], v[162:165], v[194:197], v[40:43]
	v_mfma_f32_16x16x32_bf16 v[28:31], v[146:149], v[202:205], v[28:31]
	v_mfma_f32_16x16x32_bf16 v[24:27], v[162:165], v[202:205], v[24:27]
	v_mfma_f32_16x16x32_bf16 v[12:15], v[146:149], v[210:213], v[12:15]
	v_mfma_f32_16x16x32_bf16 v[8:11], v[162:165], v[210:213], v[8:11]
	v_mfma_f32_16x16x32_bf16 v[60:63], v[158:161], v[190:193], v[60:63]
	v_mfma_f32_16x16x32_bf16 v[56:59], v[166:169], v[190:193], v[56:59]
	v_mfma_f32_16x16x32_bf16 v[44:47], v[158:161], v[198:201], v[44:47]
	v_mfma_f32_16x16x32_bf16 v[40:43], v[166:169], v[198:201], v[40:43]
	v_mfma_f32_16x16x32_bf16 v[28:31], v[158:161], v[206:209], v[28:31]
	v_mfma_f32_16x16x32_bf16 v[24:27], v[166:169], v[206:209], v[24:27]
	v_mfma_f32_16x16x32_bf16 v[12:15], v[158:161], v[218:221], v[12:15]
	v_mfma_f32_16x16x32_bf16 v[8:11], v[166:169], v[218:221], v[8:11]
	v_mfma_f32_16x16x32_bf16 v[52:55], v[170:173], v[186:189], v[52:55]
	v_mfma_f32_16x16x32_bf16 v[48:51], v[178:181], v[186:189], v[48:51]
	v_mfma_f32_16x16x32_bf16 v[36:39], v[170:173], v[194:197], v[36:39]
	v_mfma_f32_16x16x32_bf16 v[32:35], v[178:181], v[194:197], v[32:35]
	v_mfma_f32_16x16x32_bf16 v[20:23], v[170:173], v[202:205], v[20:23]
	v_mfma_f32_16x16x32_bf16 v[16:19], v[178:181], v[202:205], v[16:19]
	v_mfma_f32_16x16x32_bf16 v[4:7], v[170:173], v[210:213], v[4:7]
	v_mfma_f32_16x16x32_bf16 v[0:3], v[178:181], v[210:213], v[0:3]
	v_mfma_f32_16x16x32_bf16 v[52:55], v[174:177], v[190:193], v[52:55]
	v_mfma_f32_16x16x32_bf16 v[48:51], v[182:185], v[190:193], v[48:51]
	v_mfma_f32_16x16x32_bf16 v[36:39], v[174:177], v[198:201], v[36:39]
	v_mfma_f32_16x16x32_bf16 v[32:35], v[182:185], v[198:201], v[32:35]
	v_mfma_f32_16x16x32_bf16 v[20:23], v[174:177], v[206:209], v[20:23]
	v_mfma_f32_16x16x32_bf16 v[16:19], v[182:185], v[206:209], v[16:19]
	v_mfma_f32_16x16x32_bf16 v[4:7], v[174:177], v[218:221], v[4:7]
	v_mfma_f32_16x16x32_bf16 v[0:3], v[182:185], v[218:221], v[0:3]
	s_setprio 0
	s_barrier
	s_add_i32 s86, 0, 0x18000
	v_add_u32_e32 v157, s86, v151
	s_add_i32 s87, 0, 0x1c000
	ds_read_b128 v[146:149], v157
	ds_read_b128 v[158:161], v157 offset:1024
	ds_read_b128 v[162:165], v157 offset:2048
	ds_read_b128 v[166:169], v157 offset:3072
	v_add_u32_e32 v157, s87, v151
	ds_read_b128 v[170:173], v157
	ds_read_b128 v[174:177], v157 offset:1024
	ds_read_b128 v[178:181], v157 offset:2048
	ds_read_b128 v[182:185], v157 offset:3072
	s_add_u32 s64, s64, 0x80000
	s_addc_u32 s65, s65, 0
	s_mov_b32 m0, s73
	v_lshl_add_u64 v[230:231], s[64:65], 0, v[128:129]
	ds_read_b128 v[186:189], v156 offset:32768
	ds_read_b128 v[190:193], v156 offset:33792
	ds_read_b128 v[194:197], v156 offset:34816
	ds_read_b128 v[198:201], v156 offset:35840
	ds_read_b128 v[202:205], v156 offset:36864
	ds_read_b128 v[206:209], v156 offset:37888
	ds_read_b128 v[210:213], v156 offset:38912
	ds_read_b128 v[218:221], v156 offset:39936
	global_load_lds_dwordx4 v[230:231], off
	v_lshl_add_u64 v[230:231], s[64:65], 0, v[132:133]
	s_mov_b32 m0, s74
	s_nop 0
	global_load_lds_dwordx4 v[230:231], off
	s_waitcnt vmcnt(8)
	s_waitcnt lgkmcnt(0)
	s_barrier
	s_setprio 1
	s_waitcnt lgkmcnt(0)
	v_mfma_f32_16x16x32_bf16 v[124:127], v[146:149], v[186:189], v[124:127]
	v_mfma_f32_16x16x32_bf16 v[120:123], v[162:165], v[186:189], v[120:123]
	v_mfma_f32_16x16x32_bf16 v[108:111], v[146:149], v[194:197], v[108:111]
	v_mfma_f32_16x16x32_bf16 v[104:107], v[162:165], v[194:197], v[104:107]
	v_mfma_f32_16x16x32_bf16 v[92:95], v[146:149], v[202:205], v[92:95]
	v_mfma_f32_16x16x32_bf16 v[88:91], v[162:165], v[202:205], v[88:91]
	v_mfma_f32_16x16x32_bf16 v[76:79], v[146:149], v[210:213], v[76:79]
	v_mfma_f32_16x16x32_bf16 v[72:75], v[162:165], v[210:213], v[72:75]
	v_mfma_f32_16x16x32_bf16 v[124:127], v[158:161], v[190:193], v[124:127]
	v_mfma_f32_16x16x32_bf16 v[120:123], v[166:169], v[190:193], v[120:123]
	v_mfma_f32_16x16x32_bf16 v[108:111], v[158:161], v[198:201], v[108:111]
	v_mfma_f32_16x16x32_bf16 v[104:107], v[166:169], v[198:201], v[104:107]
	v_mfma_f32_16x16x32_bf16 v[92:95], v[158:161], v[206:209], v[92:95]
	v_mfma_f32_16x16x32_bf16 v[88:91], v[166:169], v[206:209], v[88:91]
	v_mfma_f32_16x16x32_bf16 v[76:79], v[158:161], v[218:221], v[76:79]
	v_mfma_f32_16x16x32_bf16 v[72:75], v[166:169], v[218:221], v[72:75]
	v_mfma_f32_16x16x32_bf16 v[116:119], v[170:173], v[186:189], v[116:119]
	v_mfma_f32_16x16x32_bf16 v[112:115], v[178:181], v[186:189], v[112:115]
	v_mfma_f32_16x16x32_bf16 v[100:103], v[170:173], v[194:197], v[100:103]
	v_mfma_f32_16x16x32_bf16 v[96:99], v[178:181], v[194:197], v[96:99]
	v_mfma_f32_16x16x32_bf16 v[84:87], v[170:173], v[202:205], v[84:87]
	v_mfma_f32_16x16x32_bf16 v[80:83], v[178:181], v[202:205], v[80:83]
	v_mfma_f32_16x16x32_bf16 v[68:71], v[170:173], v[210:213], v[68:71]
	v_mfma_f32_16x16x32_bf16 v[64:67], v[178:181], v[210:213], v[64:67]
	v_mfma_f32_16x16x32_bf16 v[116:119], v[174:177], v[190:193], v[116:119]
	v_mfma_f32_16x16x32_bf16 v[112:115], v[182:185], v[190:193], v[112:115]
	v_mfma_f32_16x16x32_bf16 v[100:103], v[174:177], v[198:201], v[100:103]
	v_mfma_f32_16x16x32_bf16 v[96:99], v[182:185], v[198:201], v[96:99]
	v_mfma_f32_16x16x32_bf16 v[84:87], v[174:177], v[206:209], v[84:87]
	v_mfma_f32_16x16x32_bf16 v[80:83], v[182:185], v[206:209], v[80:83]
	v_mfma_f32_16x16x32_bf16 v[68:71], v[174:177], v[218:221], v[68:71]
	v_mfma_f32_16x16x32_bf16 v[64:67], v[182:185], v[218:221], v[64:67]
	s_setprio 0
	s_barrier
; #define PG8_STAGE(bufoff, gbase, voff) do { _Pragma("unroll") for (int _i = 0; _i < 2; ++_i) \
;         __builtin_amdgcn_global_load_lds((const unsigned*)((const char*)(gbase) + (voff)[_i]), (PG8_LAS unsigned*)(lds + (bufoff) + ldsw + _i * 8192), 16, 0, 0); } while (0)
; #define PG8_LDA(dst, b, h) do { _Pragma("unroll") for (int m = 0; m < 4; ++m) _Pragma("unroll") for (int k = 0; k < 2; ++k) dst[m][k] = *(const PG8_LAS bf16x8*)(lds + PG8_SA(b, h) + aoff + m * 2048 + k * 1024); } while (0)
; #define PG8_MMA(ai, bj, At, Bt) do { __builtin_amdgcn_s_setprio(1); _Pragma("unroll") for (int m = 0; m < 4; ++m) _Pragma("unroll") for (int n = 0; n < 2; ++n) _Pragma("unroll") for (int k = 0; k < 2; ++k) \
;         acc[ai][bj][m][n] = __builtin_amdgcn_mfma_f32_16x16x32_bf16(Bt[n][k], At[m][k], acc[ai][bj][m][n], 0, 0, 0); __builtin_amdgcn_s_setprio(0); } while (0)
; #define PG8_WAIT_V(n) asm volatile("s_waitcnt vmcnt(" #n ")" ::: "memory")
; #define PG8_WAIT_L(n) asm volatile("s_waitcnt lgkmcnt(" #n ")" ::: "memory")
; #define PG8_BAR __builtin_amdgcn_s_barrier()
; #define PG8_SCHED __builtin_amdgcn_sched_barrier(0)
; template <class Epi, class Sched, bool ALIGN_EPI = false, bool SP2 = false>
; __device__ __forceinline__ void gemm_phase(PG8_LAS unsigned char* lds, const Gemm g, const Sched& S, const Epi& E, int tid_in) {
;     ...
;         for (int t = 0; t < nt; t += 2) {
;     ...
;             PG8_LDA(At, 1, 1); PG8_STAGE(PG8_SB(1, 0), b3, voffB); PG8_STAGE(PG8_SB(1, 1), b3 + hstep, voffB); PG8_STAGE(PG8_SA(1, 0), a3, voffA);
;             PG8_WAIT_V(8); PG8_WAIT_L(0); PG8_BAR; PG8_MMA(1, 0, At, B0); PG8_MMA(1, 1, At, B1); PG8_BAR; PG8_SCHED;
	s_add_i32 s64, s86, s71
	v_lshl_add_u64 v[222:223], v[222:223], 0, s[20:21]
	s_mov_b32 m0, s64
	ds_read_b128 v[186:189], v156 offset:49152
	ds_read_b128 v[190:193], v156 offset:50176
	ds_read_b128 v[194:197], v156 offset:51200
	ds_read_b128 v[198:201], v156 offset:52224
	ds_read_b128 v[202:205], v156 offset:53248
	ds_read_b128 v[206:209], v156 offset:54272
	ds_read_b128 v[210:213], v156 offset:55296
	ds_read_b128 v[218:221], v156 offset:56320
	global_load_lds_dwordx4 v[222:223], off
	s_add_i32 m0, s64, 0x2000
	s_add_u32 s62, s62, 0x80080
	v_lshl_add_u64 v[222:223], v[224:225], 0, s[20:21]
	s_addc_u32 s63, s63, 0
	s_add_i32 s64, s87, s71
	global_load_lds_dwordx4 v[222:223], off
	v_lshl_add_u64 v[222:223], s[62:63], 0, v[130:131]
	s_mov_b32 m0, s64
	s_nop 0
	global_load_lds_dwordx4 v[222:223], off
	v_lshl_add_u64 v[222:223], s[62:63], 0, v[134:135]
	s_add_i32 m0, s64, 0x2000
	s_nop 0
	global_load_lds_dwordx4 v[222:223], off
	v_lshl_add_u64 v[222:223], v[226:227], 0, s[20:21]
	s_mov_b32 m0, s76
	s_nop 0
	global_load_lds_dwordx4 v[222:223], off
	v_lshl_add_u64 v[222:223], v[228:229], 0, s[20:21]
	s_mov_b32 m0, s77
	s_nop 0
	global_load_lds_dwordx4 v[222:223], off
	s_waitcnt vmcnt(8)
	s_waitcnt lgkmcnt(0)
	s_barrier
	s_setprio 1
	s_waitcnt lgkmcnt(0)
	v_mfma_f32_16x16x32_bf16 v[60:63], v[146:149], v[186:189], v[60:63]
	v_mfma_f32_16x16x32_bf16 v[56:59], v[162:165], v[186:189], v[56:59]
	v_mfma_f32_16x16x32_bf16 v[44:47], v[146:149], v[194:197], v[44:47]
	v_mfma_f32_16x16x32_bf16 v[40:43], v[162:165], v[194:197], v[40:43]
	v_mfma_f32_16x16x32_bf16 v[28:31], v[146:149], v[202:205], v[28:31]
	v_mfma_f32_16x16x32_bf16 v[24:27], v[162:165], v[202:205], v[24:27]
	v_mfma_f32_16x16x32_bf16 v[12:15], v[146:149], v[210:213], v[12:15]
	v_mfma_f32_16x16x32_bf16 v[8:11], v[162:165], v[210:213], v[8:11]
	v_mfma_f32_16x16x32_bf16 v[60:63], v[158:161], v[190:193], v[60:63]
	v_mfma_f32_16x16x32_bf16 v[56:59], v[166:169], v[190:193], v[56:59]
	v_mfma_f32_16x16x32_bf16 v[44:47], v[158:161], v[198:201], v[44:47]
	v_mfma_f32_16x16x32_bf16 v[40:43], v[166:169], v[198:201], v[40:43]
	v_mfma_f32_16x16x32_bf16 v[28:31], v[158:161], v[206:209], v[28:31]
	v_mfma_f32_16x16x32_bf16 v[24:27], v[166:169], v[206:209], v[24:27]
	v_mfma_f32_16x16x32_bf16 v[12:15], v[158:161], v[218:221], v[12:15]
	v_mfma_f32_16x16x32_bf16 v[8:11], v[166:169], v[218:221], v[8:11]
	v_mfma_f32_16x16x32_bf16 v[52:55], v[170:173], v[186:189], v[52:55]
	v_mfma_f32_16x16x32_bf16 v[48:51], v[178:181], v[186:189], v[48:51]
	v_mfma_f32_16x16x32_bf16 v[36:39], v[170:173], v[194:197], v[36:39]
	v_mfma_f32_16x16x32_bf16 v[32:35], v[178:181], v[194:197], v[32:35]
	v_mfma_f32_16x16x32_bf16 v[20:23], v[170:173], v[202:205], v[20:23]
	v_mfma_f32_16x16x32_bf16 v[16:19], v[178:181], v[202:205], v[16:19]
	v_mfma_f32_16x16x32_bf16 v[4:7], v[170:173], v[210:213], v[4:7]
	v_mfma_f32_16x16x32_bf16 v[0:3], v[178:181], v[210:213], v[0:3]
	v_mfma_f32_16x16x32_bf16 v[52:55], v[174:177], v[190:193], v[52:55]
	v_mfma_f32_16x16x32_bf16 v[48:51], v[182:185], v[190:193], v[48:51]
	v_mfma_f32_16x16x32_bf16 v[36:39], v[174:177], v[198:201], v[36:39]
	v_mfma_f32_16x16x32_bf16 v[32:35], v[182:185], v[198:201], v[32:35]
	v_mfma_f32_16x16x32_bf16 v[20:23], v[174:177], v[206:209], v[20:23]
	v_mfma_f32_16x16x32_bf16 v[16:19], v[182:185], v[206:209], v[16:19]
	v_mfma_f32_16x16x32_bf16 v[4:7], v[174:177], v[218:221], v[4:7]
	v_mfma_f32_16x16x32_bf16 v[0:3], v[182:185], v[218:221], v[0:3]
	s_add_i32 s85, s85, 2
	s_add_u32 s60, s60, 0x100
	s_addc_u32 s61, s61, 0
	s_add_u32 s83, s83, 0x100
	s_addc_u32 s84, s84, 0
	s_cmp_gt_u32 s85, 29
	s_setprio 0
	s_barrier
	s_cbranch_scc0 .LBB0_302
	s_and_b64 vcc, exec, s[22:23]
	s_cbranch_vccz .LBB0_305
	s_barrier

; #define PG8_STAGE(bufoff, gbase, voff) do { _Pragma("unroll") for (int _i = 0; _i < 2; ++_i) \
;         __builtin_amdgcn_global_load_lds((const unsigned*)((const char*)(gbase) + (voff)[_i]), (PG8_LAS unsigned*)(lds + (bufoff) + ldsw + _i * 8192), 16, 0, 0); } while (0)
; #define PG8_LDA(dst, b, h) do { _Pragma("unroll") for (int m = 0; m < 4; ++m) _Pragma("unroll") for (int k = 0; k < 2; ++k) dst[m][k] = *(const PG8_LAS bf16x8*)(lds + PG8_SA(b, h) + aoff + m * 2048 + k * 1024); } while (0)
; #define PG8_LDB(dst, b, h) do { _Pragma("unroll") for (int n = 0; n < 2; ++n) _Pragma("unroll") for (int k = 0; k < 2; ++k) dst[n][k] = *(const PG8_LAS bf16x8*)(lds + PG8_SB(b, h) + boff + n * 2048 + k * 1024); } while (0)
; #define PG8_MMA(ai, bj, At, Bt) do { __builtin_amdgcn_s_setprio(1); _Pragma("unroll") for (int m = 0; m < 4; ++m) _Pragma("unroll") for (int n = 0; n < 2; ++n) _Pragma("unroll") for (int k = 0; k < 2; ++k) \
;         acc[ai][bj][m][n] = __builtin_amdgcn_mfma_f32_16x16x32_bf16(Bt[n][k], At[m][k], acc[ai][bj][m][n], 0, 0, 0); __builtin_amdgcn_s_setprio(0); } while (0)
; #define PG8_WAIT_V(n) asm volatile("s_waitcnt vmcnt(" #n ")" ::: "memory")
; #define PG8_WAIT_L(n) asm volatile("s_waitcnt lgkmcnt(" #n ")" ::: "memory")
; #define PG8_BAR __builtin_amdgcn_s_barrier()
; #define PG8_SCHED __builtin_amdgcn_sched_barrier(0)
; template <class Epi, class Sched, bool ALIGN_EPI = false, bool SP2 = false>
; __device__ __forceinline__ void gemm_phase(PG8_LAS unsigned char* lds, const Gemm g, const Sched& S, const Epi& E, int tid_in) {
;     ...
;             PG8_LDB(B0, 0, 0); PG8_LDB(B1, 0, 1); PG8_SCHED; PG8_LDA(At, 0, 0); PG8_STAGE(PG8_SA(1, 1), a1 + hstep, voffA);
;             PG8_WAIT_V(8); PG8_WAIT_L(0); PG8_BAR; PG8_MMA(0, 0, At, B0); PG8_MMA(0, 1, At, B1); PG8_BAR; PG8_SCHED;
;             PG8_LDA(At, 0, 1); PG8_STAGE(PG8_SB(0, 0), b2, voffB); PG8_STAGE(PG8_SB(0, 1), b2 + hstep, voffB); PG8_STAGE(PG8_SA(0, 0), a2, voffA);
.LBB0_352:
	ds_read_b128 v[148:151], v161
	ds_read_b128 v[152:155], v161 offset:1024
	ds_read_b128 v[166:169], v161 offset:2048
	ds_read_b128 v[170:173], v161 offset:3072
	ds_read_b128 v[174:177], v162
	ds_read_b128 v[178:181], v162 offset:1024
	ds_read_b128 v[182:185], v162 offset:2048
	ds_read_b128 v[186:189], v162 offset:3072
	s_add_u32 s64, s62, 0xfffc0080
	s_addc_u32 s65, s63, -1
	s_cmp_eq_u32 s92, 12
	s_cselect_b32 s67, s9, s65
	s_cselect_b32 s66, s11, s64
	s_cselect_b32 s65, s55, s91
	s_cselect_b32 s64, s57, s90
	v_lshl_add_u64 v[156:157], s[62:63], 0, v[140:141]
	s_add_i32 m0, s74, 0xc000
	ds_read_b128 v[190:193], v163
	ds_read_b128 v[194:197], v163 offset:1024
	ds_read_b128 v[198:201], v163 offset:2048
	ds_read_b128 v[202:205], v163 offset:3072
	ds_read_b128 v[206:209], v163 offset:4096
	ds_read_b128 v[210:213], v163 offset:5120
	ds_read_b128 v[216:219], v163 offset:6144
	ds_read_b128 v[220:223], v163 offset:7168
	global_load_lds_dwordx4 v[156:157], off
	v_lshl_add_u64 v[156:157], s[62:63], 0, v[142:143]
	s_add_i32 m0, s74, 0xe000
	s_nop 0
	global_load_lds_dwordx4 v[156:157], off
	s_waitcnt vmcnt(8)
	s_waitcnt lgkmcnt(0)
	s_barrier
	s_setprio 1
	s_waitcnt lgkmcnt(0)
	v_mfma_f32_16x16x32_bf16 v[124:127], v[148:151], v[190:193], v[124:127]
	v_mfma_f32_16x16x32_bf16 v[120:123], v[166:169], v[190:193], v[120:123]
	v_mfma_f32_16x16x32_bf16 v[108:111], v[148:151], v[198:201], v[108:111]
	v_mfma_f32_16x16x32_bf16 v[104:107], v[166:169], v[198:201], v[104:107]
	v_mfma_f32_16x16x32_bf16 v[92:95], v[148:151], v[206:209], v[92:95]
	v_mfma_f32_16x16x32_bf16 v[88:91], v[166:169], v[206:209], v[88:91]
	v_mfma_f32_16x16x32_bf16 v[76:79], v[148:151], v[216:219], v[76:79]
	v_mfma_f32_16x16x32_bf16 v[72:75], v[166:169], v[216:219], v[72:75]
	v_mfma_f32_16x16x32_bf16 v[124:127], v[152:155], v[194:197], v[124:127]
	v_mfma_f32_16x16x32_bf16 v[120:123], v[170:173], v[194:197], v[120:123]
	v_mfma_f32_16x16x32_bf16 v[108:111], v[152:155], v[202:205], v[108:111]
	v_mfma_f32_16x16x32_bf16 v[104:107], v[170:173], v[202:205], v[104:107]
	v_mfma_f32_16x16x32_bf16 v[92:95], v[152:155], v[210:213], v[92:95]
	v_mfma_f32_16x16x32_bf16 v[88:91], v[170:173], v[210:213], v[88:91]
	v_mfma_f32_16x16x32_bf16 v[76:79], v[152:155], v[220:223], v[76:79]
	v_mfma_f32_16x16x32_bf16 v[72:75], v[170:173], v[220:223], v[72:75]
	v_mfma_f32_16x16x32_bf16 v[116:119], v[174:177], v[190:193], v[116:119]
	v_mfma_f32_16x16x32_bf16 v[112:115], v[182:185], v[190:193], v[112:115]
	v_mfma_f32_16x16x32_bf16 v[100:103], v[174:177], v[198:201], v[100:103]
	v_mfma_f32_16x16x32_bf16 v[96:99], v[182:185], v[198:201], v[96:99]
	v_mfma_f32_16x16x32_bf16 v[84:87], v[174:177], v[206:209], v[84:87]
	v_mfma_f32_16x16x32_bf16 v[80:83], v[182:185], v[206:209], v[80:83]
	v_mfma_f32_16x16x32_bf16 v[68:71], v[174:177], v[216:219], v[68:71]
	v_mfma_f32_16x16x32_bf16 v[64:67], v[182:185], v[216:219], v[64:67]
	v_mfma_f32_16x16x32_bf16 v[116:119], v[178:181], v[194:197], v[116:119]
	v_mfma_f32_16x16x32_bf16 v[112:115], v[186:189], v[194:197], v[112:115]
	v_mfma_f32_16x16x32_bf16 v[100:103], v[178:181], v[202:205], v[100:103]
	v_mfma_f32_16x16x32_bf16 v[96:99], v[186:189], v[202:205], v[96:99]
	v_mfma_f32_16x16x32_bf16 v[84:87], v[178:181], v[210:213], v[84:87]
	v_mfma_f32_16x16x32_bf16 v[80:83], v[186:189], v[210:213], v[80:83]
	v_mfma_f32_16x16x32_bf16 v[68:71], v[178:181], v[220:223], v[68:71]
	v_mfma_f32_16x16x32_bf16 v[64:67], v[186:189], v[220:223], v[64:67]
	s_setprio 0
	s_barrier
	s_add_i32 s93, s83, s73
	v_lshl_add_u64 v[156:157], s[64:65], 0, v[130:131]
	s_mov_b32 m0, s93
	ds_read_b128 v[190:193], v163 offset:16384
	ds_read_b128 v[194:197], v163 offset:17408
	ds_read_b128 v[198:201], v163 offset:18432
	ds_read_b128 v[202:205], v163 offset:19456
	ds_read_b128 v[206:209], v163 offset:20480
	ds_read_b128 v[210:213], v163 offset:21504
	ds_read_b128 v[216:219], v163 offset:22528
	ds_read_b128 v[220:223], v163 offset:23552
	global_load_lds_dwordx4 v[156:157], off
	s_add_i32 m0, s93, 0x2000
	s_add_u32 s94, s64, 0x40000
	v_lshl_add_u64 v[224:225], s[64:65], 0, v[134:135]
	s_addc_u32 s95, s65, 0
	s_add_i32 s93, s84, s73
	global_load_lds_dwordx4 v[224:225], off
	v_lshl_add_u64 v[226:227], s[94:95], 0, v[130:131]
	s_mov_b32 m0, s93
	v_lshl_add_u64 v[228:229], s[66:67], 0, v[132:133]
	global_load_lds_dwordx4 v[226:227], off
	v_lshl_add_u64 v[226:227], s[94:95], 0, v[134:135]
	s_add_i32 m0, s93, 0x2000
	s_nop 0
	global_load_lds_dwordx4 v[226:227], off
	v_lshl_add_u64 v[226:227], s[66:67], 0, v[128:129]
	s_mov_b32 m0, s74
	s_nop 0
	global_load_lds_dwordx4 v[226:227], off
	s_mov_b32 m0, s75
	s_nop 0
	global_load_lds_dwordx4 v[228:229], off
	s_waitcnt vmcnt(8)
	s_waitcnt lgkmcnt(0)
	s_barrier
; #define PG8_STAGE(bufoff, gbase, voff) do { _Pragma("unroll") for (int _i = 0; _i < 2; ++_i) \
;         __builtin_amdgcn_global_load_lds((const unsigned*)((const char*)(gbase) + (voff)[_i]), (PG8_LAS unsigned*)(lds + (bufoff) + ldsw + _i * 8192), 16, 0, 0); } while (0)
; #define PG8_LDA(dst, b, h) do { _Pragma("unroll") for (int m = 0; m < 4; ++m) _Pragma("unroll") for (int k = 0; k < 2; ++k) dst[m][k] = *(const PG8_LAS bf16x8*)(lds + PG8_SA(b, h) + aoff + m * 2048 + k * 1024); } while (0)
; #define PG8_LDB(dst, b, h) do { _Pragma("unroll") for (int n = 0; n < 2; ++n) _Pragma("unroll") for (int k = 0; k < 2; ++k) dst[n][k] = *(const PG8_LAS bf16x8*)(lds + PG8_SB(b, h) + boff + n * 2048 + k * 1024); } while (0)
; #define PG8_MMA(ai, bj, At, Bt) do { __builtin_amdgcn_s_setprio(1); _Pragma("unroll") for (int m = 0; m < 4; ++m) _Pragma("unroll") for (int n = 0; n < 2; ++n) _Pragma("unroll") for (int k = 0; k < 2; ++k) \
;         acc[ai][bj][m][n] = __builtin_amdgcn_mfma_f32_16x16x32_bf16(Bt[n][k], At[m][k], acc[ai][bj][m][n], 0, 0, 0); __builtin_amdgcn_s_setprio(0); } while (0)
; #define PG8_WAIT_V(n) asm volatile("s_waitcnt vmcnt(" #n ")" ::: "memory")
; #define PG8_WAIT_L(n) asm volatile("s_waitcnt lgkmcnt(" #n ")" ::: "memory")
; #define PG8_BAR __builtin_amdgcn_s_barrier()
; #define PG8_SCHED __builtin_amdgcn_sched_barrier(0)
; template <class Epi, class Sched, bool ALIGN_EPI = false, bool SP2 = false>
; __device__ __forceinline__ void gemm_phase(PG8_LAS unsigned char* lds, const Gemm g, const Sched& S, const Epi& E, int tid_in) {
;     ...
;             PG8_WAIT_V(8); PG8_WAIT_L(0); PG8_BAR; PG8_MMA(1, 0, At, B0); PG8_MMA(1, 1, At, B1); PG8_BAR; PG8_SCHED;
;             PG8_LDB(B0, 1, 0); PG8_LDB(B1, 1, 1); PG8_SCHED; PG8_LDA(At, 1, 0); PG8_STAGE(PG8_SA(0, 1), a2 + hstep, voffA);
;             PG8_WAIT_V(8); PG8_WAIT_L(0); PG8_BAR; PG8_MMA(0, 0, At, B0); PG8_MMA(0, 1, At, B1); PG8_BAR; PG8_SCHED;
	s_setprio 1
	s_waitcnt lgkmcnt(0)
	v_mfma_f32_16x16x32_bf16 v[60:63], v[148:151], v[190:193], v[60:63]
	v_mfma_f32_16x16x32_bf16 v[56:59], v[166:169], v[190:193], v[56:59]
	v_mfma_f32_16x16x32_bf16 v[44:47], v[148:151], v[198:201], v[44:47]
	v_mfma_f32_16x16x32_bf16 v[40:43], v[166:169], v[198:201], v[40:43]
	v_mfma_f32_16x16x32_bf16 v[28:31], v[148:151], v[206:209], v[28:31]
	v_mfma_f32_16x16x32_bf16 v[24:27], v[166:169], v[206:209], v[24:27]
	v_mfma_f32_16x16x32_bf16 v[12:15], v[148:151], v[216:219], v[12:15]
	v_mfma_f32_16x16x32_bf16 v[8:11], v[166:169], v[216:219], v[8:11]
	v_mfma_f32_16x16x32_bf16 v[60:63], v[152:155], v[194:197], v[60:63]
	v_mfma_f32_16x16x32_bf16 v[56:59], v[170:173], v[194:197], v[56:59]
	v_mfma_f32_16x16x32_bf16 v[44:47], v[152:155], v[202:205], v[44:47]
	v_mfma_f32_16x16x32_bf16 v[40:43], v[170:173], v[202:205], v[40:43]
	v_mfma_f32_16x16x32_bf16 v[28:31], v[152:155], v[210:213], v[28:31]
	v_mfma_f32_16x16x32_bf16 v[24:27], v[170:173], v[210:213], v[24:27]
	v_mfma_f32_16x16x32_bf16 v[12:15], v[152:155], v[220:223], v[12:15]
	v_mfma_f32_16x16x32_bf16 v[8:11], v[170:173], v[220:223], v[8:11]
	v_mfma_f32_16x16x32_bf16 v[52:55], v[174:177], v[190:193], v[52:55]
	v_mfma_f32_16x16x32_bf16 v[48:51], v[182:185], v[190:193], v[48:51]
	v_mfma_f32_16x16x32_bf16 v[36:39], v[174:177], v[198:201], v[36:39]
	v_mfma_f32_16x16x32_bf16 v[32:35], v[182:185], v[198:201], v[32:35]
	v_mfma_f32_16x16x32_bf16 v[20:23], v[174:177], v[206:209], v[20:23]
	v_mfma_f32_16x16x32_bf16 v[16:19], v[182:185], v[206:209], v[16:19]
	v_mfma_f32_16x16x32_bf16 v[4:7], v[174:177], v[216:219], v[4:7]
	v_mfma_f32_16x16x32_bf16 v[0:3], v[182:185], v[216:219], v[0:3]
	v_mfma_f32_16x16x32_bf16 v[52:55], v[178:181], v[194:197], v[52:55]
	v_mfma_f32_16x16x32_bf16 v[48:51], v[186:189], v[194:197], v[48:51]
	v_mfma_f32_16x16x32_bf16 v[36:39], v[178:181], v[202:205], v[36:39]
	v_mfma_f32_16x16x32_bf16 v[32:35], v[186:189], v[202:205], v[32:35]
	v_mfma_f32_16x16x32_bf16 v[20:23], v[178:181], v[210:213], v[20:23]
	v_mfma_f32_16x16x32_bf16 v[16:19], v[186:189], v[210:213], v[16:19]
	v_mfma_f32_16x16x32_bf16 v[4:7], v[178:181], v[220:223], v[4:7]
	v_mfma_f32_16x16x32_bf16 v[0:3], v[186:189], v[220:223], v[0:3]
	s_setprio 0
	s_barrier
	s_add_i32 s93, 0, 0x18000
	v_add_u32_e32 v138, s93, v159
	s_add_i32 s94, 0, 0x1c000
	ds_read_b128 v[148:151], v138
	ds_read_b128 v[152:155], v138 offset:1024
	ds_read_b128 v[166:169], v138 offset:2048
	ds_read_b128 v[170:173], v138 offset:3072
	v_add_u32_e32 v138, s94, v159
	ds_read_b128 v[174:177], v138
	ds_read_b128 v[178:181], v138 offset:1024
	ds_read_b128 v[182:185], v138 offset:2048
	ds_read_b128 v[186:189], v138 offset:3072
	s_add_u32 s66, s66, 0x40000
	s_addc_u32 s67, s67, 0
	s_mov_b32 m0, s76
	v_lshl_add_u64 v[230:231], s[66:67], 0, v[128:129]
	ds_read_b128 v[190:193], v163 offset:32768
	ds_read_b128 v[194:197], v163 offset:33792
	ds_read_b128 v[198:201], v163 offset:34816
	ds_read_b128 v[202:205], v163 offset:35840
	ds_read_b128 v[206:209], v163 offset:36864
	ds_read_b128 v[210:213], v163 offset:37888
	ds_read_b128 v[216:219], v163 offset:38912
	ds_read_b128 v[220:223], v163 offset:39936
	global_load_lds_dwordx4 v[230:231], off
	v_lshl_add_u64 v[230:231], s[66:67], 0, v[132:133]
	s_mov_b32 m0, s77
	s_nop 0
	global_load_lds_dwordx4 v[230:231], off
	s_waitcnt vmcnt(8)
	s_waitcnt lgkmcnt(0)
	s_barrier
	s_setprio 1
	s_waitcnt lgkmcnt(0)
	v_mfma_f32_16x16x32_bf16 v[124:127], v[148:151], v[190:193], v[124:127]
	v_mfma_f32_16x16x32_bf16 v[120:123], v[166:169], v[190:193], v[120:123]
	v_mfma_f32_16x16x32_bf16 v[108:111], v[148:151], v[198:201], v[108:111]
	v_mfma_f32_16x16x32_bf16 v[104:107], v[166:169], v[198:201], v[104:107]
	v_mfma_f32_16x16x32_bf16 v[92:95], v[148:151], v[206:209], v[92:95]
	v_mfma_f32_16x16x32_bf16 v[88:91], v[166:169], v[206:209], v[88:91]
	v_mfma_f32_16x16x32_bf16 v[76:79], v[148:151], v[216:219], v[76:79]
	v_mfma_f32_16x16x32_bf16 v[72:75], v[166:169], v[216:219], v[72:75]
	v_mfma_f32_16x16x32_bf16 v[124:127], v[152:155], v[194:197], v[124:127]
	v_mfma_f32_16x16x32_bf16 v[120:123], v[170:173], v[194:197], v[120:123]
	v_mfma_f32_16x16x32_bf16 v[108:111], v[152:155], v[202:205], v[108:111]
	v_mfma_f32_16x16x32_bf16 v[104:107], v[170:173], v[202:205], v[104:107]
	v_mfma_f32_16x16x32_bf16 v[92:95], v[152:155], v[210:213], v[92:95]
	v_mfma_f32_16x16x32_bf16 v[88:91], v[170:173], v[210:213], v[88:91]
	v_mfma_f32_16x16x32_bf16 v[76:79], v[152:155], v[220:223], v[76:79]
	v_mfma_f32_16x16x32_bf16 v[72:75], v[170:173], v[220:223], v[72:75]
	v_mfma_f32_16x16x32_bf16 v[116:119], v[174:177], v[190:193], v[116:119]
	v_mfma_f32_16x16x32_bf16 v[112:115], v[182:185], v[190:193], v[112:115]
	v_mfma_f32_16x16x32_bf16 v[100:103], v[174:177], v[198:201], v[100:103]
	v_mfma_f32_16x16x32_bf16 v[96:99], v[182:185], v[198:201], v[96:99]
	v_mfma_f32_16x16x32_bf16 v[84:87], v[174:177], v[206:209], v[84:87]
	v_mfma_f32_16x16x32_bf16 v[80:83], v[182:185], v[206:209], v[80:83]
	v_mfma_f32_16x16x32_bf16 v[68:71], v[174:177], v[216:219], v[68:71]
	v_mfma_f32_16x16x32_bf16 v[64:67], v[182:185], v[216:219], v[64:67]
	v_mfma_f32_16x16x32_bf16 v[116:119], v[178:181], v[194:197], v[116:119]
	v_mfma_f32_16x16x32_bf16 v[112:115], v[186:189], v[194:197], v[112:115]
	v_mfma_f32_16x16x32_bf16 v[100:103], v[178:181], v[202:205], v[100:103]
	v_mfma_f32_16x16x32_bf16 v[96:99], v[186:189], v[202:205], v[96:99]
	v_mfma_f32_16x16x32_bf16 v[84:87], v[178:181], v[210:213], v[84:87]
	v_mfma_f32_16x16x32_bf16 v[80:83], v[186:189], v[210:213], v[80:83]
	v_mfma_f32_16x16x32_bf16 v[68:71], v[178:181], v[220:223], v[68:71]
	v_mfma_f32_16x16x32_bf16 v[64:67], v[186:189], v[220:223], v[64:67]
	s_setprio 0
	s_barrier
; #define PG8_STAGE(bufoff, gbase, voff) do { _Pragma("unroll") for (int _i = 0; _i < 2; ++_i) \
;         __builtin_amdgcn_global_load_lds((const unsigned*)((const char*)(gbase) + (voff)[_i]), (PG8_LAS unsigned*)(lds + (bufoff) + ldsw + _i * 8192), 16, 0, 0); } while (0)
; #define PG8_LDA(dst, b, h) do { _Pragma("unroll") for (int m = 0; m < 4; ++m) _Pragma("unroll") for (int k = 0; k < 2; ++k) dst[m][k] = *(const PG8_LAS bf16x8*)(lds + PG8_SA(b, h) + aoff + m * 2048 + k * 1024); } while (0)
; #define PG8_MMA(ai, bj, At, Bt) do { __builtin_amdgcn_s_setprio(1); _Pragma("unroll") for (int m = 0; m < 4; ++m) _Pragma("unroll") for (int n = 0; n < 2; ++n) _Pragma("unroll") for (int k = 0; k < 2; ++k) \
;         acc[ai][bj][m][n] = __builtin_amdgcn_mfma_f32_16x16x32_bf16(Bt[n][k], At[m][k], acc[ai][bj][m][n], 0, 0, 0); __builtin_amdgcn_s_setprio(0); } while (0)
; #define PG8_WAIT_V(n) asm volatile("s_waitcnt vmcnt(" #n ")" ::: "memory")
; #define PG8_WAIT_L(n) asm volatile("s_waitcnt lgkmcnt(" #n ")" ::: "memory")
; #define PG8_BAR __builtin_amdgcn_s_barrier()
; #define PG8_SCHED __builtin_amdgcn_sched_barrier(0)
; template <class Epi, class Sched, bool ALIGN_EPI = false, bool SP2 = false>
; __device__ __forceinline__ void gemm_phase(PG8_LAS unsigned char* lds, const Gemm g, const Sched& S, const Epi& E, int tid_in) {
;     ...
;         for (int t = 0; t < nt; t += 2) {
;             const bool last = (t == nt - 2);
;     ...
;             PG8_LDA(At, 1, 1); PG8_STAGE(PG8_SB(1, 0), b3, voffB); PG8_STAGE(PG8_SB(1, 1), b3 + hstep, voffB); PG8_STAGE(PG8_SA(1, 0), a3, voffA);
;             PG8_WAIT_V(8); PG8_WAIT_L(0); PG8_BAR; PG8_MMA(1, 0, At, B0); PG8_MMA(1, 1, At, B1); PG8_BAR; PG8_SCHED;
	s_add_i32 s66, s93, s73
	v_lshl_add_u64 v[156:157], v[156:157], 0, s[18:19]
	s_mov_b32 m0, s66
	ds_read_b128 v[190:193], v163 offset:49152
	ds_read_b128 v[194:197], v163 offset:50176
	ds_read_b128 v[198:201], v163 offset:51200
	ds_read_b128 v[202:205], v163 offset:52224
	ds_read_b128 v[206:209], v163 offset:53248
	ds_read_b128 v[210:213], v163 offset:54272
	ds_read_b128 v[216:219], v163 offset:55296
	ds_read_b128 v[220:223], v163 offset:56320
	global_load_lds_dwordx4 v[156:157], off
	s_add_i32 m0, s66, 0x2000
	s_add_u32 s64, s64, 0x40080
	v_lshl_add_u64 v[156:157], v[224:225], 0, s[18:19]
	s_addc_u32 s65, s65, 0
	s_add_i32 s66, s94, s73
	global_load_lds_dwordx4 v[156:157], off
	v_lshl_add_u64 v[156:157], s[64:65], 0, v[130:131]
	s_mov_b32 m0, s66
	s_nop 0
	global_load_lds_dwordx4 v[156:157], off
	v_lshl_add_u64 v[156:157], s[64:65], 0, v[134:135]
	s_add_i32 m0, s66, 0x2000
	s_nop 0
	global_load_lds_dwordx4 v[156:157], off
	v_lshl_add_u64 v[156:157], v[226:227], 0, s[18:19]
	s_mov_b32 m0, s79
	s_nop 0
	global_load_lds_dwordx4 v[156:157], off
	v_lshl_add_u64 v[156:157], v[228:229], 0, s[18:19]
	s_mov_b32 m0, s80
	s_nop 0
	global_load_lds_dwordx4 v[156:157], off
	s_waitcnt vmcnt(8)
	s_waitcnt lgkmcnt(0)
	s_barrier
	s_setprio 1
	s_waitcnt lgkmcnt(0)
	v_mfma_f32_16x16x32_bf16 v[60:63], v[148:151], v[190:193], v[60:63]
	v_mfma_f32_16x16x32_bf16 v[56:59], v[166:169], v[190:193], v[56:59]
	v_mfma_f32_16x16x32_bf16 v[44:47], v[148:151], v[198:201], v[44:47]
	v_mfma_f32_16x16x32_bf16 v[40:43], v[166:169], v[198:201], v[40:43]
	v_mfma_f32_16x16x32_bf16 v[28:31], v[148:151], v[206:209], v[28:31]
	v_mfma_f32_16x16x32_bf16 v[24:27], v[166:169], v[206:209], v[24:27]
	v_mfma_f32_16x16x32_bf16 v[12:15], v[148:151], v[216:219], v[12:15]
	v_mfma_f32_16x16x32_bf16 v[8:11], v[166:169], v[216:219], v[8:11]
	v_mfma_f32_16x16x32_bf16 v[60:63], v[152:155], v[194:197], v[60:63]
	v_mfma_f32_16x16x32_bf16 v[56:59], v[170:173], v[194:197], v[56:59]
	v_mfma_f32_16x16x32_bf16 v[44:47], v[152:155], v[202:205], v[44:47]
	v_mfma_f32_16x16x32_bf16 v[40:43], v[170:173], v[202:205], v[40:43]
	v_mfma_f32_16x16x32_bf16 v[28:31], v[152:155], v[210:213], v[28:31]
	v_mfma_f32_16x16x32_bf16 v[24:27], v[170:173], v[210:213], v[24:27]
	v_mfma_f32_16x16x32_bf16 v[12:15], v[152:155], v[220:223], v[12:15]
	v_mfma_f32_16x16x32_bf16 v[8:11], v[170:173], v[220:223], v[8:11]
	v_mfma_f32_16x16x32_bf16 v[52:55], v[174:177], v[190:193], v[52:55]
	v_mfma_f32_16x16x32_bf16 v[48:51], v[182:185], v[190:193], v[48:51]
	v_mfma_f32_16x16x32_bf16 v[36:39], v[174:177], v[198:201], v[36:39]
	v_mfma_f32_16x16x32_bf16 v[32:35], v[182:185], v[198:201], v[32:35]
	v_mfma_f32_16x16x32_bf16 v[20:23], v[174:177], v[206:209], v[20:23]
	v_mfma_f32_16x16x32_bf16 v[16:19], v[182:185], v[206:209], v[16:19]
	v_mfma_f32_16x16x32_bf16 v[4:7], v[174:177], v[216:219], v[4:7]
	v_mfma_f32_16x16x32_bf16 v[0:3], v[182:185], v[216:219], v[0:3]
	v_mfma_f32_16x16x32_bf16 v[52:55], v[178:181], v[194:197], v[52:55]
	v_mfma_f32_16x16x32_bf16 v[48:51], v[186:189], v[194:197], v[48:51]
	v_mfma_f32_16x16x32_bf16 v[36:39], v[178:181], v[202:205], v[36:39]
	v_mfma_f32_16x16x32_bf16 v[32:35], v[186:189], v[202:205], v[32:35]
	v_mfma_f32_16x16x32_bf16 v[20:23], v[178:181], v[210:213], v[20:23]
	v_mfma_f32_16x16x32_bf16 v[16:19], v[186:189], v[210:213], v[16:19]
	v_mfma_f32_16x16x32_bf16 v[4:7], v[178:181], v[220:223], v[4:7]
	v_mfma_f32_16x16x32_bf16 v[0:3], v[186:189], v[220:223], v[0:3]
	s_add_i32 s92, s92, 2
	s_add_u32 s62, s62, 0x100
	s_addc_u32 s63, s63, 0
	s_add_u32 s90, s90, 0x100
	s_addc_u32 s91, s91, 0
	s_cmp_gt_u32 s92, 13
	s_setprio 0
	s_barrier
	s_cbranch_scc0 .LBB0_352
	s_and_b64 vcc, exec, s[20:21]
	s_cbranch_vccz .LBB0_355
	s_barrier

; #define PG8_STAGE(bufoff, gbase, voff) do { _Pragma("unroll") for (int _i = 0; _i < 2; ++_i) \
;         __builtin_amdgcn_global_load_lds((const unsigned*)((const char*)(gbase) + (voff)[_i]), (PG8_LAS unsigned*)(lds + (bufoff) + ldsw + _i * 8192), 16, 0, 0); } while (0)
; #define PG8_LDA(dst, b, h) do { _Pragma("unroll") for (int m = 0; m < 4; ++m) _Pragma("unroll") for (int k = 0; k < 2; ++k) dst[m][k] = *(const PG8_LAS bf16x8*)(lds + PG8_SA(b, h) + aoff + m * 2048 + k * 1024); } while (0)
; #define PG8_LDB(dst, b, h) do { _Pragma("unroll") for (int n = 0; n < 2; ++n) _Pragma("unroll") for (int k = 0; k < 2; ++k) dst[n][k] = *(const PG8_LAS bf16x8*)(lds + PG8_SB(b, h) + boff + n * 2048 + k * 1024); } while (0)
; #define PG8_MMA(ai, bj, At, Bt) do { __builtin_amdgcn_s_setprio(1); _Pragma("unroll") for (int m = 0; m < 4; ++m) _Pragma("unroll") for (int n = 0; n < 2; ++n) _Pragma("unroll") for (int k = 0; k < 2; ++k) \
;         acc[ai][bj][m][n] = __builtin_amdgcn_mfma_f32_16x16x32_bf16(Bt[n][k], At[m][k], acc[ai][bj][m][n], 0, 0, 0); __builtin_amdgcn_s_setprio(0); } while (0)
; #define PG8_WAIT_V(n) asm volatile("s_waitcnt vmcnt(" #n ")" ::: "memory")
; #define PG8_WAIT_L(n) asm volatile("s_waitcnt lgkmcnt(" #n ")" ::: "memory")
; #define PG8_BAR __builtin_amdgcn_s_barrier()
; #define PG8_SCHED __builtin_amdgcn_sched_barrier(0)
; template <class Epi, class Sched, bool ALIGN_EPI = false, bool SP2 = false>
; __device__ __forceinline__ void gemm_phase(PG8_LAS unsigned char* lds, const Gemm g, const Sched& S, const Epi& E, int tid_in) {
;     ...
;             const bool last = (t == nt - 2);
;             const char* a1 = cA + (size_t)(t + 1) * kstep;
;             const char* a2 = last ? nA : cA + (size_t)(t + 2) * kstep; const char* b2 = last ? nB : cB + (size_t)(t + 2) * kstep;
;             const char* a3 = a2 + kstep; const char* b3 = b2 + kstep;
;             if (last && has_next) S.a_ready(nxt);
;             if constexpr (SP2) {
;             PG8_LDB(B0, 0, 0); PG8_LDB(B1, 0, 1); PG8_SCHED; PG8_LDA(At, 0, 0); PG8_STAGE(PG8_SA(1, 1), a1 + hstep, voffA);
;             PG8_WAIT_V(8); PG8_WAIT_L(0); PG8_BAR; PG8_MMA(0, 0, At, B0); PG8_MMA(0, 1, At, B1); PG8_BAR; PG8_SCHED;
;             PG8_LDA(At, 0, 1); PG8_STAGE(PG8_SB(0, 0), b2, voffB); PG8_STAGE(PG8_SB(0, 1), b2 + hstep, voffB); PG8_STAGE(PG8_SA(0, 0), a2, voffA);
.LBB0_452:
	ds_read_b128 v[104:107], v167
	ds_read_b128 v[108:111], v167 offset:1024
	ds_read_b128 v[154:157], v167 offset:2048
	ds_read_b128 v[158:161], v167 offset:3072
	ds_read_b128 v[170:173], v168
	ds_read_b128 v[174:177], v168 offset:1024
	ds_read_b128 v[178:181], v168 offset:2048
	ds_read_b128 v[182:185], v168 offset:3072
	s_add_u32 s50, s46, 0xfff80080
	s_addc_u32 s51, s47, -1
	s_cmp_eq_u32 s73, 28
	s_cselect_b32 s53, s23, s51
	s_cselect_b32 s52, s67, s50
	s_cselect_b32 s51, s21, s72
	s_cselect_b32 s50, s68, s71
	v_lshl_add_u64 v[162:163], s[46:47], 0, v[146:147]
	s_add_i32 m0, s45, 0xc000
	ds_read_b128 v[186:189], v169
	ds_read_b128 v[190:193], v169 offset:1024
	ds_read_b128 v[194:197], v169 offset:2048
	ds_read_b128 v[198:201], v169 offset:3072
	ds_read_b128 v[202:205], v169 offset:4096
	ds_read_b128 v[206:209], v169 offset:5120
	ds_read_b128 v[210:213], v169 offset:6144
	ds_read_b128 v[216:219], v169 offset:7168
	global_load_lds_dwordx4 v[162:163], off
	v_lshl_add_u64 v[162:163], s[46:47], 0, v[148:149]
	s_add_i32 m0, s45, 0xe000
	s_nop 0
	global_load_lds_dwordx4 v[162:163], off
	s_waitcnt vmcnt(8)
	s_waitcnt lgkmcnt(0)
	s_barrier
	s_setprio 1
	s_waitcnt lgkmcnt(0)
	v_mfma_f32_16x16x32_bf16 v[132:135], v[104:107], v[186:189], v[132:135]
	v_mfma_f32_16x16x32_bf16 v[128:131], v[154:157], v[186:189], v[128:131]
	v_mfma_f32_16x16x32_bf16 v[124:127], v[104:107], v[194:197], v[124:127]
	v_mfma_f32_16x16x32_bf16 v[120:123], v[154:157], v[194:197], v[120:123]
	v_mfma_f32_16x16x32_bf16 v[116:119], v[104:107], v[202:205], v[116:119]
	v_mfma_f32_16x16x32_bf16 v[112:115], v[154:157], v[202:205], v[112:115]
	v_mfma_f32_16x16x32_bf16 v[100:103], v[104:107], v[210:213], v[100:103]
	v_mfma_f32_16x16x32_bf16 v[96:99], v[154:157], v[210:213], v[96:99]
	v_mfma_f32_16x16x32_bf16 v[132:135], v[108:111], v[190:193], v[132:135]
	v_mfma_f32_16x16x32_bf16 v[128:131], v[158:161], v[190:193], v[128:131]
	v_mfma_f32_16x16x32_bf16 v[124:127], v[108:111], v[198:201], v[124:127]
	v_mfma_f32_16x16x32_bf16 v[120:123], v[158:161], v[198:201], v[120:123]
	v_mfma_f32_16x16x32_bf16 v[116:119], v[108:111], v[206:209], v[116:119]
	v_mfma_f32_16x16x32_bf16 v[112:115], v[158:161], v[206:209], v[112:115]
	v_mfma_f32_16x16x32_bf16 v[100:103], v[108:111], v[216:219], v[100:103]
	v_mfma_f32_16x16x32_bf16 v[96:99], v[158:161], v[216:219], v[96:99]
	v_mfma_f32_16x16x32_bf16 v[60:63], v[170:173], v[186:189], v[60:63]
	v_mfma_f32_16x16x32_bf16 v[56:59], v[178:181], v[186:189], v[56:59]
	v_mfma_f32_16x16x32_bf16 v[52:55], v[170:173], v[194:197], v[52:55]
	v_mfma_f32_16x16x32_bf16 v[48:51], v[178:181], v[194:197], v[48:51]
	v_mfma_f32_16x16x32_bf16 v[44:47], v[170:173], v[202:205], v[44:47]
	v_mfma_f32_16x16x32_bf16 v[40:43], v[178:181], v[202:205], v[40:43]
	v_mfma_f32_16x16x32_bf16 v[36:39], v[170:173], v[210:213], v[36:39]
	v_mfma_f32_16x16x32_bf16 v[32:35], v[178:181], v[210:213], v[32:35]
	v_mfma_f32_16x16x32_bf16 v[60:63], v[174:177], v[190:193], v[60:63]
	v_mfma_f32_16x16x32_bf16 v[56:59], v[182:185], v[190:193], v[56:59]
	v_mfma_f32_16x16x32_bf16 v[52:55], v[174:177], v[198:201], v[52:55]
	v_mfma_f32_16x16x32_bf16 v[48:51], v[182:185], v[198:201], v[48:51]
	v_mfma_f32_16x16x32_bf16 v[44:47], v[174:177], v[206:209], v[44:47]
	v_mfma_f32_16x16x32_bf16 v[40:43], v[182:185], v[206:209], v[40:43]
	v_mfma_f32_16x16x32_bf16 v[36:39], v[174:177], v[216:219], v[36:39]
	v_mfma_f32_16x16x32_bf16 v[32:35], v[182:185], v[216:219], v[32:35]
	s_setprio 0
	s_barrier
	s_add_i32 s74, s64, s56
	v_lshl_add_u64 v[162:163], s[50:51], 0, v[140:141]
	s_mov_b32 m0, s74
	ds_read_b128 v[186:189], v169 offset:16384
	ds_read_b128 v[190:193], v169 offset:17408
	ds_read_b128 v[194:197], v169 offset:18432
	ds_read_b128 v[198:201], v169 offset:19456
	ds_read_b128 v[202:205], v169 offset:20480
	ds_read_b128 v[206:209], v169 offset:21504
	ds_read_b128 v[210:213], v169 offset:22528
	ds_read_b128 v[216:219], v169 offset:23552
	global_load_lds_dwordx4 v[162:163], off
	s_add_i32 m0, s74, 0x2000
	s_add_u32 s74, s50, 0x80000
	v_lshl_add_u64 v[220:221], s[50:51], 0, v[144:145]
	s_addc_u32 s75, s51, 0
	s_add_i32 s76, s65, s56
	global_load_lds_dwordx4 v[220:221], off
	v_lshl_add_u64 v[222:223], s[74:75], 0, v[140:141]
	s_mov_b32 m0, s76
	v_lshl_add_u64 v[224:225], s[52:53], 0, v[142:143]
	global_load_lds_dwordx4 v[222:223], off
	v_lshl_add_u64 v[222:223], s[74:75], 0, v[144:145]
	s_add_i32 m0, s76, 0x2000
	s_nop 0
	global_load_lds_dwordx4 v[222:223], off
	v_lshl_add_u64 v[222:223], s[52:53], 0, v[138:139]
	s_mov_b32 m0, s45
	s_nop 0
	global_load_lds_dwordx4 v[222:223], off
	s_mov_b32 m0, s57
	s_nop 0
	global_load_lds_dwordx4 v[224:225], off
	s_waitcnt vmcnt(8)
	s_waitcnt lgkmcnt(0)
	s_barrier
; #define PG8_STAGE(bufoff, gbase, voff) do { _Pragma("unroll") for (int _i = 0; _i < 2; ++_i) \
;         __builtin_amdgcn_global_load_lds((const unsigned*)((const char*)(gbase) + (voff)[_i]), (PG8_LAS unsigned*)(lds + (bufoff) + ldsw + _i * 8192), 16, 0, 0); } while (0)
; #define PG8_LDA(dst, b, h) do { _Pragma("unroll") for (int m = 0; m < 4; ++m) _Pragma("unroll") for (int k = 0; k < 2; ++k) dst[m][k] = *(const PG8_LAS bf16x8*)(lds + PG8_SA(b, h) + aoff + m * 2048 + k * 1024); } while (0)
; #define PG8_LDB(dst, b, h) do { _Pragma("unroll") for (int n = 0; n < 2; ++n) _Pragma("unroll") for (int k = 0; k < 2; ++k) dst[n][k] = *(const PG8_LAS bf16x8*)(lds + PG8_SB(b, h) + boff + n * 2048 + k * 1024); } while (0)
; #define PG8_MMA(ai, bj, At, Bt) do { __builtin_amdgcn_s_setprio(1); _Pragma("unroll") for (int m = 0; m < 4; ++m) _Pragma("unroll") for (int n = 0; n < 2; ++n) _Pragma("unroll") for (int k = 0; k < 2; ++k) \
;         acc[ai][bj][m][n] = __builtin_amdgcn_mfma_f32_16x16x32_bf16(Bt[n][k], At[m][k], acc[ai][bj][m][n], 0, 0, 0); __builtin_amdgcn_s_setprio(0); } while (0)
; #define PG8_WAIT_V(n) asm volatile("s_waitcnt vmcnt(" #n ")" ::: "memory")
; #define PG8_WAIT_L(n) asm volatile("s_waitcnt lgkmcnt(" #n ")" ::: "memory")
; #define PG8_BAR __builtin_amdgcn_s_barrier()
; #define PG8_SCHED __builtin_amdgcn_sched_barrier(0)
; template <class Epi, class Sched, bool ALIGN_EPI = false, bool SP2 = false>
; __device__ __forceinline__ void gemm_phase(PG8_LAS unsigned char* lds, const Gemm g, const Sched& S, const Epi& E, int tid_in) {
;     ...
;             PG8_WAIT_V(8); PG8_WAIT_L(0); PG8_BAR; PG8_MMA(1, 0, At, B0); PG8_MMA(1, 1, At, B1); PG8_BAR; PG8_SCHED;
;             PG8_LDB(B0, 1, 0); PG8_LDB(B1, 1, 1); PG8_SCHED; PG8_LDA(At, 1, 0); PG8_STAGE(PG8_SA(0, 1), a2 + hstep, voffA);
;             PG8_WAIT_V(8); PG8_WAIT_L(0); PG8_BAR; PG8_MMA(0, 0, At, B0); PG8_MMA(0, 1, At, B1); PG8_BAR; PG8_SCHED;
	s_setprio 1
	s_waitcnt lgkmcnt(0)
	v_mfma_f32_16x16x32_bf16 v[92:95], v[104:107], v[186:189], v[92:95]
	v_mfma_f32_16x16x32_bf16 v[88:91], v[154:157], v[186:189], v[88:91]
	v_mfma_f32_16x16x32_bf16 v[84:87], v[104:107], v[194:197], v[84:87]
	v_mfma_f32_16x16x32_bf16 v[80:83], v[154:157], v[194:197], v[80:83]
	v_mfma_f32_16x16x32_bf16 v[76:79], v[104:107], v[202:205], v[76:79]
	v_mfma_f32_16x16x32_bf16 v[72:75], v[154:157], v[202:205], v[72:75]
	v_mfma_f32_16x16x32_bf16 v[68:71], v[104:107], v[210:213], v[68:71]
	v_mfma_f32_16x16x32_bf16 v[64:67], v[154:157], v[210:213], v[64:67]
	v_mfma_f32_16x16x32_bf16 v[92:95], v[108:111], v[190:193], v[92:95]
	v_mfma_f32_16x16x32_bf16 v[88:91], v[158:161], v[190:193], v[88:91]
	v_mfma_f32_16x16x32_bf16 v[84:87], v[108:111], v[198:201], v[84:87]
	v_mfma_f32_16x16x32_bf16 v[80:83], v[158:161], v[198:201], v[80:83]
	v_mfma_f32_16x16x32_bf16 v[76:79], v[108:111], v[206:209], v[76:79]
	v_mfma_f32_16x16x32_bf16 v[72:75], v[158:161], v[206:209], v[72:75]
	v_mfma_f32_16x16x32_bf16 v[68:71], v[108:111], v[216:219], v[68:71]
	v_mfma_f32_16x16x32_bf16 v[64:67], v[158:161], v[216:219], v[64:67]
	v_mfma_f32_16x16x32_bf16 v[28:31], v[170:173], v[186:189], v[28:31]
	v_mfma_f32_16x16x32_bf16 v[24:27], v[178:181], v[186:189], v[24:27]
	v_mfma_f32_16x16x32_bf16 v[20:23], v[170:173], v[194:197], v[20:23]
	v_mfma_f32_16x16x32_bf16 v[16:19], v[178:181], v[194:197], v[16:19]
	v_mfma_f32_16x16x32_bf16 v[12:15], v[170:173], v[202:205], v[12:15]
	v_mfma_f32_16x16x32_bf16 v[8:11], v[178:181], v[202:205], v[8:11]
	v_mfma_f32_16x16x32_bf16 v[4:7], v[170:173], v[210:213], v[4:7]
	v_mfma_f32_16x16x32_bf16 v[0:3], v[178:181], v[210:213], v[0:3]
	v_mfma_f32_16x16x32_bf16 v[28:31], v[174:177], v[190:193], v[28:31]
	v_mfma_f32_16x16x32_bf16 v[24:27], v[182:185], v[190:193], v[24:27]
	v_mfma_f32_16x16x32_bf16 v[20:23], v[174:177], v[198:201], v[20:23]
	v_mfma_f32_16x16x32_bf16 v[16:19], v[182:185], v[198:201], v[16:19]
	v_mfma_f32_16x16x32_bf16 v[12:15], v[174:177], v[206:209], v[12:15]
	v_mfma_f32_16x16x32_bf16 v[8:11], v[182:185], v[206:209], v[8:11]
	v_mfma_f32_16x16x32_bf16 v[4:7], v[174:177], v[216:219], v[4:7]
	v_mfma_f32_16x16x32_bf16 v[0:3], v[182:185], v[216:219], v[0:3]
	s_setprio 0
	s_barrier
	s_add_i32 s74, 0, 0x18000
	s_add_i32 s75, 0, 0x1c000
	v_add_u32_e32 v158, s74, v165
	v_add_u32_e32 v182, s75, v165
	ds_read_b128 v[104:107], v158
	ds_read_b128 v[108:111], v158 offset:1024
	ds_read_b128 v[154:157], v158 offset:2048
	ds_read_b128 v[158:161], v158 offset:3072
	ds_read_b128 v[170:173], v182
	ds_read_b128 v[174:177], v182 offset:1024
	ds_read_b128 v[178:181], v182 offset:2048
	ds_read_b128 v[182:185], v182 offset:3072
	s_add_u32 s52, s52, 0x80000
	s_addc_u32 s53, s53, 0
	s_mov_b32 m0, s58
	v_lshl_add_u64 v[226:227], s[52:53], 0, v[138:139]
	ds_read_b128 v[186:189], v169 offset:32768
	ds_read_b128 v[190:193], v169 offset:33792
	ds_read_b128 v[194:197], v169 offset:34816
	ds_read_b128 v[198:201], v169 offset:35840
	ds_read_b128 v[202:205], v169 offset:36864
	ds_read_b128 v[206:209], v169 offset:37888
	ds_read_b128 v[210:213], v169 offset:38912
	ds_read_b128 v[216:219], v169 offset:39936
	global_load_lds_dwordx4 v[226:227], off
	v_lshl_add_u64 v[226:227], s[52:53], 0, v[142:143]
	s_mov_b32 m0, s59
	s_nop 0
	global_load_lds_dwordx4 v[226:227], off
	s_waitcnt vmcnt(8)
	s_waitcnt lgkmcnt(0)
	s_barrier
	s_setprio 1
	s_waitcnt lgkmcnt(0)
	v_mfma_f32_16x16x32_bf16 v[132:135], v[104:107], v[186:189], v[132:135]
	v_mfma_f32_16x16x32_bf16 v[128:131], v[154:157], v[186:189], v[128:131]
	v_mfma_f32_16x16x32_bf16 v[124:127], v[104:107], v[194:197], v[124:127]
	v_mfma_f32_16x16x32_bf16 v[120:123], v[154:157], v[194:197], v[120:123]
	v_mfma_f32_16x16x32_bf16 v[116:119], v[104:107], v[202:205], v[116:119]
	v_mfma_f32_16x16x32_bf16 v[112:115], v[154:157], v[202:205], v[112:115]
	v_mfma_f32_16x16x32_bf16 v[100:103], v[104:107], v[210:213], v[100:103]
	v_mfma_f32_16x16x32_bf16 v[96:99], v[154:157], v[210:213], v[96:99]
	v_mfma_f32_16x16x32_bf16 v[132:135], v[108:111], v[190:193], v[132:135]
	v_mfma_f32_16x16x32_bf16 v[128:131], v[158:161], v[190:193], v[128:131]
	v_mfma_f32_16x16x32_bf16 v[124:127], v[108:111], v[198:201], v[124:127]
	v_mfma_f32_16x16x32_bf16 v[120:123], v[158:161], v[198:201], v[120:123]
	v_mfma_f32_16x16x32_bf16 v[116:119], v[108:111], v[206:209], v[116:119]
	v_mfma_f32_16x16x32_bf16 v[112:115], v[158:161], v[206:209], v[112:115]
	v_mfma_f32_16x16x32_bf16 v[100:103], v[108:111], v[216:219], v[100:103]
	v_mfma_f32_16x16x32_bf16 v[96:99], v[158:161], v[216:219], v[96:99]
	v_mfma_f32_16x16x32_bf16 v[60:63], v[170:173], v[186:189], v[60:63]
	v_mfma_f32_16x16x32_bf16 v[56:59], v[178:181], v[186:189], v[56:59]
	v_mfma_f32_16x16x32_bf16 v[52:55], v[170:173], v[194:197], v[52:55]
	v_mfma_f32_16x16x32_bf16 v[48:51], v[178:181], v[194:197], v[48:51]
	v_mfma_f32_16x16x32_bf16 v[44:47], v[170:173], v[202:205], v[44:47]
	v_mfma_f32_16x16x32_bf16 v[40:43], v[178:181], v[202:205], v[40:43]
	v_mfma_f32_16x16x32_bf16 v[36:39], v[170:173], v[210:213], v[36:39]
	v_mfma_f32_16x16x32_bf16 v[32:35], v[178:181], v[210:213], v[32:35]
	v_mfma_f32_16x16x32_bf16 v[60:63], v[174:177], v[190:193], v[60:63]
	v_mfma_f32_16x16x32_bf16 v[56:59], v[182:185], v[190:193], v[56:59]
	v_mfma_f32_16x16x32_bf16 v[52:55], v[174:177], v[198:201], v[52:55]
	v_mfma_f32_16x16x32_bf16 v[48:51], v[182:185], v[198:201], v[48:51]
	v_mfma_f32_16x16x32_bf16 v[44:47], v[174:177], v[206:209], v[44:47]
	v_mfma_f32_16x16x32_bf16 v[40:43], v[182:185], v[206:209], v[40:43]
	v_mfma_f32_16x16x32_bf16 v[36:39], v[174:177], v[216:219], v[36:39]
	v_mfma_f32_16x16x32_bf16 v[32:35], v[182:185], v[216:219], v[32:35]
	s_setprio 0
	s_barrier
; #define PG8_STAGE(bufoff, gbase, voff) do { _Pragma("unroll") for (int _i = 0; _i < 2; ++_i) \
;         __builtin_amdgcn_global_load_lds((const unsigned*)((const char*)(gbase) + (voff)[_i]), (PG8_LAS unsigned*)(lds + (bufoff) + ldsw + _i * 8192), 16, 0, 0); } while (0)
; #define PG8_LDA(dst, b, h) do { _Pragma("unroll") for (int m = 0; m < 4; ++m) _Pragma("unroll") for (int k = 0; k < 2; ++k) dst[m][k] = *(const PG8_LAS bf16x8*)(lds + PG8_SA(b, h) + aoff + m * 2048 + k * 1024); } while (0)
; #define PG8_MMA(ai, bj, At, Bt) do { __builtin_amdgcn_s_setprio(1); _Pragma("unroll") for (int m = 0; m < 4; ++m) _Pragma("unroll") for (int n = 0; n < 2; ++n) _Pragma("unroll") for (int k = 0; k < 2; ++k) \
;         acc[ai][bj][m][n] = __builtin_amdgcn_mfma_f32_16x16x32_bf16(Bt[n][k], At[m][k], acc[ai][bj][m][n], 0, 0, 0); __builtin_amdgcn_s_setprio(0); } while (0)
; #define PG8_WAIT_V(n) asm volatile("s_waitcnt vmcnt(" #n ")" ::: "memory")
; #define PG8_WAIT_L(n) asm volatile("s_waitcnt lgkmcnt(" #n ")" ::: "memory")
; #define PG8_BAR __builtin_amdgcn_s_barrier()
; #define PG8_SCHED __builtin_amdgcn_sched_barrier(0)
; template <class Epi, class Sched, bool ALIGN_EPI = false, bool SP2 = false>
; __device__ __forceinline__ void gemm_phase(PG8_LAS unsigned char* lds, const Gemm g, const Sched& S, const Epi& E, int tid_in) {
;     ...
;         for (int t = 0; t < nt; t += 2) {
;             const bool last = (t == nt - 2);
;     ...
;             PG8_LDA(At, 1, 1); PG8_STAGE(PG8_SB(1, 0), b3, voffB); PG8_STAGE(PG8_SB(1, 1), b3 + hstep, voffB); PG8_STAGE(PG8_SA(1, 0), a3, voffA);
;             PG8_WAIT_V(8); PG8_WAIT_L(0); PG8_BAR; PG8_MMA(1, 0, At, B0); PG8_MMA(1, 1, At, B1); PG8_BAR; PG8_SCHED;
	s_add_i32 s52, s74, s56
	v_lshl_add_u64 v[162:163], v[162:163], 0, s[8:9]
	s_mov_b32 m0, s52
	ds_read_b128 v[186:189], v169 offset:49152
	ds_read_b128 v[190:193], v169 offset:50176
	ds_read_b128 v[194:197], v169 offset:51200
	ds_read_b128 v[198:201], v169 offset:52224
	ds_read_b128 v[202:205], v169 offset:53248
	ds_read_b128 v[206:209], v169 offset:54272
	ds_read_b128 v[210:213], v169 offset:55296
	ds_read_b128 v[216:219], v169 offset:56320
	global_load_lds_dwordx4 v[162:163], off
	s_add_i32 m0, s52, 0x2000
	s_add_u32 s50, s50, 0x80080
	v_lshl_add_u64 v[162:163], v[220:221], 0, s[8:9]
	s_addc_u32 s51, s51, 0
	s_add_i32 s52, s75, s56
	global_load_lds_dwordx4 v[162:163], off
	v_lshl_add_u64 v[162:163], s[50:51], 0, v[140:141]
	s_mov_b32 m0, s52
	s_nop 0
	global_load_lds_dwordx4 v[162:163], off
	v_lshl_add_u64 v[162:163], s[50:51], 0, v[144:145]
	s_add_i32 m0, s52, 0x2000
	s_nop 0
	global_load_lds_dwordx4 v[162:163], off
	v_lshl_add_u64 v[162:163], v[222:223], 0, s[8:9]
	s_mov_b32 m0, s61
	s_nop 0
	global_load_lds_dwordx4 v[162:163], off
	v_lshl_add_u64 v[162:163], v[224:225], 0, s[8:9]
	s_mov_b32 m0, s62
	s_nop 0
	global_load_lds_dwordx4 v[162:163], off
	s_waitcnt vmcnt(8)
	s_waitcnt lgkmcnt(0)
	s_barrier
	s_setprio 1
	s_waitcnt lgkmcnt(0)
	v_mfma_f32_16x16x32_bf16 v[92:95], v[104:107], v[186:189], v[92:95]
	v_mfma_f32_16x16x32_bf16 v[88:91], v[154:157], v[186:189], v[88:91]
	v_mfma_f32_16x16x32_bf16 v[84:87], v[104:107], v[194:197], v[84:87]
	v_mfma_f32_16x16x32_bf16 v[80:83], v[154:157], v[194:197], v[80:83]
	v_mfma_f32_16x16x32_bf16 v[76:79], v[104:107], v[202:205], v[76:79]
	v_mfma_f32_16x16x32_bf16 v[72:75], v[154:157], v[202:205], v[72:75]
	v_mfma_f32_16x16x32_bf16 v[68:71], v[104:107], v[210:213], v[68:71]
	v_mfma_f32_16x16x32_bf16 v[64:67], v[154:157], v[210:213], v[64:67]
	v_mfma_f32_16x16x32_bf16 v[92:95], v[108:111], v[190:193], v[92:95]
	v_mfma_f32_16x16x32_bf16 v[88:91], v[158:161], v[190:193], v[88:91]
	v_mfma_f32_16x16x32_bf16 v[84:87], v[108:111], v[198:201], v[84:87]
	v_mfma_f32_16x16x32_bf16 v[80:83], v[158:161], v[198:201], v[80:83]
	v_mfma_f32_16x16x32_bf16 v[76:79], v[108:111], v[206:209], v[76:79]
	v_mfma_f32_16x16x32_bf16 v[72:75], v[158:161], v[206:209], v[72:75]
	v_mfma_f32_16x16x32_bf16 v[68:71], v[108:111], v[216:219], v[68:71]
	v_mfma_f32_16x16x32_bf16 v[64:67], v[158:161], v[216:219], v[64:67]
	v_mfma_f32_16x16x32_bf16 v[28:31], v[170:173], v[186:189], v[28:31]
	v_mfma_f32_16x16x32_bf16 v[24:27], v[178:181], v[186:189], v[24:27]
	v_mfma_f32_16x16x32_bf16 v[20:23], v[170:173], v[194:197], v[20:23]
	v_mfma_f32_16x16x32_bf16 v[16:19], v[178:181], v[194:197], v[16:19]
	v_mfma_f32_16x16x32_bf16 v[12:15], v[170:173], v[202:205], v[12:15]
	v_mfma_f32_16x16x32_bf16 v[8:11], v[178:181], v[202:205], v[8:11]
	v_mfma_f32_16x16x32_bf16 v[4:7], v[170:173], v[210:213], v[4:7]
	v_mfma_f32_16x16x32_bf16 v[0:3], v[178:181], v[210:213], v[0:3]
	v_mfma_f32_16x16x32_bf16 v[28:31], v[174:177], v[190:193], v[28:31]
	v_mfma_f32_16x16x32_bf16 v[24:27], v[182:185], v[190:193], v[24:27]
	v_mfma_f32_16x16x32_bf16 v[20:23], v[174:177], v[198:201], v[20:23]
	v_mfma_f32_16x16x32_bf16 v[16:19], v[182:185], v[198:201], v[16:19]
	v_mfma_f32_16x16x32_bf16 v[12:15], v[174:177], v[206:209], v[12:15]
	v_mfma_f32_16x16x32_bf16 v[8:11], v[182:185], v[206:209], v[8:11]
	v_mfma_f32_16x16x32_bf16 v[4:7], v[174:177], v[216:219], v[4:7]
	v_mfma_f32_16x16x32_bf16 v[0:3], v[182:185], v[216:219], v[0:3]
	s_add_i32 s73, s73, 2
	s_add_u32 s46, s46, 0x100
	s_addc_u32 s47, s47, 0
	s_add_u32 s71, s71, 0x100
	s_addc_u32 s72, s72, 0
	s_cmp_gt_u32 s73, 29
	s_setprio 0
	s_barrier
	s_cbranch_scc0 .LBB0_452
	s_and_b64 vcc, exec, s[10:11]
	s_cbranch_vccz .LBB0_455
	s_barrier

; #define PG8_STAGE(bufoff, gbase, voff) do { _Pragma("unroll") for (int _i = 0; _i < 2; ++_i) \
;         __builtin_amdgcn_global_load_lds((const unsigned*)((const char*)(gbase) + (voff)[_i]), (PG8_LAS unsigned*)(lds + (bufoff) + ldsw + _i * 8192), 16, 0, 0); } while (0)
; #define PG8_LDA(dst, b, h) do { _Pragma("unroll") for (int m = 0; m < 4; ++m) _Pragma("unroll") for (int k = 0; k < 2; ++k) dst[m][k] = *(const PG8_LAS bf16x8*)(lds + PG8_SA(b, h) + aoff + m * 2048 + k * 1024); } while (0)
; #define PG8_LDB(dst, b, h) do { _Pragma("unroll") for (int n = 0; n < 2; ++n) _Pragma("unroll") for (int k = 0; k < 2; ++k) dst[n][k] = *(const PG8_LAS bf16x8*)(lds + PG8_SB(b, h) + boff + n * 2048 + k * 1024); } while (0)
; #define PG8_MMA(ai, bj, At, Bt) do { __builtin_amdgcn_s_setprio(1); _Pragma("unroll") for (int m = 0; m < 4; ++m) _Pragma("unroll") for (int n = 0; n < 2; ++n) _Pragma("unroll") for (int k = 0; k < 2; ++k) \
;         acc[ai][bj][m][n] = __builtin_amdgcn_mfma_f32_16x16x32_bf16(Bt[n][k], At[m][k], acc[ai][bj][m][n], 0, 0, 0); __builtin_amdgcn_s_setprio(0); } while (0)
; #define PG8_WAIT_V(n) asm volatile("s_waitcnt vmcnt(" #n ")" ::: "memory")
; #define PG8_WAIT_L(n) asm volatile("s_waitcnt lgkmcnt(" #n ")" ::: "memory")
; #define PG8_BAR __builtin_amdgcn_s_barrier()
; #define PG8_SCHED __builtin_amdgcn_sched_barrier(0)
; template <class Epi, class Sched, bool ALIGN_EPI = false, bool SP2 = false>
; __device__ __forceinline__ void gemm_phase(PG8_LAS unsigned char* lds, const Gemm g, const Sched& S, const Epi& E, int tid_in) {
;     ...
;             const bool last = (t == nt - 2);
;             const char* a1 = cA + (size_t)(t + 1) * kstep;
;             const char* a2 = last ? nA : cA + (size_t)(t + 2) * kstep; const char* b2 = last ? nB : cB + (size_t)(t + 2) * kstep;
;             const char* a3 = a2 + kstep; const char* b3 = b2 + kstep;
;             if (last && has_next) S.a_ready(nxt);
;             if constexpr (SP2) {
;             PG8_LDB(B0, 0, 0); PG8_LDB(B1, 0, 1); PG8_SCHED; PG8_LDA(At, 0, 0); PG8_STAGE(PG8_SA(1, 1), a1 + hstep, voffA);
;             PG8_WAIT_V(8); PG8_WAIT_L(0); PG8_BAR; PG8_MMA(0, 0, At, B0); PG8_MMA(0, 1, At, B1); PG8_BAR; PG8_SCHED;
;             PG8_LDA(At, 0, 1); PG8_STAGE(PG8_SB(0, 0), b2, voffB); PG8_STAGE(PG8_SB(0, 1), b2 + hstep, voffB); PG8_STAGE(PG8_SA(0, 0), a2, voffA);
.LBB0_484:
	ds_read_b128 v[144:147], v153
	ds_read_b128 v[156:159], v153 offset:1024
	ds_read_b128 v[160:163], v153 offset:2048
	ds_read_b128 v[164:167], v153 offset:3072
	ds_read_b128 v[168:171], v154
	ds_read_b128 v[172:175], v154 offset:1024
	ds_read_b128 v[176:179], v154 offset:2048
	ds_read_b128 v[180:183], v154 offset:3072
	s_add_u32 s38, s36, 0xfff80080
	s_addc_u32 s39, s37, -1
	s_cmp_eq_u32 s59, 28
	s_cselect_b32 s41, s21, s39
	s_cselect_b32 s40, s55, s38
	s_cselect_b32 s39, s19, s58
	s_cselect_b32 s38, s56, s57
	v_lshl_add_u64 v[148:149], s[36:37], 0, v[136:137]
	s_add_i32 m0, s31, 0xc000
	ds_read_b128 v[184:187], v155
	ds_read_b128 v[188:191], v155 offset:1024
	ds_read_b128 v[192:195], v155 offset:2048
	ds_read_b128 v[196:199], v155 offset:3072
	ds_read_b128 v[200:203], v155 offset:4096
	ds_read_b128 v[204:207], v155 offset:5120
	ds_read_b128 v[208:211], v155 offset:6144
	ds_read_b128 v[212:215], v155 offset:7168
	global_load_lds_dwordx4 v[148:149], off
	v_lshl_add_u64 v[148:149], s[36:37], 0, v[138:139]
	s_add_i32 m0, s31, 0xe000
	s_nop 0
	global_load_lds_dwordx4 v[148:149], off
	s_waitcnt vmcnt(8)
	s_waitcnt lgkmcnt(0)
	s_barrier
	s_setprio 1
	s_waitcnt lgkmcnt(0)
	v_mfma_f32_16x16x32_bf16 v[124:127], v[144:147], v[184:187], v[124:127]
	v_mfma_f32_16x16x32_bf16 v[120:123], v[160:163], v[184:187], v[120:123]
	v_mfma_f32_16x16x32_bf16 v[108:111], v[144:147], v[192:195], v[108:111]
	v_mfma_f32_16x16x32_bf16 v[104:107], v[160:163], v[192:195], v[104:107]
	v_mfma_f32_16x16x32_bf16 v[92:95], v[144:147], v[200:203], v[92:95]
	v_mfma_f32_16x16x32_bf16 v[88:91], v[160:163], v[200:203], v[88:91]
	v_mfma_f32_16x16x32_bf16 v[76:79], v[144:147], v[208:211], v[76:79]
	v_mfma_f32_16x16x32_bf16 v[72:75], v[160:163], v[208:211], v[72:75]
	v_mfma_f32_16x16x32_bf16 v[124:127], v[156:159], v[188:191], v[124:127]
	v_mfma_f32_16x16x32_bf16 v[120:123], v[164:167], v[188:191], v[120:123]
	v_mfma_f32_16x16x32_bf16 v[108:111], v[156:159], v[196:199], v[108:111]
	v_mfma_f32_16x16x32_bf16 v[104:107], v[164:167], v[196:199], v[104:107]
	v_mfma_f32_16x16x32_bf16 v[92:95], v[156:159], v[204:207], v[92:95]
	v_mfma_f32_16x16x32_bf16 v[88:91], v[164:167], v[204:207], v[88:91]
	v_mfma_f32_16x16x32_bf16 v[76:79], v[156:159], v[212:215], v[76:79]
	v_mfma_f32_16x16x32_bf16 v[72:75], v[164:167], v[212:215], v[72:75]
	v_mfma_f32_16x16x32_bf16 v[116:119], v[168:171], v[184:187], v[116:119]
	v_mfma_f32_16x16x32_bf16 v[112:115], v[176:179], v[184:187], v[112:115]
	v_mfma_f32_16x16x32_bf16 v[100:103], v[168:171], v[192:195], v[100:103]
	v_mfma_f32_16x16x32_bf16 v[96:99], v[176:179], v[192:195], v[96:99]
	v_mfma_f32_16x16x32_bf16 v[84:87], v[168:171], v[200:203], v[84:87]
	v_mfma_f32_16x16x32_bf16 v[80:83], v[176:179], v[200:203], v[80:83]
	v_mfma_f32_16x16x32_bf16 v[68:71], v[168:171], v[208:211], v[68:71]
	v_mfma_f32_16x16x32_bf16 v[64:67], v[176:179], v[208:211], v[64:67]
	v_mfma_f32_16x16x32_bf16 v[116:119], v[172:175], v[188:191], v[116:119]
	v_mfma_f32_16x16x32_bf16 v[112:115], v[180:183], v[188:191], v[112:115]
	v_mfma_f32_16x16x32_bf16 v[100:103], v[172:175], v[196:199], v[100:103]
	v_mfma_f32_16x16x32_bf16 v[96:99], v[180:183], v[196:199], v[96:99]
	v_mfma_f32_16x16x32_bf16 v[84:87], v[172:175], v[204:207], v[84:87]
	v_mfma_f32_16x16x32_bf16 v[80:83], v[180:183], v[204:207], v[80:83]
	v_mfma_f32_16x16x32_bf16 v[68:71], v[172:175], v[212:215], v[68:71]
	v_mfma_f32_16x16x32_bf16 v[64:67], v[180:183], v[212:215], v[64:67]
	s_setprio 0
	s_barrier
	s_add_i32 s60, s52, s44
	v_lshl_add_u64 v[148:149], s[38:39], 0, v[130:131]
	s_mov_b32 m0, s60
	ds_read_b128 v[184:187], v155 offset:16384
	ds_read_b128 v[188:191], v155 offset:17408
	ds_read_b128 v[192:195], v155 offset:18432
	ds_read_b128 v[196:199], v155 offset:19456
	ds_read_b128 v[200:203], v155 offset:20480
	ds_read_b128 v[204:207], v155 offset:21504
	ds_read_b128 v[208:211], v155 offset:22528
	ds_read_b128 v[212:215], v155 offset:23552
	global_load_lds_dwordx4 v[148:149], off
	s_add_i32 m0, s60, 0x2000
	s_add_u32 s60, s38, 0x80000
	v_lshl_add_u64 v[216:217], s[38:39], 0, v[134:135]
	s_addc_u32 s61, s39, 0
	s_add_i32 s62, s53, s44
	global_load_lds_dwordx4 v[216:217], off
	v_lshl_add_u64 v[218:219], s[60:61], 0, v[130:131]
	s_mov_b32 m0, s62
	v_lshl_add_u64 v[220:221], s[40:41], 0, v[132:133]
	global_load_lds_dwordx4 v[218:219], off
	v_lshl_add_u64 v[218:219], s[60:61], 0, v[134:135]
	s_add_i32 m0, s62, 0x2000
	s_nop 0
	global_load_lds_dwordx4 v[218:219], off
	v_lshl_add_u64 v[218:219], s[40:41], 0, v[128:129]
	s_mov_b32 m0, s31
	s_nop 0
	global_load_lds_dwordx4 v[218:219], off
	s_mov_b32 m0, s45
	s_nop 0
	global_load_lds_dwordx4 v[220:221], off
	s_waitcnt vmcnt(8)
	s_waitcnt lgkmcnt(0)
	s_barrier
; #define PG8_STAGE(bufoff, gbase, voff) do { _Pragma("unroll") for (int _i = 0; _i < 2; ++_i) \
;         __builtin_amdgcn_global_load_lds((const unsigned*)((const char*)(gbase) + (voff)[_i]), (PG8_LAS unsigned*)(lds + (bufoff) + ldsw + _i * 8192), 16, 0, 0); } while (0)
; #define PG8_LDA(dst, b, h) do { _Pragma("unroll") for (int m = 0; m < 4; ++m) _Pragma("unroll") for (int k = 0; k < 2; ++k) dst[m][k] = *(const PG8_LAS bf16x8*)(lds + PG8_SA(b, h) + aoff + m * 2048 + k * 1024); } while (0)
; #define PG8_LDB(dst, b, h) do { _Pragma("unroll") for (int n = 0; n < 2; ++n) _Pragma("unroll") for (int k = 0; k < 2; ++k) dst[n][k] = *(const PG8_LAS bf16x8*)(lds + PG8_SB(b, h) + boff + n * 2048 + k * 1024); } while (0)
; #define PG8_MMA(ai, bj, At, Bt) do { __builtin_amdgcn_s_setprio(1); _Pragma("unroll") for (int m = 0; m < 4; ++m) _Pragma("unroll") for (int n = 0; n < 2; ++n) _Pragma("unroll") for (int k = 0; k < 2; ++k) \
;         acc[ai][bj][m][n] = __builtin_amdgcn_mfma_f32_16x16x32_bf16(Bt[n][k], At[m][k], acc[ai][bj][m][n], 0, 0, 0); __builtin_amdgcn_s_setprio(0); } while (0)
; #define PG8_WAIT_V(n) asm volatile("s_waitcnt vmcnt(" #n ")" ::: "memory")
; #define PG8_WAIT_L(n) asm volatile("s_waitcnt lgkmcnt(" #n ")" ::: "memory")
; #define PG8_BAR __builtin_amdgcn_s_barrier()
; #define PG8_SCHED __builtin_amdgcn_sched_barrier(0)
; template <class Epi, class Sched, bool ALIGN_EPI = false, bool SP2 = false>
; __device__ __forceinline__ void gemm_phase(PG8_LAS unsigned char* lds, const Gemm g, const Sched& S, const Epi& E, int tid_in) {
;     ...
;             PG8_WAIT_V(8); PG8_WAIT_L(0); PG8_BAR; PG8_MMA(1, 0, At, B0); PG8_MMA(1, 1, At, B1); PG8_BAR; PG8_SCHED;
;             PG8_LDB(B0, 1, 0); PG8_LDB(B1, 1, 1); PG8_SCHED; PG8_LDA(At, 1, 0); PG8_STAGE(PG8_SA(0, 1), a2 + hstep, voffA);
;             PG8_WAIT_V(8); PG8_WAIT_L(0); PG8_BAR; PG8_MMA(0, 0, At, B0); PG8_MMA(0, 1, At, B1); PG8_BAR; PG8_SCHED;
	s_setprio 1
	s_waitcnt lgkmcnt(0)
	v_mfma_f32_16x16x32_bf16 v[60:63], v[144:147], v[184:187], v[60:63]
	v_mfma_f32_16x16x32_bf16 v[56:59], v[160:163], v[184:187], v[56:59]
	v_mfma_f32_16x16x32_bf16 v[44:47], v[144:147], v[192:195], v[44:47]
	v_mfma_f32_16x16x32_bf16 v[40:43], v[160:163], v[192:195], v[40:43]
	v_mfma_f32_16x16x32_bf16 v[28:31], v[144:147], v[200:203], v[28:31]
	v_mfma_f32_16x16x32_bf16 v[24:27], v[160:163], v[200:203], v[24:27]
	v_mfma_f32_16x16x32_bf16 v[12:15], v[144:147], v[208:211], v[12:15]
	v_mfma_f32_16x16x32_bf16 v[8:11], v[160:163], v[208:211], v[8:11]
	v_mfma_f32_16x16x32_bf16 v[60:63], v[156:159], v[188:191], v[60:63]
	v_mfma_f32_16x16x32_bf16 v[56:59], v[164:167], v[188:191], v[56:59]
	v_mfma_f32_16x16x32_bf16 v[44:47], v[156:159], v[196:199], v[44:47]
	v_mfma_f32_16x16x32_bf16 v[40:43], v[164:167], v[196:199], v[40:43]
	v_mfma_f32_16x16x32_bf16 v[28:31], v[156:159], v[204:207], v[28:31]
	v_mfma_f32_16x16x32_bf16 v[24:27], v[164:167], v[204:207], v[24:27]
	v_mfma_f32_16x16x32_bf16 v[12:15], v[156:159], v[212:215], v[12:15]
	v_mfma_f32_16x16x32_bf16 v[8:11], v[164:167], v[212:215], v[8:11]
	v_mfma_f32_16x16x32_bf16 v[52:55], v[168:171], v[184:187], v[52:55]
	v_mfma_f32_16x16x32_bf16 v[48:51], v[176:179], v[184:187], v[48:51]
	v_mfma_f32_16x16x32_bf16 v[36:39], v[168:171], v[192:195], v[36:39]
	v_mfma_f32_16x16x32_bf16 v[32:35], v[176:179], v[192:195], v[32:35]
	v_mfma_f32_16x16x32_bf16 v[20:23], v[168:171], v[200:203], v[20:23]
	v_mfma_f32_16x16x32_bf16 v[16:19], v[176:179], v[200:203], v[16:19]
	v_mfma_f32_16x16x32_bf16 v[4:7], v[168:171], v[208:211], v[4:7]
	v_mfma_f32_16x16x32_bf16 v[0:3], v[176:179], v[208:211], v[0:3]
	v_mfma_f32_16x16x32_bf16 v[52:55], v[172:175], v[188:191], v[52:55]
	v_mfma_f32_16x16x32_bf16 v[48:51], v[180:183], v[188:191], v[48:51]
	v_mfma_f32_16x16x32_bf16 v[36:39], v[172:175], v[196:199], v[36:39]
	v_mfma_f32_16x16x32_bf16 v[32:35], v[180:183], v[196:199], v[32:35]
	v_mfma_f32_16x16x32_bf16 v[20:23], v[172:175], v[204:207], v[20:23]
	v_mfma_f32_16x16x32_bf16 v[16:19], v[180:183], v[204:207], v[16:19]
	v_mfma_f32_16x16x32_bf16 v[4:7], v[172:175], v[212:215], v[4:7]
	v_mfma_f32_16x16x32_bf16 v[0:3], v[180:183], v[212:215], v[0:3]
	s_setprio 0
	s_barrier
	s_add_i32 s60, 0, 0x18000
	s_add_i32 s61, 0, 0x1c000
	v_add_u32_e32 v164, s60, v151
	v_add_u32_e32 v180, s61, v151
	ds_read_b128 v[144:147], v164
	ds_read_b128 v[156:159], v164 offset:1024
	ds_read_b128 v[160:163], v164 offset:2048
	ds_read_b128 v[164:167], v164 offset:3072
	ds_read_b128 v[168:171], v180
	ds_read_b128 v[172:175], v180 offset:1024
	ds_read_b128 v[176:179], v180 offset:2048
	ds_read_b128 v[180:183], v180 offset:3072
	s_add_u32 s40, s40, 0x80000
	s_addc_u32 s41, s41, 0
	s_mov_b32 m0, s46
	v_lshl_add_u64 v[222:223], s[40:41], 0, v[128:129]
	ds_read_b128 v[184:187], v155 offset:32768
	ds_read_b128 v[188:191], v155 offset:33792
	ds_read_b128 v[192:195], v155 offset:34816
	ds_read_b128 v[196:199], v155 offset:35840
	ds_read_b128 v[200:203], v155 offset:36864
	ds_read_b128 v[204:207], v155 offset:37888
	ds_read_b128 v[208:211], v155 offset:38912
	ds_read_b128 v[212:215], v155 offset:39936
	global_load_lds_dwordx4 v[222:223], off
	v_lshl_add_u64 v[222:223], s[40:41], 0, v[132:133]
	s_mov_b32 m0, s47
	s_nop 0
	global_load_lds_dwordx4 v[222:223], off
	s_waitcnt vmcnt(8)
	s_waitcnt lgkmcnt(0)
	s_barrier
	s_setprio 1
	s_waitcnt lgkmcnt(0)
	v_mfma_f32_16x16x32_bf16 v[124:127], v[144:147], v[184:187], v[124:127]
	v_mfma_f32_16x16x32_bf16 v[120:123], v[160:163], v[184:187], v[120:123]
	v_mfma_f32_16x16x32_bf16 v[108:111], v[144:147], v[192:195], v[108:111]
	v_mfma_f32_16x16x32_bf16 v[104:107], v[160:163], v[192:195], v[104:107]
	v_mfma_f32_16x16x32_bf16 v[92:95], v[144:147], v[200:203], v[92:95]
	v_mfma_f32_16x16x32_bf16 v[88:91], v[160:163], v[200:203], v[88:91]
	v_mfma_f32_16x16x32_bf16 v[76:79], v[144:147], v[208:211], v[76:79]
	v_mfma_f32_16x16x32_bf16 v[72:75], v[160:163], v[208:211], v[72:75]
	v_mfma_f32_16x16x32_bf16 v[124:127], v[156:159], v[188:191], v[124:127]
	v_mfma_f32_16x16x32_bf16 v[120:123], v[164:167], v[188:191], v[120:123]
	v_mfma_f32_16x16x32_bf16 v[108:111], v[156:159], v[196:199], v[108:111]
	v_mfma_f32_16x16x32_bf16 v[104:107], v[164:167], v[196:199], v[104:107]
	v_mfma_f32_16x16x32_bf16 v[92:95], v[156:159], v[204:207], v[92:95]
	v_mfma_f32_16x16x32_bf16 v[88:91], v[164:167], v[204:207], v[88:91]
	v_mfma_f32_16x16x32_bf16 v[76:79], v[156:159], v[212:215], v[76:79]
	v_mfma_f32_16x16x32_bf16 v[72:75], v[164:167], v[212:215], v[72:75]
	v_mfma_f32_16x16x32_bf16 v[116:119], v[168:171], v[184:187], v[116:119]
	v_mfma_f32_16x16x32_bf16 v[112:115], v[176:179], v[184:187], v[112:115]
	v_mfma_f32_16x16x32_bf16 v[100:103], v[168:171], v[192:195], v[100:103]
	v_mfma_f32_16x16x32_bf16 v[96:99], v[176:179], v[192:195], v[96:99]
	v_mfma_f32_16x16x32_bf16 v[84:87], v[168:171], v[200:203], v[84:87]
	v_mfma_f32_16x16x32_bf16 v[80:83], v[176:179], v[200:203], v[80:83]
	v_mfma_f32_16x16x32_bf16 v[68:71], v[168:171], v[208:211], v[68:71]
	v_mfma_f32_16x16x32_bf16 v[64:67], v[176:179], v[208:211], v[64:67]
	v_mfma_f32_16x16x32_bf16 v[116:119], v[172:175], v[188:191], v[116:119]
	v_mfma_f32_16x16x32_bf16 v[112:115], v[180:183], v[188:191], v[112:115]
	v_mfma_f32_16x16x32_bf16 v[100:103], v[172:175], v[196:199], v[100:103]
	v_mfma_f32_16x16x32_bf16 v[96:99], v[180:183], v[196:199], v[96:99]
	v_mfma_f32_16x16x32_bf16 v[84:87], v[172:175], v[204:207], v[84:87]
	v_mfma_f32_16x16x32_bf16 v[80:83], v[180:183], v[204:207], v[80:83]
	v_mfma_f32_16x16x32_bf16 v[68:71], v[172:175], v[212:215], v[68:71]
	v_mfma_f32_16x16x32_bf16 v[64:67], v[180:183], v[212:215], v[64:67]
	s_setprio 0
	s_barrier
; #define PG8_STAGE(bufoff, gbase, voff) do { _Pragma("unroll") for (int _i = 0; _i < 2; ++_i) \
;         __builtin_amdgcn_global_load_lds((const unsigned*)((const char*)(gbase) + (voff)[_i]), (PG8_LAS unsigned*)(lds + (bufoff) + ldsw + _i * 8192), 16, 0, 0); } while (0)
; #define PG8_LDA(dst, b, h) do { _Pragma("unroll") for (int m = 0; m < 4; ++m) _Pragma("unroll") for (int k = 0; k < 2; ++k) dst[m][k] = *(const PG8_LAS bf16x8*)(lds + PG8_SA(b, h) + aoff + m * 2048 + k * 1024); } while (0)
; #define PG8_MMA(ai, bj, At, Bt) do { __builtin_amdgcn_s_setprio(1); _Pragma("unroll") for (int m = 0; m < 4; ++m) _Pragma("unroll") for (int n = 0; n < 2; ++n) _Pragma("unroll") for (int k = 0; k < 2; ++k) \
;         acc[ai][bj][m][n] = __builtin_amdgcn_mfma_f32_16x16x32_bf16(Bt[n][k], At[m][k], acc[ai][bj][m][n], 0, 0, 0); __builtin_amdgcn_s_setprio(0); } while (0)
; #define PG8_WAIT_V(n) asm volatile("s_waitcnt vmcnt(" #n ")" ::: "memory")
; #define PG8_WAIT_L(n) asm volatile("s_waitcnt lgkmcnt(" #n ")" ::: "memory")
; #define PG8_BAR __builtin_amdgcn_s_barrier()
; #define PG8_SCHED __builtin_amdgcn_sched_barrier(0)
; template <class Epi, class Sched, bool ALIGN_EPI = false, bool SP2 = false>
; __device__ __forceinline__ void gemm_phase(PG8_LAS unsigned char* lds, const Gemm g, const Sched& S, const Epi& E, int tid_in) {
;     ...
;         for (int t = 0; t < nt; t += 2) {
;             const bool last = (t == nt - 2);
;     ...
;             PG8_LDA(At, 1, 1); PG8_STAGE(PG8_SB(1, 0), b3, voffB); PG8_STAGE(PG8_SB(1, 1), b3 + hstep, voffB); PG8_STAGE(PG8_SA(1, 0), a3, voffA);
;             PG8_WAIT_V(8); PG8_WAIT_L(0); PG8_BAR; PG8_MMA(1, 0, At, B0); PG8_MMA(1, 1, At, B1); PG8_BAR; PG8_SCHED;
	s_add_i32 s40, s60, s44
	v_lshl_add_u64 v[148:149], v[148:149], 0, s[6:7]
	s_mov_b32 m0, s40
	ds_read_b128 v[184:187], v155 offset:49152
	ds_read_b128 v[188:191], v155 offset:50176
	ds_read_b128 v[192:195], v155 offset:51200
	ds_read_b128 v[196:199], v155 offset:52224
	ds_read_b128 v[200:203], v155 offset:53248
	ds_read_b128 v[204:207], v155 offset:54272
	ds_read_b128 v[208:211], v155 offset:55296
	ds_read_b128 v[212:215], v155 offset:56320
	global_load_lds_dwordx4 v[148:149], off
	s_add_i32 m0, s40, 0x2000
	s_add_u32 s38, s38, 0x80080
	v_lshl_add_u64 v[148:149], v[216:217], 0, s[6:7]
	s_addc_u32 s39, s39, 0
	s_add_i32 s40, s61, s44
	global_load_lds_dwordx4 v[148:149], off
	v_lshl_add_u64 v[148:149], s[38:39], 0, v[130:131]
	s_mov_b32 m0, s40
	s_nop 0
	global_load_lds_dwordx4 v[148:149], off
	v_lshl_add_u64 v[148:149], s[38:39], 0, v[134:135]
	s_add_i32 m0, s40, 0x2000
	s_nop 0
	global_load_lds_dwordx4 v[148:149], off
	v_lshl_add_u64 v[148:149], v[218:219], 0, s[6:7]
	s_mov_b32 m0, s49
	s_nop 0
	global_load_lds_dwordx4 v[148:149], off
	v_lshl_add_u64 v[148:149], v[220:221], 0, s[6:7]
	s_mov_b32 m0, s50
	s_nop 0
	global_load_lds_dwordx4 v[148:149], off
	s_waitcnt vmcnt(8)
	s_waitcnt lgkmcnt(0)
	s_barrier
	s_setprio 1
	s_waitcnt lgkmcnt(0)
	v_mfma_f32_16x16x32_bf16 v[60:63], v[144:147], v[184:187], v[60:63]
	v_mfma_f32_16x16x32_bf16 v[56:59], v[160:163], v[184:187], v[56:59]
	v_mfma_f32_16x16x32_bf16 v[44:47], v[144:147], v[192:195], v[44:47]
	v_mfma_f32_16x16x32_bf16 v[40:43], v[160:163], v[192:195], v[40:43]
	v_mfma_f32_16x16x32_bf16 v[28:31], v[144:147], v[200:203], v[28:31]
	v_mfma_f32_16x16x32_bf16 v[24:27], v[160:163], v[200:203], v[24:27]
	v_mfma_f32_16x16x32_bf16 v[12:15], v[144:147], v[208:211], v[12:15]
	v_mfma_f32_16x16x32_bf16 v[8:11], v[160:163], v[208:211], v[8:11]
	v_mfma_f32_16x16x32_bf16 v[60:63], v[156:159], v[188:191], v[60:63]
	v_mfma_f32_16x16x32_bf16 v[56:59], v[164:167], v[188:191], v[56:59]
	v_mfma_f32_16x16x32_bf16 v[44:47], v[156:159], v[196:199], v[44:47]
	v_mfma_f32_16x16x32_bf16 v[40:43], v[164:167], v[196:199], v[40:43]
	v_mfma_f32_16x16x32_bf16 v[28:31], v[156:159], v[204:207], v[28:31]
	v_mfma_f32_16x16x32_bf16 v[24:27], v[164:167], v[204:207], v[24:27]
	v_mfma_f32_16x16x32_bf16 v[12:15], v[156:159], v[212:215], v[12:15]
	v_mfma_f32_16x16x32_bf16 v[8:11], v[164:167], v[212:215], v[8:11]
	v_mfma_f32_16x16x32_bf16 v[52:55], v[168:171], v[184:187], v[52:55]
	v_mfma_f32_16x16x32_bf16 v[48:51], v[176:179], v[184:187], v[48:51]
	v_mfma_f32_16x16x32_bf16 v[36:39], v[168:171], v[192:195], v[36:39]
	v_mfma_f32_16x16x32_bf16 v[32:35], v[176:179], v[192:195], v[32:35]
	v_mfma_f32_16x16x32_bf16 v[20:23], v[168:171], v[200:203], v[20:23]
	v_mfma_f32_16x16x32_bf16 v[16:19], v[176:179], v[200:203], v[16:19]
	v_mfma_f32_16x16x32_bf16 v[4:7], v[168:171], v[208:211], v[4:7]
	v_mfma_f32_16x16x32_bf16 v[0:3], v[176:179], v[208:211], v[0:3]
	v_mfma_f32_16x16x32_bf16 v[52:55], v[172:175], v[188:191], v[52:55]
	v_mfma_f32_16x16x32_bf16 v[48:51], v[180:183], v[188:191], v[48:51]
	v_mfma_f32_16x16x32_bf16 v[36:39], v[172:175], v[196:199], v[36:39]
	v_mfma_f32_16x16x32_bf16 v[32:35], v[180:183], v[196:199], v[32:35]
	v_mfma_f32_16x16x32_bf16 v[20:23], v[172:175], v[204:207], v[20:23]
	v_mfma_f32_16x16x32_bf16 v[16:19], v[180:183], v[204:207], v[16:19]
	v_mfma_f32_16x16x32_bf16 v[4:7], v[172:175], v[212:215], v[4:7]
	v_mfma_f32_16x16x32_bf16 v[0:3], v[180:183], v[212:215], v[0:3]
	s_add_i32 s59, s59, 2
	s_add_u32 s36, s36, 0x100
	s_addc_u32 s37, s37, 0
	s_add_u32 s57, s57, 0x100
	s_addc_u32 s58, s58, 0
	s_cmp_gt_u32 s59, 29
	s_setprio 0
	s_barrier
	s_cbranch_scc0 .LBB0_484
	s_and_b64 vcc, exec, s[8:9]
	s_cbranch_vccz .LBB0_487
	s_barrier
